# GEMM K-loops: all VALU removed from the load segments (LDS-DMA loads in SGPR-base + VGPR-offset form, B-fragment LDS read bases hoisted to v252-255 per unit)
# speedup vs baseline: 1.0058x; 1.0058x over previous
; #define PG8_STAGE(bufoff, gbase, voff) do { _Pragma("unroll") for (int _i = 0; _i < 2; ++_i) \
;         __builtin_amdgcn_global_load_lds((const unsigned*)((const char*)(gbase) + (voff)[_i]), (PG8_LAS unsigned*)(lds + (bufoff) + ldsw + _i * 8192), 16, 0, 0); } while (0)
; #define PG8_LDA(dst, b, h) do { _Pragma("unroll") for (int m = 0; m < 4; ++m) _Pragma("unroll") for (int k = 0; k < 2; ++k) dst[m][k] = *(const PG8_LAS bf16x8*)(lds + PG8_SA(b, h) + aoff + m * 2048 + k * 1024); } while (0)
; #define PG8_LDB(dst, b, h) do { _Pragma("unroll") for (int n = 0; n < 2; ++n) _Pragma("unroll") for (int k = 0; k < 2; ++k) dst[n][k] = *(const PG8_LAS bf16x8*)(lds + PG8_SB(b, h) + boff + n * 2048 + k * 1024); } while (0)
; #define PG8_MMA(ai, bj, At, Bt) do { __builtin_amdgcn_s_setprio(1); _Pragma("unroll") for (int m = 0; m < 4; ++m) _Pragma("unroll") for (int n = 0; n < 2; ++n) _Pragma("unroll") for (int k = 0; k < 2; ++k) \
;         acc[ai][bj][m][n] = __builtin_amdgcn_mfma_f32_16x16x32_bf16(Bt[n][k], At[m][k], acc[ai][bj][m][n], 0, 0, 0); __builtin_amdgcn_s_setprio(0); } while (0)
; #define PG8_WAIT_V(n) asm volatile("s_waitcnt vmcnt(" #n ")" ::: "memory")
; #define PG8_WAIT_L(n) asm volatile("s_waitcnt lgkmcnt(" #n ")" ::: "memory")
; #define PG8_BAR __builtin_amdgcn_s_barrier()
; #define PG8_SCHED __builtin_amdgcn_sched_barrier(0)
; template <class Epi, class Sched, bool ALIGN_EPI = false, bool SP2 = false>
; __device__ __forceinline__ void gemm_phase(PG8_LAS unsigned char* lds, const Gemm g, const Sched& S, const Epi& E, const int wave0) {
;     ...
;             if constexpr (SP2) {
;             PG8_LDB(B0, 0, 0); PG8_LDB(B1, 0, 1); PG8_SCHED; PG8_LDA(At, 0, 0); PG8_STAGE(PG8_SA(1, 1), a1 + hstepA, voffA);
;             PG8_WAIT_V(8); PG8_WAIT_L(0); PG8_BAR; PG8_MMA(0, 0, At, B0); PG8_MMA(0, 1, At, B1); PG8_BAR; PG8_SCHED;
;     ...
;         for (int a = 0; a < 2; ++a)
; #pragma unroll
;             for (int b = 0; b < 2; ++b)
; #pragma unroll
;                 for (int m = 0; m < 4; ++m)
; #pragma unroll
;                     for (int n = 0; n < 2; ++n) acc[a][b][m][n] = (f32x4){0.f, 0.f, 0.f, 0.f};
.LBB0_315:
	s_ashr_i32 s11, s10, 31
	s_lshl_b64 s[12:13], s[10:11], 20
	v_readlane_b32 s14, v245, 1
	v_readlane_b32 s15, v245, 2
	s_add_u32 s12, s14, s12
	s_addc_u32 s13, s15, s13
	s_and_b64 s[14:15], s[2:3], exec
	s_cselect_b32 s11, s13, s1
	s_cselect_b32 s33, s12, s0
	s_ashr_i32 s9, s8, 31
	s_lshl_b64 s[14:15], s[8:9], 20
	s_add_u32 s14, s20, s14
	s_addc_u32 s15, s21, s15
	s_and_b64 s[18:19], s[2:3], exec
	s_cselect_b32 s9, s15, s17
	s_cselect_b32 s34, s14, s16
	s_add_u32 s0, s0, 0x80080
	s_addc_u32 s1, s1, 0
	s_add_u32 s35, s16, 0x100
	v_mov_b32_e32 v0, 0
	s_addc_u32 s36, s17, 0
	s_mov_b32 s37, -2
	v_mov_b32_e32 v1, v0
	v_mov_b64_e32 v[2:3], 0
	v_mov_b64_e32 v[4:5], 0
	v_mov_b64_e32 v[6:7], 0
	v_mov_b64_e32 v[8:9], 0
	v_mov_b64_e32 v[10:11], 0
	v_mov_b64_e32 v[12:13], 0
	v_mov_b64_e32 v[14:15], 0
	v_mov_b64_e32 v[24:25], 0
	v_mov_b64_e32 v[26:27], 0
	v_mov_b64_e32 v[28:29], 0
	v_mov_b64_e32 v[30:31], 0
	v_mov_b64_e32 v[40:41], 0
	v_mov_b64_e32 v[42:43], 0
	v_mov_b64_e32 v[44:45], 0
	v_mov_b64_e32 v[46:47], 0
	v_mov_b64_e32 v[16:17], 0
	v_mov_b64_e32 v[18:19], 0
	v_mov_b64_e32 v[20:21], 0
	v_mov_b64_e32 v[22:23], 0
	v_mov_b64_e32 v[32:33], 0
	v_mov_b64_e32 v[34:35], 0
	v_mov_b64_e32 v[36:37], 0
	v_mov_b64_e32 v[38:39], 0
	v_mov_b64_e32 v[48:49], 0
	v_mov_b64_e32 v[50:51], 0
	v_mov_b64_e32 v[52:53], 0
	v_mov_b64_e32 v[54:55], 0
	v_mov_b64_e32 v[56:57], 0
	v_mov_b64_e32 v[58:59], 0
	v_mov_b64_e32 v[60:61], 0
	v_mov_b64_e32 v[62:63], 0
	v_mov_b64_e32 v[66:67], 0
	v_mov_b64_e32 v[68:69], 0
	v_mov_b64_e32 v[70:71], 0
	v_mov_b64_e32 v[72:73], 0
	v_mov_b64_e32 v[74:75], 0
	v_mov_b64_e32 v[76:77], 0
	v_mov_b64_e32 v[78:79], 0
	v_mov_b64_e32 v[80:81], 0
	v_mov_b64_e32 v[90:91], 0
	v_mov_b64_e32 v[92:93], 0
	v_mov_b64_e32 v[94:95], 0
	v_mov_b64_e32 v[96:97], 0
	v_mov_b64_e32 v[106:107], 0
	v_mov_b64_e32 v[108:109], 0
	v_mov_b64_e32 v[110:111], 0
	v_mov_b64_e32 v[112:113], 0
	v_mov_b64_e32 v[82:83], 0
	v_mov_b64_e32 v[84:85], 0
	v_mov_b64_e32 v[86:87], 0
	v_mov_b64_e32 v[88:89], 0
	v_mov_b64_e32 v[98:99], 0
	v_mov_b64_e32 v[100:101], 0
	v_mov_b64_e32 v[102:103], 0
	v_mov_b64_e32 v[104:105], 0
	v_mov_b64_e32 v[114:115], 0
	v_mov_b64_e32 v[116:117], 0
	v_mov_b64_e32 v[118:119], 0
	v_mov_b64_e32 v[120:121], 0
	v_mov_b64_e32 v[122:123], 0
	v_mov_b64_e32 v[124:125], 0
	v_mov_b64_e32 v[126:127], 0
	v_mov_b64_e32 v[128:129], 0
	s_mov_b64 s[42:43], 0x80
	v_add_u32_e32 v252, 0x10000, v141
	v_add_u32_e32 v253, 0x14000, v141
	v_add_u32_e32 v254, 0x18000, v141
	v_add_u32_e32 v255, 0x1c000, v141
.LBB0_316:
	s_add_u32 s16, s0, 0xfff80080
	s_addc_u32 s17, s1, -1
	s_add_i32 s38, 0, 0x10000
	s_cmp_eq_u32 s37, 28
	s_cselect_b32 s19, s11, s17
	s_cselect_b32 s18, s33, s16
	s_cselect_b32 s17, s9, s36
	s_cselect_b32 s16, s34, s35
	s_add_i32 s40, 0, 0x14000
	ds_read_b128 v[144:147], v252
	ds_read_b128 v[148:151], v252 offset:1024
	ds_read_b128 v[152:155], v252 offset:2048
	ds_read_b128 v[156:159], v252 offset:3072
	ds_read_b128 v[178:181], v253
	ds_read_b128 v[182:185], v253 offset:1024
	ds_read_b128 v[186:189], v253 offset:2048
	ds_read_b128 v[190:193], v253 offset:3072
	s_add_i32 m0, s23, 0xc000
	ds_read_b128 v[194:197], v143
	ds_read_b128 v[208:211], v143 offset:1024
	ds_read_b128 v[212:215], v143 offset:2048
	ds_read_b128 v[216:219], v143 offset:3072
	ds_read_b128 v[220:223], v143 offset:4096
	ds_read_b128 v[224:227], v143 offset:5120
	ds_read_b128 v[228:231], v143 offset:6144
	ds_read_b128 v[232:235], v143 offset:7168
	global_load_lds_dwordx4 v136, s[0:1]
	s_add_i32 m0, s23, 0xe000
	s_nop 0
	global_load_lds_dwordx4 v138, s[0:1]
	s_waitcnt vmcnt(8)
	s_waitcnt lgkmcnt(0)
	s_barrier
	s_setprio 1
	s_waitcnt lgkmcnt(0)
	v_mfma_f32_16x16x32_bf16 v[126:129], v[144:147], v[194:197], v[126:129]
	v_mfma_f32_16x16x32_bf16 v[122:125], v[152:155], v[194:197], v[122:125]
	v_mfma_f32_16x16x32_bf16 v[118:121], v[144:147], v[212:215], v[118:121]
	v_mfma_f32_16x16x32_bf16 v[114:117], v[152:155], v[212:215], v[114:117]
	v_mfma_f32_16x16x32_bf16 v[102:105], v[144:147], v[220:223], v[102:105]
	v_mfma_f32_16x16x32_bf16 v[98:101], v[152:155], v[220:223], v[98:101]
	v_mfma_f32_16x16x32_bf16 v[86:89], v[144:147], v[228:231], v[86:89]
	v_mfma_f32_16x16x32_bf16 v[82:85], v[152:155], v[228:231], v[82:85]
	v_mfma_f32_16x16x32_bf16 v[126:129], v[148:151], v[208:211], v[126:129]
	v_mfma_f32_16x16x32_bf16 v[122:125], v[156:159], v[208:211], v[122:125]
	v_mfma_f32_16x16x32_bf16 v[118:121], v[148:151], v[216:219], v[118:121]
	v_mfma_f32_16x16x32_bf16 v[114:117], v[156:159], v[216:219], v[114:117]
	v_mfma_f32_16x16x32_bf16 v[102:105], v[148:151], v[224:227], v[102:105]
	v_mfma_f32_16x16x32_bf16 v[98:101], v[156:159], v[224:227], v[98:101]
	v_mfma_f32_16x16x32_bf16 v[86:89], v[148:151], v[232:235], v[86:89]
	v_mfma_f32_16x16x32_bf16 v[82:85], v[156:159], v[232:235], v[82:85]
	s_setprio 0
	s_setprio 1
	v_mfma_f32_16x16x32_bf16 v[110:113], v[178:181], v[194:197], v[110:113]
	v_mfma_f32_16x16x32_bf16 v[106:109], v[186:189], v[194:197], v[106:109]
	v_mfma_f32_16x16x32_bf16 v[94:97], v[178:181], v[212:215], v[94:97]
	v_mfma_f32_16x16x32_bf16 v[90:93], v[186:189], v[212:215], v[90:93]
	v_mfma_f32_16x16x32_bf16 v[78:81], v[178:181], v[220:223], v[78:81]
	v_mfma_f32_16x16x32_bf16 v[74:77], v[186:189], v[220:223], v[74:77]
	v_mfma_f32_16x16x32_bf16 v[70:73], v[178:181], v[228:231], v[70:73]
	v_mfma_f32_16x16x32_bf16 v[66:69], v[186:189], v[228:231], v[66:69]
	v_mfma_f32_16x16x32_bf16 v[110:113], v[182:185], v[208:211], v[110:113]
	v_mfma_f32_16x16x32_bf16 v[106:109], v[190:193], v[208:211], v[106:109]
	v_mfma_f32_16x16x32_bf16 v[94:97], v[182:185], v[216:219], v[94:97]
	v_mfma_f32_16x16x32_bf16 v[90:93], v[190:193], v[216:219], v[90:93]
	v_mfma_f32_16x16x32_bf16 v[78:81], v[182:185], v[224:227], v[78:81]
	v_mfma_f32_16x16x32_bf16 v[74:77], v[190:193], v[224:227], v[74:77]
	v_mfma_f32_16x16x32_bf16 v[70:73], v[182:185], v[232:235], v[70:73]
	v_mfma_f32_16x16x32_bf16 v[66:69], v[190:193], v[232:235], v[66:69]
	s_setprio 0
	s_barrier
; #define PG8_STAGE(bufoff, gbase, voff) do { _Pragma("unroll") for (int _i = 0; _i < 2; ++_i) \
;         __builtin_amdgcn_global_load_lds((const unsigned*)((const char*)(gbase) + (voff)[_i]), (PG8_LAS unsigned*)(lds + (bufoff) + ldsw + _i * 8192), 16, 0, 0); } while (0)
; #define PG8_LDA(dst, b, h) do { _Pragma("unroll") for (int m = 0; m < 4; ++m) _Pragma("unroll") for (int k = 0; k < 2; ++k) dst[m][k] = *(const PG8_LAS bf16x8*)(lds + PG8_SA(b, h) + aoff + m * 2048 + k * 1024); } while (0)
; #define PG8_LDB(dst, b, h) do { _Pragma("unroll") for (int n = 0; n < 2; ++n) _Pragma("unroll") for (int k = 0; k < 2; ++k) dst[n][k] = *(const PG8_LAS bf16x8*)(lds + PG8_SB(b, h) + boff + n * 2048 + k * 1024); } while (0)
; #define PG8_MMA(ai, bj, At, Bt) do { __builtin_amdgcn_s_setprio(1); _Pragma("unroll") for (int m = 0; m < 4; ++m) _Pragma("unroll") for (int n = 0; n < 2; ++n) _Pragma("unroll") for (int k = 0; k < 2; ++k) \
;         acc[ai][bj][m][n] = __builtin_amdgcn_mfma_f32_16x16x32_bf16(Bt[n][k], At[m][k], acc[ai][bj][m][n], 0, 0, 0); __builtin_amdgcn_s_setprio(0); } while (0)
; #define PG8_WAIT_V(n) asm volatile("s_waitcnt vmcnt(" #n ")" ::: "memory")
; #define PG8_WAIT_L(n) asm volatile("s_waitcnt lgkmcnt(" #n ")" ::: "memory")
; #define PG8_BAR __builtin_amdgcn_s_barrier()
; #define PG8_SCHED __builtin_amdgcn_sched_barrier(0)
; template <class Epi, class Sched, bool ALIGN_EPI = false, bool SP2 = false>
; __device__ __forceinline__ void gemm_phase(PG8_LAS unsigned char* lds, const Gemm g, const Sched& S, const Epi& E, const int wave0) {
;     ...
;             PG8_WAIT_V(8); PG8_WAIT_L(0); PG8_BAR; PG8_MMA(0, 0, At, B0); PG8_MMA(0, 1, At, B1); PG8_BAR; PG8_SCHED;
;             PG8_LDA(At, 0, 1); PG8_STAGE(PG8_SB(0, 0), b2, voffB); PG8_STAGE(PG8_SB(0, 1), b2 + hstepB, voffB); PG8_STAGE(PG8_SA(0, 0), a2, voffA);
;             PG8_WAIT_V(8); PG8_WAIT_L(0); PG8_BAR; PG8_MMA(1, 0, At, B0); PG8_MMA(1, 1, At, B1); PG8_BAR; PG8_SCHED;
;             PG8_LDB(B0, 1, 0); PG8_LDB(B1, 1, 1); PG8_SCHED; PG8_LDA(At, 1, 0); PG8_STAGE(PG8_SA(0, 1), a2 + hstepA, voffA);
	s_add_i32 s38, s38, s22
	s_mov_b32 m0, s38
	ds_read_b128 v[194:197], v143 offset:16384
	ds_read_b128 v[208:211], v143 offset:17408
	ds_read_b128 v[212:215], v143 offset:18432
	ds_read_b128 v[216:219], v143 offset:19456
	ds_read_b128 v[220:223], v143 offset:20480
	ds_read_b128 v[224:227], v143 offset:21504
	ds_read_b128 v[228:231], v143 offset:22528
	ds_read_b128 v[232:235], v143 offset:23552
	global_load_lds_dwordx4 v64, s[16:17]
	s_add_i32 m0, s38, 0x2000
	s_add_u32 s38, s16, 0x80000
	s_addc_u32 s39, s17, 0
	s_add_i32 s40, s40, s22
	global_load_lds_dwordx4 v130, s[16:17]
	s_mov_b32 m0, s40
	s_mov_b64 s[100:101], s[18:19]
	global_load_lds_dwordx4 v64, s[38:39]
	s_add_i32 m0, s40, 0x2000
	s_nop 0
	global_load_lds_dwordx4 v130, s[38:39]
	s_mov_b32 m0, s23
	s_nop 0
	global_load_lds_dwordx4 v134, s[18:19]
	s_mov_b32 m0, s24
	s_nop 0
	global_load_lds_dwordx4 v132, s[18:19]
	s_waitcnt vmcnt(8)
	s_waitcnt lgkmcnt(0)
	s_barrier
	s_setprio 1
	s_waitcnt lgkmcnt(0)
	v_mfma_f32_16x16x32_bf16 v[60:63], v[144:147], v[194:197], v[60:63]
	v_mfma_f32_16x16x32_bf16 v[56:59], v[152:155], v[194:197], v[56:59]
	v_mfma_f32_16x16x32_bf16 v[52:55], v[144:147], v[212:215], v[52:55]
	v_mfma_f32_16x16x32_bf16 v[48:51], v[152:155], v[212:215], v[48:51]
	v_mfma_f32_16x16x32_bf16 v[36:39], v[144:147], v[220:223], v[36:39]
	v_mfma_f32_16x16x32_bf16 v[32:35], v[152:155], v[220:223], v[32:35]
	v_mfma_f32_16x16x32_bf16 v[20:23], v[144:147], v[228:231], v[20:23]
	v_mfma_f32_16x16x32_bf16 v[16:19], v[152:155], v[228:231], v[16:19]
	v_mfma_f32_16x16x32_bf16 v[60:63], v[148:151], v[208:211], v[60:63]
	v_mfma_f32_16x16x32_bf16 v[56:59], v[156:159], v[208:211], v[56:59]
	v_mfma_f32_16x16x32_bf16 v[52:55], v[148:151], v[216:219], v[52:55]
	v_mfma_f32_16x16x32_bf16 v[48:51], v[156:159], v[216:219], v[48:51]
	v_mfma_f32_16x16x32_bf16 v[36:39], v[148:151], v[224:227], v[36:39]
	v_mfma_f32_16x16x32_bf16 v[32:35], v[156:159], v[224:227], v[32:35]
	v_mfma_f32_16x16x32_bf16 v[20:23], v[148:151], v[232:235], v[20:23]
	v_mfma_f32_16x16x32_bf16 v[16:19], v[156:159], v[232:235], v[16:19]
	s_setprio 0
	s_setprio 1
	v_mfma_f32_16x16x32_bf16 v[44:47], v[178:181], v[194:197], v[44:47]
	v_mfma_f32_16x16x32_bf16 v[40:43], v[186:189], v[194:197], v[40:43]
	v_mfma_f32_16x16x32_bf16 v[28:31], v[178:181], v[212:215], v[28:31]
	v_mfma_f32_16x16x32_bf16 v[24:27], v[186:189], v[212:215], v[24:27]
	v_mfma_f32_16x16x32_bf16 v[12:15], v[178:181], v[220:223], v[12:15]
	v_mfma_f32_16x16x32_bf16 v[8:11], v[186:189], v[220:223], v[8:11]
	v_mfma_f32_16x16x32_bf16 v[4:7], v[178:181], v[228:231], v[4:7]
	v_mfma_f32_16x16x32_bf16 v[0:3], v[186:189], v[228:231], v[0:3]
	v_mfma_f32_16x16x32_bf16 v[44:47], v[182:185], v[208:211], v[44:47]
	v_mfma_f32_16x16x32_bf16 v[40:43], v[190:193], v[208:211], v[40:43]
	v_mfma_f32_16x16x32_bf16 v[28:31], v[182:185], v[216:219], v[28:31]
	v_mfma_f32_16x16x32_bf16 v[24:27], v[190:193], v[216:219], v[24:27]
	v_mfma_f32_16x16x32_bf16 v[12:15], v[182:185], v[224:227], v[12:15]
	v_mfma_f32_16x16x32_bf16 v[8:11], v[190:193], v[224:227], v[8:11]
	v_mfma_f32_16x16x32_bf16 v[4:7], v[182:185], v[232:235], v[4:7]
	v_mfma_f32_16x16x32_bf16 v[0:3], v[190:193], v[232:235], v[0:3]
	s_setprio 0
	s_barrier
	s_add_i32 s38, 0, 0x18000
	s_add_i32 s39, 0, 0x1c000
	ds_read_b128 v[144:147], v254
	ds_read_b128 v[148:151], v254 offset:1024
	ds_read_b128 v[152:155], v254 offset:2048
	ds_read_b128 v[156:159], v254 offset:3072
	ds_read_b128 v[178:181], v255
	ds_read_b128 v[182:185], v255 offset:1024
	ds_read_b128 v[186:189], v255 offset:2048
	ds_read_b128 v[190:193], v255 offset:3072
	s_add_u32 s18, s18, 0x80000
	s_addc_u32 s19, s19, 0
	s_mov_b32 m0, s25
	ds_read_b128 v[194:197], v143 offset:32768
	ds_read_b128 v[208:211], v143 offset:33792
	ds_read_b128 v[212:215], v143 offset:34816
	ds_read_b128 v[216:219], v143 offset:35840
	ds_read_b128 v[220:223], v143 offset:36864
	ds_read_b128 v[224:227], v143 offset:37888
	ds_read_b128 v[228:231], v143 offset:38912
	ds_read_b128 v[232:235], v143 offset:39936
	global_load_lds_dwordx4 v134, s[18:19]
	s_mov_b32 m0, s26
	s_nop 0
	global_load_lds_dwordx4 v132, s[18:19]
	s_waitcnt vmcnt(8)
	s_waitcnt lgkmcnt(0)
	s_barrier
; #define PG8_STAGE(bufoff, gbase, voff) do { _Pragma("unroll") for (int _i = 0; _i < 2; ++_i) \
;         __builtin_amdgcn_global_load_lds((const unsigned*)((const char*)(gbase) + (voff)[_i]), (PG8_LAS unsigned*)(lds + (bufoff) + ldsw + _i * 8192), 16, 0, 0); } while (0)
; #define PG8_LDA(dst, b, h) do { _Pragma("unroll") for (int m = 0; m < 4; ++m) _Pragma("unroll") for (int k = 0; k < 2; ++k) dst[m][k] = *(const PG8_LAS bf16x8*)(lds + PG8_SA(b, h) + aoff + m * 2048 + k * 1024); } while (0)
; #define PG8_MMA(ai, bj, At, Bt) do { __builtin_amdgcn_s_setprio(1); _Pragma("unroll") for (int m = 0; m < 4; ++m) _Pragma("unroll") for (int n = 0; n < 2; ++n) _Pragma("unroll") for (int k = 0; k < 2; ++k) \
;         acc[ai][bj][m][n] = __builtin_amdgcn_mfma_f32_16x16x32_bf16(Bt[n][k], At[m][k], acc[ai][bj][m][n], 0, 0, 0); __builtin_amdgcn_s_setprio(0); } while (0)
; #define PG8_WAIT_V(n) asm volatile("s_waitcnt vmcnt(" #n ")" ::: "memory")
; #define PG8_WAIT_L(n) asm volatile("s_waitcnt lgkmcnt(" #n ")" ::: "memory")
; #define PG8_BAR __builtin_amdgcn_s_barrier()
; #define PG8_SCHED __builtin_amdgcn_sched_barrier(0)
; template <class Epi, class Sched, bool ALIGN_EPI = false, bool SP2 = false>
; __device__ __forceinline__ void gemm_phase(PG8_LAS unsigned char* lds, const Gemm g, const Sched& S, const Epi& E, const int wave0) {
;     ...
;         for (int t = 0; t < nt; t += 2) {
;     ...
;             PG8_WAIT_V(8); PG8_WAIT_L(0); PG8_BAR; PG8_MMA(0, 0, At, B0); PG8_MMA(0, 1, At, B1); PG8_BAR; PG8_SCHED;
;             PG8_LDA(At, 1, 1); PG8_STAGE(PG8_SB(1, 0), b3, voffB); PG8_STAGE(PG8_SB(1, 1), b3 + hstepB, voffB); PG8_STAGE(PG8_SA(1, 0), a3, voffA);
;             PG8_WAIT_V(8); PG8_WAIT_L(0); PG8_BAR; PG8_MMA(1, 0, At, B0); PG8_MMA(1, 1, At, B1); PG8_BAR; PG8_SCHED;
	s_setprio 1
	s_waitcnt lgkmcnt(0)
	v_mfma_f32_16x16x32_bf16 v[126:129], v[144:147], v[194:197], v[126:129]
	v_mfma_f32_16x16x32_bf16 v[122:125], v[152:155], v[194:197], v[122:125]
	v_mfma_f32_16x16x32_bf16 v[118:121], v[144:147], v[212:215], v[118:121]
	v_mfma_f32_16x16x32_bf16 v[114:117], v[152:155], v[212:215], v[114:117]
	v_mfma_f32_16x16x32_bf16 v[102:105], v[144:147], v[220:223], v[102:105]
	v_mfma_f32_16x16x32_bf16 v[98:101], v[152:155], v[220:223], v[98:101]
	v_mfma_f32_16x16x32_bf16 v[86:89], v[144:147], v[228:231], v[86:89]
	v_mfma_f32_16x16x32_bf16 v[82:85], v[152:155], v[228:231], v[82:85]
	v_mfma_f32_16x16x32_bf16 v[126:129], v[148:151], v[208:211], v[126:129]
	v_mfma_f32_16x16x32_bf16 v[122:125], v[156:159], v[208:211], v[122:125]
	v_mfma_f32_16x16x32_bf16 v[118:121], v[148:151], v[216:219], v[118:121]
	v_mfma_f32_16x16x32_bf16 v[114:117], v[156:159], v[216:219], v[114:117]
	v_mfma_f32_16x16x32_bf16 v[102:105], v[148:151], v[224:227], v[102:105]
	v_mfma_f32_16x16x32_bf16 v[98:101], v[156:159], v[224:227], v[98:101]
	v_mfma_f32_16x16x32_bf16 v[86:89], v[148:151], v[232:235], v[86:89]
	v_mfma_f32_16x16x32_bf16 v[82:85], v[156:159], v[232:235], v[82:85]
	s_setprio 0
	s_setprio 1
	v_mfma_f32_16x16x32_bf16 v[110:113], v[178:181], v[194:197], v[110:113]
	v_mfma_f32_16x16x32_bf16 v[106:109], v[186:189], v[194:197], v[106:109]
	v_mfma_f32_16x16x32_bf16 v[94:97], v[178:181], v[212:215], v[94:97]
	v_mfma_f32_16x16x32_bf16 v[90:93], v[186:189], v[212:215], v[90:93]
	v_mfma_f32_16x16x32_bf16 v[78:81], v[178:181], v[220:223], v[78:81]
	v_mfma_f32_16x16x32_bf16 v[74:77], v[186:189], v[220:223], v[74:77]
	v_mfma_f32_16x16x32_bf16 v[70:73], v[178:181], v[228:231], v[70:73]
	v_mfma_f32_16x16x32_bf16 v[66:69], v[186:189], v[228:231], v[66:69]
	v_mfma_f32_16x16x32_bf16 v[110:113], v[182:185], v[208:211], v[110:113]
	v_mfma_f32_16x16x32_bf16 v[106:109], v[190:193], v[208:211], v[106:109]
	v_mfma_f32_16x16x32_bf16 v[94:97], v[182:185], v[216:219], v[94:97]
	v_mfma_f32_16x16x32_bf16 v[90:93], v[190:193], v[216:219], v[90:93]
	v_mfma_f32_16x16x32_bf16 v[78:81], v[182:185], v[224:227], v[78:81]
	v_mfma_f32_16x16x32_bf16 v[74:77], v[190:193], v[224:227], v[74:77]
	v_mfma_f32_16x16x32_bf16 v[70:73], v[182:185], v[232:235], v[70:73]
	v_mfma_f32_16x16x32_bf16 v[66:69], v[190:193], v[232:235], v[66:69]
	s_setprio 0
	s_barrier
	s_add_i32 s18, s38, s22
	s_add_u32 s42, s16, 0x80
	s_addc_u32 s43, s17, 0
	s_mov_b32 m0, s18
	ds_read_b128 v[194:197], v143 offset:49152
	ds_read_b128 v[208:211], v143 offset:50176
	ds_read_b128 v[212:215], v143 offset:51200
	ds_read_b128 v[216:219], v143 offset:52224
	ds_read_b128 v[220:223], v143 offset:53248
	ds_read_b128 v[224:227], v143 offset:54272
	ds_read_b128 v[228:231], v143 offset:55296
	ds_read_b128 v[232:235], v143 offset:56320
	global_load_lds_dwordx4 v64, s[42:43]
	s_add_i32 m0, s18, 0x2000
	s_add_u32 s16, s16, 0x80080
	s_addc_u32 s17, s17, 0
	s_add_i32 s18, s39, s22
	global_load_lds_dwordx4 v130, s[42:43]
	s_mov_b32 m0, s18
	s_nop 0
	global_load_lds_dwordx4 v64, s[16:17]
	s_add_i32 m0, s18, 0x2000
	s_nop 0
	global_load_lds_dwordx4 v130, s[16:17]
	s_add_u32 s100, s100, 0x80
	s_addc_u32 s101, s101, 0
	s_mov_b32 m0, s27
	s_nop 0
	global_load_lds_dwordx4 v134, s[100:101]
	s_mov_b32 m0, s28
	s_nop 0
	global_load_lds_dwordx4 v132, s[100:101]
	s_waitcnt vmcnt(8)
	s_waitcnt lgkmcnt(0)
	s_barrier
	s_setprio 1
	s_waitcnt lgkmcnt(0)
	v_mfma_f32_16x16x32_bf16 v[60:63], v[144:147], v[194:197], v[60:63]
	v_mfma_f32_16x16x32_bf16 v[56:59], v[152:155], v[194:197], v[56:59]
	v_mfma_f32_16x16x32_bf16 v[52:55], v[144:147], v[212:215], v[52:55]
	v_mfma_f32_16x16x32_bf16 v[48:51], v[152:155], v[212:215], v[48:51]
	v_mfma_f32_16x16x32_bf16 v[36:39], v[144:147], v[220:223], v[36:39]
	v_mfma_f32_16x16x32_bf16 v[32:35], v[152:155], v[220:223], v[32:35]
	v_mfma_f32_16x16x32_bf16 v[20:23], v[144:147], v[228:231], v[20:23]
	v_mfma_f32_16x16x32_bf16 v[16:19], v[152:155], v[228:231], v[16:19]
	v_mfma_f32_16x16x32_bf16 v[60:63], v[148:151], v[208:211], v[60:63]
	v_mfma_f32_16x16x32_bf16 v[56:59], v[156:159], v[208:211], v[56:59]
	v_mfma_f32_16x16x32_bf16 v[52:55], v[148:151], v[216:219], v[52:55]
	v_mfma_f32_16x16x32_bf16 v[48:51], v[156:159], v[216:219], v[48:51]
	v_mfma_f32_16x16x32_bf16 v[36:39], v[148:151], v[224:227], v[36:39]
	v_mfma_f32_16x16x32_bf16 v[32:35], v[156:159], v[224:227], v[32:35]
	v_mfma_f32_16x16x32_bf16 v[20:23], v[148:151], v[232:235], v[20:23]
	v_mfma_f32_16x16x32_bf16 v[16:19], v[156:159], v[232:235], v[16:19]
	s_setprio 0
	s_setprio 1
	v_mfma_f32_16x16x32_bf16 v[44:47], v[178:181], v[194:197], v[44:47]
	v_mfma_f32_16x16x32_bf16 v[40:43], v[186:189], v[194:197], v[40:43]
	v_mfma_f32_16x16x32_bf16 v[28:31], v[178:181], v[212:215], v[28:31]
	v_mfma_f32_16x16x32_bf16 v[24:27], v[186:189], v[212:215], v[24:27]
	v_mfma_f32_16x16x32_bf16 v[12:15], v[178:181], v[220:223], v[12:15]
	v_mfma_f32_16x16x32_bf16 v[8:11], v[186:189], v[220:223], v[8:11]
	v_mfma_f32_16x16x32_bf16 v[4:7], v[178:181], v[228:231], v[4:7]
	v_mfma_f32_16x16x32_bf16 v[0:3], v[186:189], v[228:231], v[0:3]
	v_mfma_f32_16x16x32_bf16 v[44:47], v[182:185], v[208:211], v[44:47]
	v_mfma_f32_16x16x32_bf16 v[40:43], v[190:193], v[208:211], v[40:43]
	v_mfma_f32_16x16x32_bf16 v[28:31], v[182:185], v[216:219], v[28:31]
	v_mfma_f32_16x16x32_bf16 v[24:27], v[190:193], v[216:219], v[24:27]
	v_mfma_f32_16x16x32_bf16 v[12:15], v[182:185], v[224:227], v[12:15]
	v_mfma_f32_16x16x32_bf16 v[8:11], v[190:193], v[224:227], v[8:11]
	v_mfma_f32_16x16x32_bf16 v[4:7], v[182:185], v[232:235], v[4:7]
	v_mfma_f32_16x16x32_bf16 v[0:3], v[190:193], v[232:235], v[0:3]
	s_setprio 0
	s_barrier
	s_add_i32 s37, s37, 2
	s_add_u32 s0, s0, 0x100
	s_addc_u32 s1, s1, 0
	s_add_u32 s35, s35, 0x100
	s_addc_u32 s36, s36, 0
	s_cmp_gt_u32 s37, 29
	s_cbranch_scc0 .LBB0_316
	s_mov_b64 s[42:43], 0x80
	s_and_b64 vcc, exec, s[6:7]
	s_mov_b64 s[34:35], 0x45000
	s_cbranch_vccz .LBB0_319
	s_barrier

; #define PG8_STAGE(bufoff, gbase, voff) do { _Pragma("unroll") for (int _i = 0; _i < 2; ++_i) \
;         __builtin_amdgcn_global_load_lds((const unsigned*)((const char*)(gbase) + (voff)[_i]), (PG8_LAS unsigned*)(lds + (bufoff) + ldsw + _i * 8192), 16, 0, 0); } while (0)
; #define PG8_LDA(dst, b, h) do { _Pragma("unroll") for (int m = 0; m < 4; ++m) _Pragma("unroll") for (int k = 0; k < 2; ++k) dst[m][k] = *(const PG8_LAS bf16x8*)(lds + PG8_SA(b, h) + aoff + m * 2048 + k * 1024); } while (0)
; #define PG8_LDB(dst, b, h) do { _Pragma("unroll") for (int n = 0; n < 2; ++n) _Pragma("unroll") for (int k = 0; k < 2; ++k) dst[n][k] = *(const PG8_LAS bf16x8*)(lds + PG8_SB(b, h) + boff + n * 2048 + k * 1024); } while (0)
; #define PG8_MMA(ai, bj, At, Bt) do { __builtin_amdgcn_s_setprio(1); _Pragma("unroll") for (int m = 0; m < 4; ++m) _Pragma("unroll") for (int n = 0; n < 2; ++n) _Pragma("unroll") for (int k = 0; k < 2; ++k) \
;         acc[ai][bj][m][n] = __builtin_amdgcn_mfma_f32_16x16x32_bf16(Bt[n][k], At[m][k], acc[ai][bj][m][n], 0, 0, 0); __builtin_amdgcn_s_setprio(0); } while (0)
; #define PG8_WAIT_V(n) asm volatile("s_waitcnt vmcnt(" #n ")" ::: "memory")
; #define PG8_WAIT_L(n) asm volatile("s_waitcnt lgkmcnt(" #n ")" ::: "memory")
; #define PG8_BAR __builtin_amdgcn_s_barrier()
; #define PG8_SCHED __builtin_amdgcn_sched_barrier(0)
; template <class Epi, class Sched, bool ALIGN_EPI = false, bool SP2 = false>
; __device__ __forceinline__ void gemm_phase(PG8_LAS unsigned char* lds, const Gemm g, const Sched& S, const Epi& E, const int wave0) {
;     ...
;             if constexpr (SP2) {
;             PG8_LDB(B0, 0, 0); PG8_LDB(B1, 0, 1); PG8_SCHED; PG8_LDA(At, 0, 0); PG8_STAGE(PG8_SA(1, 1), a1 + hstepA, voffA);
;             PG8_WAIT_V(8); PG8_WAIT_L(0); PG8_BAR; PG8_MMA(0, 0, At, B0); PG8_MMA(0, 1, At, B1); PG8_BAR; PG8_SCHED;
;     ...
;         for (int a = 0; a < 2; ++a)
; #pragma unroll
;             for (int b = 0; b < 2; ++b)
; #pragma unroll
;                 for (int m = 0; m < 4; ++m)
; #pragma unroll
;                     for (int n = 0; n < 2; ++n) acc[a][b][m][n] = (f32x4){0.f, 0.f, 0.f, 0.f};
.LBB0_1177:
	s_lshl_b64 s[18:19], s[10:11], 22
	s_add_u32 s11, s20, s18
	s_addc_u32 s13, s21, s19
	s_ashr_i32 s9, s8, 31
	s_lshl_b64 s[18:19], s[8:9], 19
	s_add_u32 s46, s11, s18
	s_addc_u32 s47, s13, s19
	s_and_b64 s[2:3], s[2:3], exec
	s_cselect_b32 s9, s47, s17
	s_cselect_b32 s11, s46, s16
	s_add_u32 s0, s0, 0x40080
	s_addc_u32 s1, s1, 0
	s_add_u32 s13, s16, 0x100
	v_mov_b32_e32 v0, 0
	s_addc_u32 s18, s17, 0
	s_mov_b32 s19, -2
	v_mov_b32_e32 v1, v0
	v_mov_b64_e32 v[2:3], 0
	v_mov_b64_e32 v[4:5], 0
	v_mov_b64_e32 v[6:7], 0
	v_mov_b64_e32 v[16:17], 0
	v_mov_b64_e32 v[18:19], 0
	v_mov_b64_e32 v[20:21], 0
	v_mov_b64_e32 v[22:23], 0
	v_mov_b64_e32 v[32:33], 0
	v_mov_b64_e32 v[34:35], 0
	v_mov_b64_e32 v[36:37], 0
	v_mov_b64_e32 v[38:39], 0
	v_mov_b64_e32 v[48:49], 0
	v_mov_b64_e32 v[50:51], 0
	v_mov_b64_e32 v[52:53], 0
	v_mov_b64_e32 v[54:55], 0
	v_mov_b64_e32 v[8:9], 0
	v_mov_b64_e32 v[10:11], 0
	v_mov_b64_e32 v[12:13], 0
	v_mov_b64_e32 v[14:15], 0
	v_mov_b64_e32 v[24:25], 0
	v_mov_b64_e32 v[26:27], 0
	v_mov_b64_e32 v[28:29], 0
	v_mov_b64_e32 v[30:31], 0
	v_mov_b64_e32 v[40:41], 0
	v_mov_b64_e32 v[42:43], 0
	v_mov_b64_e32 v[44:45], 0
	v_mov_b64_e32 v[46:47], 0
	v_mov_b64_e32 v[56:57], 0
	v_mov_b64_e32 v[58:59], 0
	v_mov_b64_e32 v[60:61], 0
	v_mov_b64_e32 v[62:63], 0
	v_mov_b64_e32 v[66:67], 0
	v_mov_b64_e32 v[68:69], 0
	v_mov_b64_e32 v[70:71], 0
	v_mov_b64_e32 v[72:73], 0
	v_mov_b64_e32 v[82:83], 0
	v_mov_b64_e32 v[84:85], 0
	v_mov_b64_e32 v[86:87], 0
	v_mov_b64_e32 v[88:89], 0
	v_mov_b64_e32 v[98:99], 0
	v_mov_b64_e32 v[100:101], 0
	v_mov_b64_e32 v[102:103], 0
	v_mov_b64_e32 v[104:105], 0
	v_mov_b64_e32 v[114:115], 0
	v_mov_b64_e32 v[116:117], 0
	v_mov_b64_e32 v[118:119], 0
	v_mov_b64_e32 v[120:121], 0
	v_mov_b64_e32 v[74:75], 0
	v_mov_b64_e32 v[76:77], 0
	v_mov_b64_e32 v[78:79], 0
	v_mov_b64_e32 v[80:81], 0
	v_mov_b64_e32 v[90:91], 0
	v_mov_b64_e32 v[92:93], 0
	v_mov_b64_e32 v[94:95], 0
	v_mov_b64_e32 v[96:97], 0
	v_mov_b64_e32 v[106:107], 0
	v_mov_b64_e32 v[108:109], 0
	v_mov_b64_e32 v[110:111], 0
	v_mov_b64_e32 v[112:113], 0
	v_mov_b64_e32 v[122:123], 0
	v_mov_b64_e32 v[124:125], 0
	v_mov_b64_e32 v[126:127], 0
	v_mov_b64_e32 v[128:129], 0
	v_add_u32_e32 v252, 0x10000, v157
	v_add_u32_e32 v253, 0x14000, v157
	v_add_u32_e32 v254, 0x18000, v157
	v_add_u32_e32 v255, 0x1c000, v157
.LBB0_1178:
	s_add_u32 s2, s0, 0xfffc0080
	s_addc_u32 s3, s1, -1
	s_add_i32 s31, 0, 0x10000
	s_cmp_eq_u32 s19, 12
	s_cselect_b32 s17, s45, s3
	s_cselect_b32 s16, s44, s2
	s_cselect_b32 s3, s9, s18
	s_cselect_b32 s2, s11, s13
	s_add_i32 s33, 0, 0x14000
	ds_read_b128 v[130:133], v252
	ds_read_b128 v[134:137], v252 offset:1024
	ds_read_b128 v[148:151], v252 offset:2048
	ds_read_b128 v[152:155], v252 offset:3072
	ds_read_b128 v[178:181], v253
	ds_read_b128 v[182:185], v253 offset:1024
	ds_read_b128 v[186:189], v253 offset:2048
	ds_read_b128 v[190:193], v253 offset:3072
	s_add_i32 m0, s23, 0xc000
	ds_read_b128 v[194:197], v159
	ds_read_b128 v[208:211], v159 offset:1024
	ds_read_b128 v[212:215], v159 offset:2048
	ds_read_b128 v[216:219], v159 offset:3072
	ds_read_b128 v[220:223], v159 offset:4096
	ds_read_b128 v[224:227], v159 offset:5120
	ds_read_b128 v[228:231], v159 offset:6144
	ds_read_b128 v[232:235], v159 offset:7168
	global_load_lds_dwordx4 v144, s[0:1]
	s_add_i32 m0, s23, 0xe000
	s_nop 0
	global_load_lds_dwordx4 v146, s[0:1]
	s_waitcnt vmcnt(8)
	s_waitcnt lgkmcnt(0)
	s_barrier
	s_setprio 1
	s_waitcnt lgkmcnt(0)
	v_mfma_f32_16x16x32_bf16 v[126:129], v[130:133], v[194:197], v[126:129]
	v_mfma_f32_16x16x32_bf16 v[122:125], v[148:151], v[194:197], v[122:125]
	v_mfma_f32_16x16x32_bf16 v[110:113], v[130:133], v[212:215], v[110:113]
	v_mfma_f32_16x16x32_bf16 v[106:109], v[148:151], v[212:215], v[106:109]
	v_mfma_f32_16x16x32_bf16 v[94:97], v[130:133], v[220:223], v[94:97]
	v_mfma_f32_16x16x32_bf16 v[90:93], v[148:151], v[220:223], v[90:93]
	v_mfma_f32_16x16x32_bf16 v[78:81], v[130:133], v[228:231], v[78:81]
	v_mfma_f32_16x16x32_bf16 v[74:77], v[148:151], v[228:231], v[74:77]
	v_mfma_f32_16x16x32_bf16 v[126:129], v[134:137], v[208:211], v[126:129]
	v_mfma_f32_16x16x32_bf16 v[122:125], v[152:155], v[208:211], v[122:125]
	v_mfma_f32_16x16x32_bf16 v[110:113], v[134:137], v[216:219], v[110:113]
	v_mfma_f32_16x16x32_bf16 v[106:109], v[152:155], v[216:219], v[106:109]
	v_mfma_f32_16x16x32_bf16 v[94:97], v[134:137], v[224:227], v[94:97]
	v_mfma_f32_16x16x32_bf16 v[90:93], v[152:155], v[224:227], v[90:93]
	v_mfma_f32_16x16x32_bf16 v[78:81], v[134:137], v[232:235], v[78:81]
	v_mfma_f32_16x16x32_bf16 v[74:77], v[152:155], v[232:235], v[74:77]
	s_setprio 0
	s_setprio 1
	v_mfma_f32_16x16x32_bf16 v[118:121], v[178:181], v[194:197], v[118:121]
	v_mfma_f32_16x16x32_bf16 v[114:117], v[186:189], v[194:197], v[114:117]
	v_mfma_f32_16x16x32_bf16 v[102:105], v[178:181], v[212:215], v[102:105]
	v_mfma_f32_16x16x32_bf16 v[98:101], v[186:189], v[212:215], v[98:101]
	v_mfma_f32_16x16x32_bf16 v[86:89], v[178:181], v[220:223], v[86:89]
	v_mfma_f32_16x16x32_bf16 v[82:85], v[186:189], v[220:223], v[82:85]
	v_mfma_f32_16x16x32_bf16 v[70:73], v[178:181], v[228:231], v[70:73]
	v_mfma_f32_16x16x32_bf16 v[66:69], v[186:189], v[228:231], v[66:69]
	v_mfma_f32_16x16x32_bf16 v[118:121], v[182:185], v[208:211], v[118:121]
	v_mfma_f32_16x16x32_bf16 v[114:117], v[190:193], v[208:211], v[114:117]
	v_mfma_f32_16x16x32_bf16 v[102:105], v[182:185], v[216:219], v[102:105]
	v_mfma_f32_16x16x32_bf16 v[98:101], v[190:193], v[216:219], v[98:101]
	v_mfma_f32_16x16x32_bf16 v[86:89], v[182:185], v[224:227], v[86:89]
	v_mfma_f32_16x16x32_bf16 v[82:85], v[190:193], v[224:227], v[82:85]
	v_mfma_f32_16x16x32_bf16 v[70:73], v[182:185], v[232:235], v[70:73]
	v_mfma_f32_16x16x32_bf16 v[66:69], v[190:193], v[232:235], v[66:69]
	s_setprio 0
	s_barrier
; #define PG8_STAGE(bufoff, gbase, voff) do { _Pragma("unroll") for (int _i = 0; _i < 2; ++_i) \
;         __builtin_amdgcn_global_load_lds((const unsigned*)((const char*)(gbase) + (voff)[_i]), (PG8_LAS unsigned*)(lds + (bufoff) + ldsw + _i * 8192), 16, 0, 0); } while (0)
; #define PG8_LDA(dst, b, h) do { _Pragma("unroll") for (int m = 0; m < 4; ++m) _Pragma("unroll") for (int k = 0; k < 2; ++k) dst[m][k] = *(const PG8_LAS bf16x8*)(lds + PG8_SA(b, h) + aoff + m * 2048 + k * 1024); } while (0)
; #define PG8_LDB(dst, b, h) do { _Pragma("unroll") for (int n = 0; n < 2; ++n) _Pragma("unroll") for (int k = 0; k < 2; ++k) dst[n][k] = *(const PG8_LAS bf16x8*)(lds + PG8_SB(b, h) + boff + n * 2048 + k * 1024); } while (0)
; #define PG8_MMA(ai, bj, At, Bt) do { __builtin_amdgcn_s_setprio(1); _Pragma("unroll") for (int m = 0; m < 4; ++m) _Pragma("unroll") for (int n = 0; n < 2; ++n) _Pragma("unroll") for (int k = 0; k < 2; ++k) \
;         acc[ai][bj][m][n] = __builtin_amdgcn_mfma_f32_16x16x32_bf16(Bt[n][k], At[m][k], acc[ai][bj][m][n], 0, 0, 0); __builtin_amdgcn_s_setprio(0); } while (0)
; #define PG8_WAIT_V(n) asm volatile("s_waitcnt vmcnt(" #n ")" ::: "memory")
; #define PG8_WAIT_L(n) asm volatile("s_waitcnt lgkmcnt(" #n ")" ::: "memory")
; #define PG8_BAR __builtin_amdgcn_s_barrier()
; #define PG8_SCHED __builtin_amdgcn_sched_barrier(0)
; template <class Epi, class Sched, bool ALIGN_EPI = false, bool SP2 = false>
; __device__ __forceinline__ void gemm_phase(PG8_LAS unsigned char* lds, const Gemm g, const Sched& S, const Epi& E, const int wave0) {
;     ...
;             PG8_WAIT_V(8); PG8_WAIT_L(0); PG8_BAR; PG8_MMA(0, 0, At, B0); PG8_MMA(0, 1, At, B1); PG8_BAR; PG8_SCHED;
;             PG8_LDA(At, 0, 1); PG8_STAGE(PG8_SB(0, 0), b2, voffB); PG8_STAGE(PG8_SB(0, 1), b2 + hstepB, voffB); PG8_STAGE(PG8_SA(0, 0), a2, voffA);
;             PG8_WAIT_V(8); PG8_WAIT_L(0); PG8_BAR; PG8_MMA(1, 0, At, B0); PG8_MMA(1, 1, At, B1); PG8_BAR; PG8_SCHED;
;             PG8_LDB(B0, 1, 0); PG8_LDB(B1, 1, 1); PG8_SCHED; PG8_LDA(At, 1, 0); PG8_STAGE(PG8_SA(0, 1), a2 + hstepA, voffA);
	s_add_i32 s31, s31, s22
	s_mov_b32 m0, s31
	ds_read_b128 v[194:197], v159 offset:16384
	ds_read_b128 v[208:211], v159 offset:17408
	ds_read_b128 v[212:215], v159 offset:18432
	ds_read_b128 v[216:219], v159 offset:19456
	ds_read_b128 v[220:223], v159 offset:20480
	ds_read_b128 v[224:227], v159 offset:21504
	ds_read_b128 v[228:231], v159 offset:22528
	ds_read_b128 v[232:235], v159 offset:23552
	global_load_lds_dwordx4 v64, s[2:3]
	s_add_i32 m0, s31, 0x2000
	s_add_u32 s34, s2, 0x40000
	s_addc_u32 s35, s3, 0
	s_add_i32 s31, s33, s22
	global_load_lds_dwordx4 v138, s[2:3]
	s_mov_b32 m0, s31
	s_mov_b64 s[100:101], s[16:17]
	global_load_lds_dwordx4 v64, s[34:35]
	s_add_i32 m0, s31, 0x2000
	s_nop 0
	global_load_lds_dwordx4 v138, s[34:35]
	s_mov_b32 m0, s23
	s_nop 0
	global_load_lds_dwordx4 v142, s[16:17]
	s_mov_b32 m0, s24
	s_nop 0
	global_load_lds_dwordx4 v140, s[16:17]
	s_waitcnt vmcnt(8)
	s_waitcnt lgkmcnt(0)
	s_barrier
	s_setprio 1
	s_waitcnt lgkmcnt(0)
	v_mfma_f32_16x16x32_bf16 v[60:63], v[130:133], v[194:197], v[60:63]
	v_mfma_f32_16x16x32_bf16 v[56:59], v[148:151], v[194:197], v[56:59]
	v_mfma_f32_16x16x32_bf16 v[44:47], v[130:133], v[212:215], v[44:47]
	v_mfma_f32_16x16x32_bf16 v[40:43], v[148:151], v[212:215], v[40:43]
	v_mfma_f32_16x16x32_bf16 v[28:31], v[130:133], v[220:223], v[28:31]
	v_mfma_f32_16x16x32_bf16 v[24:27], v[148:151], v[220:223], v[24:27]
	v_mfma_f32_16x16x32_bf16 v[12:15], v[130:133], v[228:231], v[12:15]
	v_mfma_f32_16x16x32_bf16 v[8:11], v[148:151], v[228:231], v[8:11]
	v_mfma_f32_16x16x32_bf16 v[60:63], v[134:137], v[208:211], v[60:63]
	v_mfma_f32_16x16x32_bf16 v[56:59], v[152:155], v[208:211], v[56:59]
	v_mfma_f32_16x16x32_bf16 v[44:47], v[134:137], v[216:219], v[44:47]
	v_mfma_f32_16x16x32_bf16 v[40:43], v[152:155], v[216:219], v[40:43]
	v_mfma_f32_16x16x32_bf16 v[28:31], v[134:137], v[224:227], v[28:31]
	v_mfma_f32_16x16x32_bf16 v[24:27], v[152:155], v[224:227], v[24:27]
	v_mfma_f32_16x16x32_bf16 v[12:15], v[134:137], v[232:235], v[12:15]
	v_mfma_f32_16x16x32_bf16 v[8:11], v[152:155], v[232:235], v[8:11]
	s_setprio 0
	s_setprio 1
	v_mfma_f32_16x16x32_bf16 v[52:55], v[178:181], v[194:197], v[52:55]
	v_mfma_f32_16x16x32_bf16 v[48:51], v[186:189], v[194:197], v[48:51]
	v_mfma_f32_16x16x32_bf16 v[36:39], v[178:181], v[212:215], v[36:39]
	v_mfma_f32_16x16x32_bf16 v[32:35], v[186:189], v[212:215], v[32:35]
	v_mfma_f32_16x16x32_bf16 v[20:23], v[178:181], v[220:223], v[20:23]
	v_mfma_f32_16x16x32_bf16 v[16:19], v[186:189], v[220:223], v[16:19]
	v_mfma_f32_16x16x32_bf16 v[4:7], v[178:181], v[228:231], v[4:7]
	v_mfma_f32_16x16x32_bf16 v[0:3], v[186:189], v[228:231], v[0:3]
	v_mfma_f32_16x16x32_bf16 v[52:55], v[182:185], v[208:211], v[52:55]
	v_mfma_f32_16x16x32_bf16 v[48:51], v[190:193], v[208:211], v[48:51]
	v_mfma_f32_16x16x32_bf16 v[36:39], v[182:185], v[216:219], v[36:39]
	v_mfma_f32_16x16x32_bf16 v[32:35], v[190:193], v[216:219], v[32:35]
	v_mfma_f32_16x16x32_bf16 v[20:23], v[182:185], v[224:227], v[20:23]
	v_mfma_f32_16x16x32_bf16 v[16:19], v[190:193], v[224:227], v[16:19]
	v_mfma_f32_16x16x32_bf16 v[4:7], v[182:185], v[232:235], v[4:7]
	v_mfma_f32_16x16x32_bf16 v[0:3], v[190:193], v[232:235], v[0:3]
	s_setprio 0
	s_barrier
	s_add_i32 s31, 0, 0x18000
	s_add_i32 s33, 0, 0x1c000
	ds_read_b128 v[130:133], v254
	ds_read_b128 v[134:137], v254 offset:1024
	ds_read_b128 v[148:151], v254 offset:2048
	ds_read_b128 v[152:155], v254 offset:3072
	ds_read_b128 v[178:181], v255
	ds_read_b128 v[182:185], v255 offset:1024
	ds_read_b128 v[186:189], v255 offset:2048
	ds_read_b128 v[190:193], v255 offset:3072
	s_add_u32 s16, s16, 0x40000
	s_addc_u32 s17, s17, 0
	s_mov_b32 m0, s25
	ds_read_b128 v[194:197], v159 offset:32768
	ds_read_b128 v[208:211], v159 offset:33792
	ds_read_b128 v[212:215], v159 offset:34816
	ds_read_b128 v[216:219], v159 offset:35840
	ds_read_b128 v[220:223], v159 offset:36864
	ds_read_b128 v[224:227], v159 offset:37888
	ds_read_b128 v[228:231], v159 offset:38912
	ds_read_b128 v[232:235], v159 offset:39936
	global_load_lds_dwordx4 v142, s[16:17]
	s_mov_b32 m0, s26
	s_nop 0
	global_load_lds_dwordx4 v140, s[16:17]
	s_waitcnt vmcnt(8)
	s_waitcnt lgkmcnt(0)
	s_barrier
; #define PG8_STAGE(bufoff, gbase, voff) do { _Pragma("unroll") for (int _i = 0; _i < 2; ++_i) \
;         __builtin_amdgcn_global_load_lds((const unsigned*)((const char*)(gbase) + (voff)[_i]), (PG8_LAS unsigned*)(lds + (bufoff) + ldsw + _i * 8192), 16, 0, 0); } while (0)
; #define PG8_LDA(dst, b, h) do { _Pragma("unroll") for (int m = 0; m < 4; ++m) _Pragma("unroll") for (int k = 0; k < 2; ++k) dst[m][k] = *(const PG8_LAS bf16x8*)(lds + PG8_SA(b, h) + aoff + m * 2048 + k * 1024); } while (0)
; #define PG8_MMA(ai, bj, At, Bt) do { __builtin_amdgcn_s_setprio(1); _Pragma("unroll") for (int m = 0; m < 4; ++m) _Pragma("unroll") for (int n = 0; n < 2; ++n) _Pragma("unroll") for (int k = 0; k < 2; ++k) \
;         acc[ai][bj][m][n] = __builtin_amdgcn_mfma_f32_16x16x32_bf16(Bt[n][k], At[m][k], acc[ai][bj][m][n], 0, 0, 0); __builtin_amdgcn_s_setprio(0); } while (0)
; #define PG8_WAIT_V(n) asm volatile("s_waitcnt vmcnt(" #n ")" ::: "memory")
; #define PG8_WAIT_L(n) asm volatile("s_waitcnt lgkmcnt(" #n ")" ::: "memory")
; #define PG8_BAR __builtin_amdgcn_s_barrier()
; #define PG8_SCHED __builtin_amdgcn_sched_barrier(0)
; template <class Epi, class Sched, bool ALIGN_EPI = false, bool SP2 = false>
; __device__ __forceinline__ void gemm_phase(PG8_LAS unsigned char* lds, const Gemm g, const Sched& S, const Epi& E, const int wave0) {
;     ...
;         for (int t = 0; t < nt; t += 2) {
;     ...
;             PG8_WAIT_V(8); PG8_WAIT_L(0); PG8_BAR; PG8_MMA(0, 0, At, B0); PG8_MMA(0, 1, At, B1); PG8_BAR; PG8_SCHED;
;             PG8_LDA(At, 1, 1); PG8_STAGE(PG8_SB(1, 0), b3, voffB); PG8_STAGE(PG8_SB(1, 1), b3 + hstepB, voffB); PG8_STAGE(PG8_SA(1, 0), a3, voffA);
;             PG8_WAIT_V(8); PG8_WAIT_L(0); PG8_BAR; PG8_MMA(1, 0, At, B0); PG8_MMA(1, 1, At, B1); PG8_BAR; PG8_SCHED;
	s_setprio 1
	s_waitcnt lgkmcnt(0)
	v_mfma_f32_16x16x32_bf16 v[126:129], v[130:133], v[194:197], v[126:129]
	v_mfma_f32_16x16x32_bf16 v[122:125], v[148:151], v[194:197], v[122:125]
	v_mfma_f32_16x16x32_bf16 v[110:113], v[130:133], v[212:215], v[110:113]
	v_mfma_f32_16x16x32_bf16 v[106:109], v[148:151], v[212:215], v[106:109]
	v_mfma_f32_16x16x32_bf16 v[94:97], v[130:133], v[220:223], v[94:97]
	v_mfma_f32_16x16x32_bf16 v[90:93], v[148:151], v[220:223], v[90:93]
	v_mfma_f32_16x16x32_bf16 v[78:81], v[130:133], v[228:231], v[78:81]
	v_mfma_f32_16x16x32_bf16 v[74:77], v[148:151], v[228:231], v[74:77]
	v_mfma_f32_16x16x32_bf16 v[126:129], v[134:137], v[208:211], v[126:129]
	v_mfma_f32_16x16x32_bf16 v[122:125], v[152:155], v[208:211], v[122:125]
	v_mfma_f32_16x16x32_bf16 v[110:113], v[134:137], v[216:219], v[110:113]
	v_mfma_f32_16x16x32_bf16 v[106:109], v[152:155], v[216:219], v[106:109]
	v_mfma_f32_16x16x32_bf16 v[94:97], v[134:137], v[224:227], v[94:97]
	v_mfma_f32_16x16x32_bf16 v[90:93], v[152:155], v[224:227], v[90:93]
	v_mfma_f32_16x16x32_bf16 v[78:81], v[134:137], v[232:235], v[78:81]
	v_mfma_f32_16x16x32_bf16 v[74:77], v[152:155], v[232:235], v[74:77]
	s_setprio 0
	s_setprio 1
	v_mfma_f32_16x16x32_bf16 v[118:121], v[178:181], v[194:197], v[118:121]
	v_mfma_f32_16x16x32_bf16 v[114:117], v[186:189], v[194:197], v[114:117]
	v_mfma_f32_16x16x32_bf16 v[102:105], v[178:181], v[212:215], v[102:105]
	v_mfma_f32_16x16x32_bf16 v[98:101], v[186:189], v[212:215], v[98:101]
	v_mfma_f32_16x16x32_bf16 v[86:89], v[178:181], v[220:223], v[86:89]
	v_mfma_f32_16x16x32_bf16 v[82:85], v[186:189], v[220:223], v[82:85]
	v_mfma_f32_16x16x32_bf16 v[70:73], v[178:181], v[228:231], v[70:73]
	v_mfma_f32_16x16x32_bf16 v[66:69], v[186:189], v[228:231], v[66:69]
	v_mfma_f32_16x16x32_bf16 v[118:121], v[182:185], v[208:211], v[118:121]
	v_mfma_f32_16x16x32_bf16 v[114:117], v[190:193], v[208:211], v[114:117]
	v_mfma_f32_16x16x32_bf16 v[102:105], v[182:185], v[216:219], v[102:105]
	v_mfma_f32_16x16x32_bf16 v[98:101], v[190:193], v[216:219], v[98:101]
	v_mfma_f32_16x16x32_bf16 v[86:89], v[182:185], v[224:227], v[86:89]
	v_mfma_f32_16x16x32_bf16 v[82:85], v[190:193], v[224:227], v[82:85]
	v_mfma_f32_16x16x32_bf16 v[70:73], v[182:185], v[232:235], v[70:73]
	v_mfma_f32_16x16x32_bf16 v[66:69], v[190:193], v[232:235], v[66:69]
	s_setprio 0
	s_barrier
	s_add_i32 s16, s31, s22
	s_add_u32 s36, s2, 0x80
	s_addc_u32 s37, s3, 0
	s_mov_b32 m0, s16
	ds_read_b128 v[194:197], v159 offset:49152
	ds_read_b128 v[208:211], v159 offset:50176
	ds_read_b128 v[212:215], v159 offset:51200
	ds_read_b128 v[216:219], v159 offset:52224
	ds_read_b128 v[220:223], v159 offset:53248
	ds_read_b128 v[224:227], v159 offset:54272
	ds_read_b128 v[228:231], v159 offset:55296
	ds_read_b128 v[232:235], v159 offset:56320
	global_load_lds_dwordx4 v64, s[36:37]
	s_add_i32 m0, s16, 0x2000
	s_add_u32 s2, s2, 0x40080
	s_addc_u32 s3, s3, 0
	s_add_i32 s16, s33, s22
	global_load_lds_dwordx4 v138, s[36:37]
	s_mov_b32 m0, s16
	s_nop 0
	global_load_lds_dwordx4 v64, s[2:3]
	s_add_i32 m0, s16, 0x2000
	s_nop 0
	global_load_lds_dwordx4 v138, s[2:3]
	s_add_u32 s100, s100, 0x80
	s_addc_u32 s101, s101, 0
	s_mov_b32 m0, s27
	s_nop 0
	global_load_lds_dwordx4 v142, s[100:101]
	s_mov_b32 m0, s28
	s_nop 0
	global_load_lds_dwordx4 v140, s[100:101]
	s_waitcnt vmcnt(8)
	s_waitcnt lgkmcnt(0)
	s_barrier
	s_setprio 1
	s_waitcnt lgkmcnt(0)
	v_mfma_f32_16x16x32_bf16 v[60:63], v[130:133], v[194:197], v[60:63]
	v_mfma_f32_16x16x32_bf16 v[56:59], v[148:151], v[194:197], v[56:59]
	v_mfma_f32_16x16x32_bf16 v[44:47], v[130:133], v[212:215], v[44:47]
	v_mfma_f32_16x16x32_bf16 v[40:43], v[148:151], v[212:215], v[40:43]
	v_mfma_f32_16x16x32_bf16 v[28:31], v[130:133], v[220:223], v[28:31]
	v_mfma_f32_16x16x32_bf16 v[24:27], v[148:151], v[220:223], v[24:27]
	v_mfma_f32_16x16x32_bf16 v[12:15], v[130:133], v[228:231], v[12:15]
	v_mfma_f32_16x16x32_bf16 v[8:11], v[148:151], v[228:231], v[8:11]
	v_mfma_f32_16x16x32_bf16 v[60:63], v[134:137], v[208:211], v[60:63]
	v_mfma_f32_16x16x32_bf16 v[56:59], v[152:155], v[208:211], v[56:59]
	v_mfma_f32_16x16x32_bf16 v[44:47], v[134:137], v[216:219], v[44:47]
	v_mfma_f32_16x16x32_bf16 v[40:43], v[152:155], v[216:219], v[40:43]
	v_mfma_f32_16x16x32_bf16 v[28:31], v[134:137], v[224:227], v[28:31]
	v_mfma_f32_16x16x32_bf16 v[24:27], v[152:155], v[224:227], v[24:27]
	v_mfma_f32_16x16x32_bf16 v[12:15], v[134:137], v[232:235], v[12:15]
	v_mfma_f32_16x16x32_bf16 v[8:11], v[152:155], v[232:235], v[8:11]
	s_setprio 0
	s_setprio 1
	v_mfma_f32_16x16x32_bf16 v[52:55], v[178:181], v[194:197], v[52:55]
	v_mfma_f32_16x16x32_bf16 v[48:51], v[186:189], v[194:197], v[48:51]
	v_mfma_f32_16x16x32_bf16 v[36:39], v[178:181], v[212:215], v[36:39]
	v_mfma_f32_16x16x32_bf16 v[32:35], v[186:189], v[212:215], v[32:35]
	v_mfma_f32_16x16x32_bf16 v[20:23], v[178:181], v[220:223], v[20:23]
	v_mfma_f32_16x16x32_bf16 v[16:19], v[186:189], v[220:223], v[16:19]
	v_mfma_f32_16x16x32_bf16 v[4:7], v[178:181], v[228:231], v[4:7]
	v_mfma_f32_16x16x32_bf16 v[0:3], v[186:189], v[228:231], v[0:3]
	v_mfma_f32_16x16x32_bf16 v[52:55], v[182:185], v[208:211], v[52:55]
	v_mfma_f32_16x16x32_bf16 v[48:51], v[190:193], v[208:211], v[48:51]
	v_mfma_f32_16x16x32_bf16 v[36:39], v[182:185], v[216:219], v[36:39]
	v_mfma_f32_16x16x32_bf16 v[32:35], v[190:193], v[216:219], v[32:35]
	v_mfma_f32_16x16x32_bf16 v[20:23], v[182:185], v[224:227], v[20:23]
	v_mfma_f32_16x16x32_bf16 v[16:19], v[190:193], v[224:227], v[16:19]
	v_mfma_f32_16x16x32_bf16 v[4:7], v[182:185], v[232:235], v[4:7]
	v_mfma_f32_16x16x32_bf16 v[0:3], v[190:193], v[232:235], v[0:3]
	s_setprio 0
	s_barrier
	s_add_i32 s19, s19, 2
	s_add_u32 s0, s0, 0x100
	s_addc_u32 s1, s1, 0
	s_add_u32 s13, s13, 0x100
	s_addc_u32 s18, s18, 0
	s_cmp_gt_u32 s19, 13
	s_cbranch_scc0 .LBB0_1178
	s_mov_b64 s[36:37], 0x80
	s_and_b64 vcc, exec, s[6:7]
	s_cbranch_vccz .LBB0_1181
	s_barrier

; #define PG8_STAGE(bufoff, gbase, voff) do { _Pragma("unroll") for (int _i = 0; _i < 2; ++_i) \
;         __builtin_amdgcn_global_load_lds((const unsigned*)((const char*)(gbase) + (voff)[_i]), (PG8_LAS unsigned*)(lds + (bufoff) + ldsw + _i * 8192), 16, 0, 0); } while (0)
; #define PG8_LDA(dst, b, h) do { _Pragma("unroll") for (int m = 0; m < 4; ++m) _Pragma("unroll") for (int k = 0; k < 2; ++k) dst[m][k] = *(const PG8_LAS bf16x8*)(lds + PG8_SA(b, h) + aoff + m * 2048 + k * 1024); } while (0)
; #define PG8_LDB(dst, b, h) do { _Pragma("unroll") for (int n = 0; n < 2; ++n) _Pragma("unroll") for (int k = 0; k < 2; ++k) dst[n][k] = *(const PG8_LAS bf16x8*)(lds + PG8_SB(b, h) + boff + n * 2048 + k * 1024); } while (0)
; #define PG8_MMA(ai, bj, At, Bt) do { __builtin_amdgcn_s_setprio(1); _Pragma("unroll") for (int m = 0; m < 4; ++m) _Pragma("unroll") for (int n = 0; n < 2; ++n) _Pragma("unroll") for (int k = 0; k < 2; ++k) \
;         acc[ai][bj][m][n] = __builtin_amdgcn_mfma_f32_16x16x32_bf16(Bt[n][k], At[m][k], acc[ai][bj][m][n], 0, 0, 0); __builtin_amdgcn_s_setprio(0); } while (0)
; #define PG8_WAIT_V(n) asm volatile("s_waitcnt vmcnt(" #n ")" ::: "memory")
; #define PG8_WAIT_L(n) asm volatile("s_waitcnt lgkmcnt(" #n ")" ::: "memory")
; #define PG8_BAR __builtin_amdgcn_s_barrier()
; #define PG8_SCHED __builtin_amdgcn_sched_barrier(0)
; template <class Epi, class Sched, bool ALIGN_EPI = false, bool SP2 = false>
; __device__ __forceinline__ void gemm_phase(PG8_LAS unsigned char* lds, const Gemm g, const Sched& S, const Epi& E, const int wave0) {
;     ...
;             if constexpr (SP2) {
;             PG8_LDB(B0, 0, 0); PG8_LDB(B1, 0, 1); PG8_SCHED; PG8_LDA(At, 0, 0); PG8_STAGE(PG8_SA(1, 1), a1 + hstepA, voffA);
;             PG8_WAIT_V(8); PG8_WAIT_L(0); PG8_BAR; PG8_MMA(0, 0, At, B0); PG8_MMA(0, 1, At, B1); PG8_BAR; PG8_SCHED;
;     ...
;         for (int a = 0; a < 2; ++a)
; #pragma unroll
;             for (int b = 0; b < 2; ++b)
; #pragma unroll
;                 for (int m = 0; m < 4; ++m)
; #pragma unroll
;                     for (int n = 0; n < 2; ++n) acc[a][b][m][n] = (f32x4){0.f, 0.f, 0.f, 0.f};
.LBB0_1230:
	s_lshl_b64 s[18:19], s[8:9], 22
	s_add_u32 s9, s20, s18
	s_addc_u32 s11, s21, s19
	s_ashr_i32 s13, s12, 31
	s_lshl_b64 s[18:19], s[12:13], 19
	s_add_u32 s44, s9, s18
	s_addc_u32 s45, s11, s19
	s_and_b64 s[2:3], s[2:3], exec
	s_cselect_b32 s9, s45, s17
	s_cselect_b32 s11, s44, s16
	s_add_u32 s0, s0, 0x40080
	s_addc_u32 s1, s1, 0
	s_add_u32 s13, s16, 0x100
	v_mov_b32_e32 v0, 0
	s_addc_u32 s18, s17, 0
	s_mov_b32 s19, -2
	v_mov_b32_e32 v1, v0
	v_mov_b64_e32 v[2:3], 0
	v_mov_b64_e32 v[4:5], 0
	v_mov_b64_e32 v[6:7], 0
	v_mov_b64_e32 v[16:17], 0
	v_mov_b64_e32 v[18:19], 0
	v_mov_b64_e32 v[20:21], 0
	v_mov_b64_e32 v[22:23], 0
	v_mov_b64_e32 v[32:33], 0
	v_mov_b64_e32 v[34:35], 0
	v_mov_b64_e32 v[36:37], 0
	v_mov_b64_e32 v[38:39], 0
	v_mov_b64_e32 v[48:49], 0
	v_mov_b64_e32 v[50:51], 0
	v_mov_b64_e32 v[52:53], 0
	v_mov_b64_e32 v[54:55], 0
	v_mov_b64_e32 v[8:9], 0
	v_mov_b64_e32 v[10:11], 0
	v_mov_b64_e32 v[12:13], 0
	v_mov_b64_e32 v[14:15], 0
	v_mov_b64_e32 v[24:25], 0
	v_mov_b64_e32 v[26:27], 0
	v_mov_b64_e32 v[28:29], 0
	v_mov_b64_e32 v[30:31], 0
	v_mov_b64_e32 v[40:41], 0
	v_mov_b64_e32 v[42:43], 0
	v_mov_b64_e32 v[44:45], 0
	v_mov_b64_e32 v[46:47], 0
	v_mov_b64_e32 v[56:57], 0
	v_mov_b64_e32 v[58:59], 0
	v_mov_b64_e32 v[60:61], 0
	v_mov_b64_e32 v[62:63], 0
	v_mov_b64_e32 v[66:67], 0
	v_mov_b64_e32 v[68:69], 0
	v_mov_b64_e32 v[70:71], 0
	v_mov_b64_e32 v[72:73], 0
	v_mov_b64_e32 v[82:83], 0
	v_mov_b64_e32 v[84:85], 0
	v_mov_b64_e32 v[86:87], 0
	v_mov_b64_e32 v[88:89], 0
	v_mov_b64_e32 v[98:99], 0
	v_mov_b64_e32 v[100:101], 0
	v_mov_b64_e32 v[102:103], 0
	v_mov_b64_e32 v[104:105], 0
	v_mov_b64_e32 v[114:115], 0
	v_mov_b64_e32 v[116:117], 0
	v_mov_b64_e32 v[118:119], 0
	v_mov_b64_e32 v[120:121], 0
	v_mov_b64_e32 v[74:75], 0
	v_mov_b64_e32 v[76:77], 0
	v_mov_b64_e32 v[78:79], 0
	v_mov_b64_e32 v[80:81], 0
	v_mov_b64_e32 v[90:91], 0
	v_mov_b64_e32 v[92:93], 0
	v_mov_b64_e32 v[94:95], 0
	v_mov_b64_e32 v[96:97], 0
	v_mov_b64_e32 v[106:107], 0
	v_mov_b64_e32 v[108:109], 0
	v_mov_b64_e32 v[110:111], 0
	v_mov_b64_e32 v[112:113], 0
	v_mov_b64_e32 v[122:123], 0
	v_mov_b64_e32 v[124:125], 0
	v_mov_b64_e32 v[126:127], 0
	v_mov_b64_e32 v[128:129], 0
	v_add_u32_e32 v252, 0x10000, v151
	v_add_u32_e32 v253, 0x14000, v151
	v_add_u32_e32 v254, 0x18000, v151
	v_add_u32_e32 v255, 0x1c000, v151
.LBB0_1231:
	s_add_u32 s2, s0, 0xfffc0080
	s_addc_u32 s3, s1, -1
	s_add_i32 s31, 0, 0x10000
	s_cmp_eq_u32 s19, 12
	s_cselect_b32 s17, s43, s3
	s_cselect_b32 s16, s42, s2
	s_cselect_b32 s3, s9, s18
	s_cselect_b32 s2, s11, s13
	s_add_i32 s33, 0, 0x14000
	ds_read_b128 v[140:143], v252
	ds_read_b128 v[144:147], v252 offset:1024
	ds_read_b128 v[154:157], v252 offset:2048
	ds_read_b128 v[158:161], v252 offset:3072
	ds_read_b128 v[178:181], v253
	ds_read_b128 v[182:185], v253 offset:1024
	ds_read_b128 v[186:189], v253 offset:2048
	ds_read_b128 v[190:193], v253 offset:3072
	s_add_i32 m0, s23, 0xc000
	ds_read_b128 v[194:197], v153
	ds_read_b128 v[208:211], v153 offset:1024
	ds_read_b128 v[212:215], v153 offset:2048
	ds_read_b128 v[216:219], v153 offset:3072
	ds_read_b128 v[220:223], v153 offset:4096
	ds_read_b128 v[224:227], v153 offset:5120
	ds_read_b128 v[228:231], v153 offset:6144
	ds_read_b128 v[232:235], v153 offset:7168
	global_load_lds_dwordx4 v136, s[0:1]
	s_add_i32 m0, s23, 0xe000
	s_nop 0
	global_load_lds_dwordx4 v138, s[0:1]
	s_waitcnt vmcnt(8)
	s_waitcnt lgkmcnt(0)
	s_barrier
	s_setprio 1
	s_waitcnt lgkmcnt(0)
	v_mfma_f32_16x16x32_bf16 v[126:129], v[140:143], v[194:197], v[126:129]
	v_mfma_f32_16x16x32_bf16 v[122:125], v[154:157], v[194:197], v[122:125]
	v_mfma_f32_16x16x32_bf16 v[110:113], v[140:143], v[212:215], v[110:113]
	v_mfma_f32_16x16x32_bf16 v[106:109], v[154:157], v[212:215], v[106:109]
	v_mfma_f32_16x16x32_bf16 v[94:97], v[140:143], v[220:223], v[94:97]
	v_mfma_f32_16x16x32_bf16 v[90:93], v[154:157], v[220:223], v[90:93]
	v_mfma_f32_16x16x32_bf16 v[78:81], v[140:143], v[228:231], v[78:81]
	v_mfma_f32_16x16x32_bf16 v[74:77], v[154:157], v[228:231], v[74:77]
	v_mfma_f32_16x16x32_bf16 v[126:129], v[144:147], v[208:211], v[126:129]
	v_mfma_f32_16x16x32_bf16 v[122:125], v[158:161], v[208:211], v[122:125]
	v_mfma_f32_16x16x32_bf16 v[110:113], v[144:147], v[216:219], v[110:113]
	v_mfma_f32_16x16x32_bf16 v[106:109], v[158:161], v[216:219], v[106:109]
	v_mfma_f32_16x16x32_bf16 v[94:97], v[144:147], v[224:227], v[94:97]
	v_mfma_f32_16x16x32_bf16 v[90:93], v[158:161], v[224:227], v[90:93]
	v_mfma_f32_16x16x32_bf16 v[78:81], v[144:147], v[232:235], v[78:81]
	v_mfma_f32_16x16x32_bf16 v[74:77], v[158:161], v[232:235], v[74:77]
	s_setprio 0
	s_setprio 1
	v_mfma_f32_16x16x32_bf16 v[118:121], v[178:181], v[194:197], v[118:121]
	v_mfma_f32_16x16x32_bf16 v[114:117], v[186:189], v[194:197], v[114:117]
	v_mfma_f32_16x16x32_bf16 v[102:105], v[178:181], v[212:215], v[102:105]
	v_mfma_f32_16x16x32_bf16 v[98:101], v[186:189], v[212:215], v[98:101]
	v_mfma_f32_16x16x32_bf16 v[86:89], v[178:181], v[220:223], v[86:89]
	v_mfma_f32_16x16x32_bf16 v[82:85], v[186:189], v[220:223], v[82:85]
	v_mfma_f32_16x16x32_bf16 v[70:73], v[178:181], v[228:231], v[70:73]
	v_mfma_f32_16x16x32_bf16 v[66:69], v[186:189], v[228:231], v[66:69]
	v_mfma_f32_16x16x32_bf16 v[118:121], v[182:185], v[208:211], v[118:121]
	v_mfma_f32_16x16x32_bf16 v[114:117], v[190:193], v[208:211], v[114:117]
	v_mfma_f32_16x16x32_bf16 v[102:105], v[182:185], v[216:219], v[102:105]
	v_mfma_f32_16x16x32_bf16 v[98:101], v[190:193], v[216:219], v[98:101]
	v_mfma_f32_16x16x32_bf16 v[86:89], v[182:185], v[224:227], v[86:89]
	v_mfma_f32_16x16x32_bf16 v[82:85], v[190:193], v[224:227], v[82:85]
	v_mfma_f32_16x16x32_bf16 v[70:73], v[182:185], v[232:235], v[70:73]
	v_mfma_f32_16x16x32_bf16 v[66:69], v[190:193], v[232:235], v[66:69]
	s_setprio 0
	s_barrier
; #define PG8_STAGE(bufoff, gbase, voff) do { _Pragma("unroll") for (int _i = 0; _i < 2; ++_i) \
;         __builtin_amdgcn_global_load_lds((const unsigned*)((const char*)(gbase) + (voff)[_i]), (PG8_LAS unsigned*)(lds + (bufoff) + ldsw + _i * 8192), 16, 0, 0); } while (0)
; #define PG8_LDA(dst, b, h) do { _Pragma("unroll") for (int m = 0; m < 4; ++m) _Pragma("unroll") for (int k = 0; k < 2; ++k) dst[m][k] = *(const PG8_LAS bf16x8*)(lds + PG8_SA(b, h) + aoff + m * 2048 + k * 1024); } while (0)
; #define PG8_LDB(dst, b, h) do { _Pragma("unroll") for (int n = 0; n < 2; ++n) _Pragma("unroll") for (int k = 0; k < 2; ++k) dst[n][k] = *(const PG8_LAS bf16x8*)(lds + PG8_SB(b, h) + boff + n * 2048 + k * 1024); } while (0)
; #define PG8_MMA(ai, bj, At, Bt) do { __builtin_amdgcn_s_setprio(1); _Pragma("unroll") for (int m = 0; m < 4; ++m) _Pragma("unroll") for (int n = 0; n < 2; ++n) _Pragma("unroll") for (int k = 0; k < 2; ++k) \
;         acc[ai][bj][m][n] = __builtin_amdgcn_mfma_f32_16x16x32_bf16(Bt[n][k], At[m][k], acc[ai][bj][m][n], 0, 0, 0); __builtin_amdgcn_s_setprio(0); } while (0)
; #define PG8_WAIT_V(n) asm volatile("s_waitcnt vmcnt(" #n ")" ::: "memory")
; #define PG8_WAIT_L(n) asm volatile("s_waitcnt lgkmcnt(" #n ")" ::: "memory")
; #define PG8_BAR __builtin_amdgcn_s_barrier()
; #define PG8_SCHED __builtin_amdgcn_sched_barrier(0)
; template <class Epi, class Sched, bool ALIGN_EPI = false, bool SP2 = false>
; __device__ __forceinline__ void gemm_phase(PG8_LAS unsigned char* lds, const Gemm g, const Sched& S, const Epi& E, const int wave0) {
;     ...
;             PG8_WAIT_V(8); PG8_WAIT_L(0); PG8_BAR; PG8_MMA(0, 0, At, B0); PG8_MMA(0, 1, At, B1); PG8_BAR; PG8_SCHED;
;             PG8_LDA(At, 0, 1); PG8_STAGE(PG8_SB(0, 0), b2, voffB); PG8_STAGE(PG8_SB(0, 1), b2 + hstepB, voffB); PG8_STAGE(PG8_SA(0, 0), a2, voffA);
;             PG8_WAIT_V(8); PG8_WAIT_L(0); PG8_BAR; PG8_MMA(1, 0, At, B0); PG8_MMA(1, 1, At, B1); PG8_BAR; PG8_SCHED;
;             PG8_LDB(B0, 1, 0); PG8_LDB(B1, 1, 1); PG8_SCHED; PG8_LDA(At, 1, 0); PG8_STAGE(PG8_SA(0, 1), a2 + hstepA, voffA);
	s_add_i32 s31, s31, s22
	s_mov_b32 m0, s31
	ds_read_b128 v[194:197], v153 offset:16384
	ds_read_b128 v[208:211], v153 offset:17408
	ds_read_b128 v[212:215], v153 offset:18432
	ds_read_b128 v[216:219], v153 offset:19456
	ds_read_b128 v[220:223], v153 offset:20480
	ds_read_b128 v[224:227], v153 offset:21504
	ds_read_b128 v[228:231], v153 offset:22528
	ds_read_b128 v[232:235], v153 offset:23552
	global_load_lds_dwordx4 v64, s[2:3]
	s_add_i32 m0, s31, 0x2000
	s_add_u32 s34, s2, 0x40000
	s_addc_u32 s35, s3, 0
	s_add_i32 s31, s33, s22
	global_load_lds_dwordx4 v130, s[2:3]
	s_mov_b32 m0, s31
	s_mov_b64 s[100:101], s[16:17]
	global_load_lds_dwordx4 v64, s[34:35]
	s_add_i32 m0, s31, 0x2000
	s_nop 0
	global_load_lds_dwordx4 v130, s[34:35]
	s_mov_b32 m0, s23
	s_nop 0
	global_load_lds_dwordx4 v134, s[16:17]
	s_mov_b32 m0, s24
	s_nop 0
	global_load_lds_dwordx4 v132, s[16:17]
	s_waitcnt vmcnt(8)
	s_waitcnt lgkmcnt(0)
	s_barrier
	s_setprio 1
	s_waitcnt lgkmcnt(0)
	v_mfma_f32_16x16x32_bf16 v[60:63], v[140:143], v[194:197], v[60:63]
	v_mfma_f32_16x16x32_bf16 v[56:59], v[154:157], v[194:197], v[56:59]
	v_mfma_f32_16x16x32_bf16 v[44:47], v[140:143], v[212:215], v[44:47]
	v_mfma_f32_16x16x32_bf16 v[40:43], v[154:157], v[212:215], v[40:43]
	v_mfma_f32_16x16x32_bf16 v[28:31], v[140:143], v[220:223], v[28:31]
	v_mfma_f32_16x16x32_bf16 v[24:27], v[154:157], v[220:223], v[24:27]
	v_mfma_f32_16x16x32_bf16 v[12:15], v[140:143], v[228:231], v[12:15]
	v_mfma_f32_16x16x32_bf16 v[8:11], v[154:157], v[228:231], v[8:11]
	v_mfma_f32_16x16x32_bf16 v[60:63], v[144:147], v[208:211], v[60:63]
	v_mfma_f32_16x16x32_bf16 v[56:59], v[158:161], v[208:211], v[56:59]
	v_mfma_f32_16x16x32_bf16 v[44:47], v[144:147], v[216:219], v[44:47]
	v_mfma_f32_16x16x32_bf16 v[40:43], v[158:161], v[216:219], v[40:43]
	v_mfma_f32_16x16x32_bf16 v[28:31], v[144:147], v[224:227], v[28:31]
	v_mfma_f32_16x16x32_bf16 v[24:27], v[158:161], v[224:227], v[24:27]
	v_mfma_f32_16x16x32_bf16 v[12:15], v[144:147], v[232:235], v[12:15]
	v_mfma_f32_16x16x32_bf16 v[8:11], v[158:161], v[232:235], v[8:11]
	s_setprio 0
	s_setprio 1
	v_mfma_f32_16x16x32_bf16 v[52:55], v[178:181], v[194:197], v[52:55]
	v_mfma_f32_16x16x32_bf16 v[48:51], v[186:189], v[194:197], v[48:51]
	v_mfma_f32_16x16x32_bf16 v[36:39], v[178:181], v[212:215], v[36:39]
	v_mfma_f32_16x16x32_bf16 v[32:35], v[186:189], v[212:215], v[32:35]
	v_mfma_f32_16x16x32_bf16 v[20:23], v[178:181], v[220:223], v[20:23]
	v_mfma_f32_16x16x32_bf16 v[16:19], v[186:189], v[220:223], v[16:19]
	v_mfma_f32_16x16x32_bf16 v[4:7], v[178:181], v[228:231], v[4:7]
	v_mfma_f32_16x16x32_bf16 v[0:3], v[186:189], v[228:231], v[0:3]
	v_mfma_f32_16x16x32_bf16 v[52:55], v[182:185], v[208:211], v[52:55]
	v_mfma_f32_16x16x32_bf16 v[48:51], v[190:193], v[208:211], v[48:51]
	v_mfma_f32_16x16x32_bf16 v[36:39], v[182:185], v[216:219], v[36:39]
	v_mfma_f32_16x16x32_bf16 v[32:35], v[190:193], v[216:219], v[32:35]
	v_mfma_f32_16x16x32_bf16 v[20:23], v[182:185], v[224:227], v[20:23]
	v_mfma_f32_16x16x32_bf16 v[16:19], v[190:193], v[224:227], v[16:19]
	v_mfma_f32_16x16x32_bf16 v[4:7], v[182:185], v[232:235], v[4:7]
	v_mfma_f32_16x16x32_bf16 v[0:3], v[190:193], v[232:235], v[0:3]
	s_setprio 0
	s_barrier
	s_add_i32 s31, 0, 0x18000
	s_add_i32 s33, 0, 0x1c000
	ds_read_b128 v[140:143], v254
	ds_read_b128 v[144:147], v254 offset:1024
	ds_read_b128 v[154:157], v254 offset:2048
	ds_read_b128 v[158:161], v254 offset:3072
	ds_read_b128 v[178:181], v255
	ds_read_b128 v[182:185], v255 offset:1024
	ds_read_b128 v[186:189], v255 offset:2048
	ds_read_b128 v[190:193], v255 offset:3072
	s_add_u32 s16, s16, 0x40000
	s_addc_u32 s17, s17, 0
	s_mov_b32 m0, s25
	ds_read_b128 v[194:197], v153 offset:32768
	ds_read_b128 v[208:211], v153 offset:33792
	ds_read_b128 v[212:215], v153 offset:34816
	ds_read_b128 v[216:219], v153 offset:35840
	ds_read_b128 v[220:223], v153 offset:36864
	ds_read_b128 v[224:227], v153 offset:37888
	ds_read_b128 v[228:231], v153 offset:38912
	ds_read_b128 v[232:235], v153 offset:39936
	global_load_lds_dwordx4 v134, s[16:17]
	s_mov_b32 m0, s26
	s_nop 0
	global_load_lds_dwordx4 v132, s[16:17]
	s_waitcnt vmcnt(8)
	s_waitcnt lgkmcnt(0)
	s_barrier
; #define PG8_STAGE(bufoff, gbase, voff) do { _Pragma("unroll") for (int _i = 0; _i < 2; ++_i) \
;         __builtin_amdgcn_global_load_lds((const unsigned*)((const char*)(gbase) + (voff)[_i]), (PG8_LAS unsigned*)(lds + (bufoff) + ldsw + _i * 8192), 16, 0, 0); } while (0)
; #define PG8_LDA(dst, b, h) do { _Pragma("unroll") for (int m = 0; m < 4; ++m) _Pragma("unroll") for (int k = 0; k < 2; ++k) dst[m][k] = *(const PG8_LAS bf16x8*)(lds + PG8_SA(b, h) + aoff + m * 2048 + k * 1024); } while (0)
; #define PG8_MMA(ai, bj, At, Bt) do { __builtin_amdgcn_s_setprio(1); _Pragma("unroll") for (int m = 0; m < 4; ++m) _Pragma("unroll") for (int n = 0; n < 2; ++n) _Pragma("unroll") for (int k = 0; k < 2; ++k) \
;         acc[ai][bj][m][n] = __builtin_amdgcn_mfma_f32_16x16x32_bf16(Bt[n][k], At[m][k], acc[ai][bj][m][n], 0, 0, 0); __builtin_amdgcn_s_setprio(0); } while (0)
; #define PG8_WAIT_V(n) asm volatile("s_waitcnt vmcnt(" #n ")" ::: "memory")
; #define PG8_WAIT_L(n) asm volatile("s_waitcnt lgkmcnt(" #n ")" ::: "memory")
; #define PG8_BAR __builtin_amdgcn_s_barrier()
; #define PG8_SCHED __builtin_amdgcn_sched_barrier(0)
; template <class Epi, class Sched, bool ALIGN_EPI = false, bool SP2 = false>
; __device__ __forceinline__ void gemm_phase(PG8_LAS unsigned char* lds, const Gemm g, const Sched& S, const Epi& E, const int wave0) {
;     ...
;         for (int t = 0; t < nt; t += 2) {
;     ...
;             PG8_WAIT_V(8); PG8_WAIT_L(0); PG8_BAR; PG8_MMA(0, 0, At, B0); PG8_MMA(0, 1, At, B1); PG8_BAR; PG8_SCHED;
;             PG8_LDA(At, 1, 1); PG8_STAGE(PG8_SB(1, 0), b3, voffB); PG8_STAGE(PG8_SB(1, 1), b3 + hstepB, voffB); PG8_STAGE(PG8_SA(1, 0), a3, voffA);
;             PG8_WAIT_V(8); PG8_WAIT_L(0); PG8_BAR; PG8_MMA(1, 0, At, B0); PG8_MMA(1, 1, At, B1); PG8_BAR; PG8_SCHED;
	s_setprio 1
	s_waitcnt lgkmcnt(0)
	v_mfma_f32_16x16x32_bf16 v[126:129], v[140:143], v[194:197], v[126:129]
	v_mfma_f32_16x16x32_bf16 v[122:125], v[154:157], v[194:197], v[122:125]
	v_mfma_f32_16x16x32_bf16 v[110:113], v[140:143], v[212:215], v[110:113]
	v_mfma_f32_16x16x32_bf16 v[106:109], v[154:157], v[212:215], v[106:109]
	v_mfma_f32_16x16x32_bf16 v[94:97], v[140:143], v[220:223], v[94:97]
	v_mfma_f32_16x16x32_bf16 v[90:93], v[154:157], v[220:223], v[90:93]
	v_mfma_f32_16x16x32_bf16 v[78:81], v[140:143], v[228:231], v[78:81]
	v_mfma_f32_16x16x32_bf16 v[74:77], v[154:157], v[228:231], v[74:77]
	v_mfma_f32_16x16x32_bf16 v[126:129], v[144:147], v[208:211], v[126:129]
	v_mfma_f32_16x16x32_bf16 v[122:125], v[158:161], v[208:211], v[122:125]
	v_mfma_f32_16x16x32_bf16 v[110:113], v[144:147], v[216:219], v[110:113]
	v_mfma_f32_16x16x32_bf16 v[106:109], v[158:161], v[216:219], v[106:109]
	v_mfma_f32_16x16x32_bf16 v[94:97], v[144:147], v[224:227], v[94:97]
	v_mfma_f32_16x16x32_bf16 v[90:93], v[158:161], v[224:227], v[90:93]
	v_mfma_f32_16x16x32_bf16 v[78:81], v[144:147], v[232:235], v[78:81]
	v_mfma_f32_16x16x32_bf16 v[74:77], v[158:161], v[232:235], v[74:77]
	s_setprio 0
	s_setprio 1
	v_mfma_f32_16x16x32_bf16 v[118:121], v[178:181], v[194:197], v[118:121]
	v_mfma_f32_16x16x32_bf16 v[114:117], v[186:189], v[194:197], v[114:117]
	v_mfma_f32_16x16x32_bf16 v[102:105], v[178:181], v[212:215], v[102:105]
	v_mfma_f32_16x16x32_bf16 v[98:101], v[186:189], v[212:215], v[98:101]
	v_mfma_f32_16x16x32_bf16 v[86:89], v[178:181], v[220:223], v[86:89]
	v_mfma_f32_16x16x32_bf16 v[82:85], v[186:189], v[220:223], v[82:85]
	v_mfma_f32_16x16x32_bf16 v[70:73], v[178:181], v[228:231], v[70:73]
	v_mfma_f32_16x16x32_bf16 v[66:69], v[186:189], v[228:231], v[66:69]
	v_mfma_f32_16x16x32_bf16 v[118:121], v[182:185], v[208:211], v[118:121]
	v_mfma_f32_16x16x32_bf16 v[114:117], v[190:193], v[208:211], v[114:117]
	v_mfma_f32_16x16x32_bf16 v[102:105], v[182:185], v[216:219], v[102:105]
	v_mfma_f32_16x16x32_bf16 v[98:101], v[190:193], v[216:219], v[98:101]
	v_mfma_f32_16x16x32_bf16 v[86:89], v[182:185], v[224:227], v[86:89]
	v_mfma_f32_16x16x32_bf16 v[82:85], v[190:193], v[224:227], v[82:85]
	v_mfma_f32_16x16x32_bf16 v[70:73], v[182:185], v[232:235], v[70:73]
	v_mfma_f32_16x16x32_bf16 v[66:69], v[190:193], v[232:235], v[66:69]
	s_setprio 0
	s_barrier
	s_add_i32 s16, s31, s22
	s_add_u32 s36, s2, 0x80
	s_addc_u32 s37, s3, 0
	s_mov_b32 m0, s16
	ds_read_b128 v[194:197], v153 offset:49152
	ds_read_b128 v[208:211], v153 offset:50176
	ds_read_b128 v[212:215], v153 offset:51200
	ds_read_b128 v[216:219], v153 offset:52224
	ds_read_b128 v[220:223], v153 offset:53248
	ds_read_b128 v[224:227], v153 offset:54272
	ds_read_b128 v[228:231], v153 offset:55296
	ds_read_b128 v[232:235], v153 offset:56320
	global_load_lds_dwordx4 v64, s[36:37]
	s_add_i32 m0, s16, 0x2000
	s_add_u32 s2, s2, 0x40080
	s_addc_u32 s3, s3, 0
	s_add_i32 s16, s33, s22
	global_load_lds_dwordx4 v130, s[36:37]
	s_mov_b32 m0, s16
	s_nop 0
	global_load_lds_dwordx4 v64, s[2:3]
	s_add_i32 m0, s16, 0x2000
	s_nop 0
	global_load_lds_dwordx4 v130, s[2:3]
	s_add_u32 s100, s100, 0x80
	s_addc_u32 s101, s101, 0
	s_mov_b32 m0, s27
	s_nop 0
	global_load_lds_dwordx4 v134, s[100:101]
	s_mov_b32 m0, s28
	s_nop 0
	global_load_lds_dwordx4 v132, s[100:101]
	s_waitcnt vmcnt(8)
	s_waitcnt lgkmcnt(0)
	s_barrier
	s_setprio 1
	s_waitcnt lgkmcnt(0)
	v_mfma_f32_16x16x32_bf16 v[60:63], v[140:143], v[194:197], v[60:63]
	v_mfma_f32_16x16x32_bf16 v[56:59], v[154:157], v[194:197], v[56:59]
	v_mfma_f32_16x16x32_bf16 v[44:47], v[140:143], v[212:215], v[44:47]
	v_mfma_f32_16x16x32_bf16 v[40:43], v[154:157], v[212:215], v[40:43]
	v_mfma_f32_16x16x32_bf16 v[28:31], v[140:143], v[220:223], v[28:31]
	v_mfma_f32_16x16x32_bf16 v[24:27], v[154:157], v[220:223], v[24:27]
	v_mfma_f32_16x16x32_bf16 v[12:15], v[140:143], v[228:231], v[12:15]
	v_mfma_f32_16x16x32_bf16 v[8:11], v[154:157], v[228:231], v[8:11]
	v_mfma_f32_16x16x32_bf16 v[60:63], v[144:147], v[208:211], v[60:63]
	v_mfma_f32_16x16x32_bf16 v[56:59], v[158:161], v[208:211], v[56:59]
	v_mfma_f32_16x16x32_bf16 v[44:47], v[144:147], v[216:219], v[44:47]
	v_mfma_f32_16x16x32_bf16 v[40:43], v[158:161], v[216:219], v[40:43]
	v_mfma_f32_16x16x32_bf16 v[28:31], v[144:147], v[224:227], v[28:31]
	v_mfma_f32_16x16x32_bf16 v[24:27], v[158:161], v[224:227], v[24:27]
	v_mfma_f32_16x16x32_bf16 v[12:15], v[144:147], v[232:235], v[12:15]
	v_mfma_f32_16x16x32_bf16 v[8:11], v[158:161], v[232:235], v[8:11]
	s_setprio 0
	s_setprio 1
	v_mfma_f32_16x16x32_bf16 v[52:55], v[178:181], v[194:197], v[52:55]
	v_mfma_f32_16x16x32_bf16 v[48:51], v[186:189], v[194:197], v[48:51]
	v_mfma_f32_16x16x32_bf16 v[36:39], v[178:181], v[212:215], v[36:39]
	v_mfma_f32_16x16x32_bf16 v[32:35], v[186:189], v[212:215], v[32:35]
	v_mfma_f32_16x16x32_bf16 v[20:23], v[178:181], v[220:223], v[20:23]
	v_mfma_f32_16x16x32_bf16 v[16:19], v[186:189], v[220:223], v[16:19]
	v_mfma_f32_16x16x32_bf16 v[4:7], v[178:181], v[228:231], v[4:7]
	v_mfma_f32_16x16x32_bf16 v[0:3], v[186:189], v[228:231], v[0:3]
	v_mfma_f32_16x16x32_bf16 v[52:55], v[182:185], v[208:211], v[52:55]
	v_mfma_f32_16x16x32_bf16 v[48:51], v[190:193], v[208:211], v[48:51]
	v_mfma_f32_16x16x32_bf16 v[36:39], v[182:185], v[216:219], v[36:39]
	v_mfma_f32_16x16x32_bf16 v[32:35], v[190:193], v[216:219], v[32:35]
	v_mfma_f32_16x16x32_bf16 v[20:23], v[182:185], v[224:227], v[20:23]
	v_mfma_f32_16x16x32_bf16 v[16:19], v[190:193], v[224:227], v[16:19]
	v_mfma_f32_16x16x32_bf16 v[4:7], v[182:185], v[232:235], v[4:7]
	v_mfma_f32_16x16x32_bf16 v[0:3], v[190:193], v[232:235], v[0:3]
	s_setprio 0
	s_barrier
	s_add_i32 s19, s19, 2
	s_add_u32 s0, s0, 0x100
	s_addc_u32 s1, s1, 0
	s_add_u32 s13, s13, 0x100
	s_addc_u32 s18, s18, 0
	s_cmp_gt_u32 s19, 13
	s_cbranch_scc0 .LBB0_1231
	s_mov_b64 s[36:37], 0x80
	s_and_b64 vcc, exec, s[6:7]
	s_cbranch_vccz .LBB0_1234
	s_barrier

; #define PG8_STAGE(bufoff, gbase, voff) do { _Pragma("unroll") for (int _i = 0; _i < 2; ++_i) \
;         __builtin_amdgcn_global_load_lds((const unsigned*)((const char*)(gbase) + (voff)[_i]), (PG8_LAS unsigned*)(lds + (bufoff) + ldsw + _i * 8192), 16, 0, 0); } while (0)
; #define PG8_LDA(dst, b, h) do { _Pragma("unroll") for (int m = 0; m < 4; ++m) _Pragma("unroll") for (int k = 0; k < 2; ++k) dst[m][k] = *(const PG8_LAS bf16x8*)(lds + PG8_SA(b, h) + aoff + m * 2048 + k * 1024); } while (0)
; #define PG8_LDB(dst, b, h) do { _Pragma("unroll") for (int n = 0; n < 2; ++n) _Pragma("unroll") for (int k = 0; k < 2; ++k) dst[n][k] = *(const PG8_LAS bf16x8*)(lds + PG8_SB(b, h) + boff + n * 2048 + k * 1024); } while (0)
; #define PG8_MMA(ai, bj, At, Bt) do { __builtin_amdgcn_s_setprio(1); _Pragma("unroll") for (int m = 0; m < 4; ++m) _Pragma("unroll") for (int n = 0; n < 2; ++n) _Pragma("unroll") for (int k = 0; k < 2; ++k) \
;         acc[ai][bj][m][n] = __builtin_amdgcn_mfma_f32_16x16x32_bf16(Bt[n][k], At[m][k], acc[ai][bj][m][n], 0, 0, 0); __builtin_amdgcn_s_setprio(0); } while (0)
; #define PG8_WAIT_V(n) asm volatile("s_waitcnt vmcnt(" #n ")" ::: "memory")
; #define PG8_WAIT_L(n) asm volatile("s_waitcnt lgkmcnt(" #n ")" ::: "memory")
; #define PG8_BAR __builtin_amdgcn_s_barrier()
; #define PG8_SCHED __builtin_amdgcn_sched_barrier(0)
; template <class Epi, class Sched, bool ALIGN_EPI = false, bool SP2 = false>
; __device__ __forceinline__ void gemm_phase(PG8_LAS unsigned char* lds, const Gemm g, const Sched& S, const Epi& E, const int wave0) {
;     ...
;             if constexpr (SP2) {
;             PG8_LDB(B0, 0, 0); PG8_LDB(B1, 0, 1); PG8_SCHED; PG8_LDA(At, 0, 0); PG8_STAGE(PG8_SA(1, 1), a1 + hstepA, voffA);
;             PG8_WAIT_V(8); PG8_WAIT_L(0); PG8_BAR; PG8_MMA(0, 0, At, B0); PG8_MMA(0, 1, At, B1); PG8_BAR; PG8_SCHED;
;     ...
;         for (int a = 0; a < 2; ++a)
; #pragma unroll
;             for (int b = 0; b < 2; ++b)
; #pragma unroll
;                 for (int m = 0; m < 4; ++m)
; #pragma unroll
;                     for (int n = 0; n < 2; ++n) acc[a][b][m][n] = (f32x4){0.f, 0.f, 0.f, 0.f};
.LBB0_1340:
	s_ashr_i32 s11, s10, 31
	s_lshl_b64 s[12:13], s[10:11], 20
	v_readlane_b32 s14, v246, 33
	v_readlane_b32 s15, v246, 34
	s_add_u32 s12, s14, s12
	s_addc_u32 s13, s15, s13
	s_and_b64 s[14:15], s[2:3], exec
	s_cselect_b32 s11, s13, s1
	s_cselect_b32 s33, s12, s0
	s_ashr_i32 s9, s8, 31
	s_lshl_b64 s[14:15], s[8:9], 20
	s_add_u32 s14, s20, s14
	s_addc_u32 s15, s21, s15
	s_and_b64 s[18:19], s[2:3], exec
	s_cselect_b32 s9, s15, s17
	s_cselect_b32 s34, s14, s16
	s_add_u32 s0, s0, 0x80080
	s_addc_u32 s1, s1, 0
	s_add_u32 s35, s16, 0x100
	v_mov_b32_e32 v0, 0
	s_addc_u32 s36, s17, 0
	s_mov_b32 s37, -2
	v_mov_b32_e32 v1, v0
	v_mov_b64_e32 v[2:3], 0
	v_mov_b64_e32 v[4:5], 0
	v_mov_b64_e32 v[6:7], 0
	v_mov_b64_e32 v[8:9], 0
	v_mov_b64_e32 v[10:11], 0
	v_mov_b64_e32 v[12:13], 0
	v_mov_b64_e32 v[14:15], 0
	v_mov_b64_e32 v[24:25], 0
	v_mov_b64_e32 v[26:27], 0
	v_mov_b64_e32 v[28:29], 0
	v_mov_b64_e32 v[30:31], 0
	v_mov_b64_e32 v[40:41], 0
	v_mov_b64_e32 v[42:43], 0
	v_mov_b64_e32 v[44:45], 0
	v_mov_b64_e32 v[46:47], 0
	v_mov_b64_e32 v[16:17], 0
	v_mov_b64_e32 v[18:19], 0
	v_mov_b64_e32 v[20:21], 0
	v_mov_b64_e32 v[22:23], 0
	v_mov_b64_e32 v[32:33], 0
	v_mov_b64_e32 v[34:35], 0
	v_mov_b64_e32 v[36:37], 0
	v_mov_b64_e32 v[38:39], 0
	v_mov_b64_e32 v[48:49], 0
	v_mov_b64_e32 v[50:51], 0
	v_mov_b64_e32 v[52:53], 0
	v_mov_b64_e32 v[54:55], 0
	v_mov_b64_e32 v[56:57], 0
	v_mov_b64_e32 v[58:59], 0
	v_mov_b64_e32 v[60:61], 0
	v_mov_b64_e32 v[62:63], 0
	v_mov_b64_e32 v[66:67], 0
	v_mov_b64_e32 v[68:69], 0
	v_mov_b64_e32 v[70:71], 0
	v_mov_b64_e32 v[72:73], 0
	v_mov_b64_e32 v[74:75], 0
	v_mov_b64_e32 v[76:77], 0
	v_mov_b64_e32 v[78:79], 0
	v_mov_b64_e32 v[80:81], 0
	v_mov_b64_e32 v[90:91], 0
	v_mov_b64_e32 v[92:93], 0
	v_mov_b64_e32 v[94:95], 0
	v_mov_b64_e32 v[96:97], 0
	v_mov_b64_e32 v[106:107], 0
	v_mov_b64_e32 v[108:109], 0
	v_mov_b64_e32 v[110:111], 0
	v_mov_b64_e32 v[112:113], 0
	v_mov_b64_e32 v[82:83], 0
	v_mov_b64_e32 v[84:85], 0
	v_mov_b64_e32 v[86:87], 0
	v_mov_b64_e32 v[88:89], 0
	v_mov_b64_e32 v[98:99], 0
	v_mov_b64_e32 v[100:101], 0
	v_mov_b64_e32 v[102:103], 0
	v_mov_b64_e32 v[104:105], 0
	v_mov_b64_e32 v[114:115], 0
	v_mov_b64_e32 v[116:117], 0
	v_mov_b64_e32 v[118:119], 0
	v_mov_b64_e32 v[120:121], 0
	v_mov_b64_e32 v[122:123], 0
	v_mov_b64_e32 v[124:125], 0
	v_mov_b64_e32 v[126:127], 0
	v_mov_b64_e32 v[128:129], 0
	s_mov_b64 s[44:45], 0x80
	v_add_u32_e32 v252, 0x10000, v141
	v_add_u32_e32 v253, 0x14000, v141
	v_add_u32_e32 v254, 0x18000, v141
	v_add_u32_e32 v255, 0x1c000, v141
.LBB0_1341:
	s_add_u32 s16, s0, 0xfff80080
	s_addc_u32 s17, s1, -1
	s_add_i32 s40, 0, 0x10000
	s_cmp_eq_u32 s37, 28
	s_cselect_b32 s19, s11, s17
	s_cselect_b32 s18, s33, s16
	s_cselect_b32 s17, s9, s36
	s_cselect_b32 s16, s34, s35
	s_add_i32 s42, 0, 0x14000
	ds_read_b128 v[144:147], v252
	ds_read_b128 v[148:151], v252 offset:1024
	ds_read_b128 v[152:155], v252 offset:2048
	ds_read_b128 v[156:159], v252 offset:3072
	ds_read_b128 v[178:181], v253
	ds_read_b128 v[182:185], v253 offset:1024
	ds_read_b128 v[186:189], v253 offset:2048
	ds_read_b128 v[190:193], v253 offset:3072
	s_add_i32 m0, s23, 0xc000
	ds_read_b128 v[194:197], v143
	ds_read_b128 v[208:211], v143 offset:1024
	ds_read_b128 v[212:215], v143 offset:2048
	ds_read_b128 v[216:219], v143 offset:3072
	ds_read_b128 v[220:223], v143 offset:4096
	ds_read_b128 v[224:227], v143 offset:5120
	ds_read_b128 v[228:231], v143 offset:6144
	ds_read_b128 v[232:235], v143 offset:7168
	global_load_lds_dwordx4 v136, s[0:1]
	s_add_i32 m0, s23, 0xe000
	s_nop 0
	global_load_lds_dwordx4 v138, s[0:1]
	s_waitcnt vmcnt(8)
	s_waitcnt lgkmcnt(0)
	s_barrier
	s_setprio 1
	s_waitcnt lgkmcnt(0)
	v_mfma_f32_16x16x32_bf16 v[126:129], v[144:147], v[194:197], v[126:129]
	v_mfma_f32_16x16x32_bf16 v[122:125], v[152:155], v[194:197], v[122:125]
	v_mfma_f32_16x16x32_bf16 v[118:121], v[144:147], v[212:215], v[118:121]
	v_mfma_f32_16x16x32_bf16 v[114:117], v[152:155], v[212:215], v[114:117]
	v_mfma_f32_16x16x32_bf16 v[102:105], v[144:147], v[220:223], v[102:105]
	v_mfma_f32_16x16x32_bf16 v[98:101], v[152:155], v[220:223], v[98:101]
	v_mfma_f32_16x16x32_bf16 v[86:89], v[144:147], v[228:231], v[86:89]
	v_mfma_f32_16x16x32_bf16 v[82:85], v[152:155], v[228:231], v[82:85]
	v_mfma_f32_16x16x32_bf16 v[126:129], v[148:151], v[208:211], v[126:129]
	v_mfma_f32_16x16x32_bf16 v[122:125], v[156:159], v[208:211], v[122:125]
	v_mfma_f32_16x16x32_bf16 v[118:121], v[148:151], v[216:219], v[118:121]
	v_mfma_f32_16x16x32_bf16 v[114:117], v[156:159], v[216:219], v[114:117]
	v_mfma_f32_16x16x32_bf16 v[102:105], v[148:151], v[224:227], v[102:105]
	v_mfma_f32_16x16x32_bf16 v[98:101], v[156:159], v[224:227], v[98:101]
	v_mfma_f32_16x16x32_bf16 v[86:89], v[148:151], v[232:235], v[86:89]
	v_mfma_f32_16x16x32_bf16 v[82:85], v[156:159], v[232:235], v[82:85]
	s_setprio 0
	s_setprio 1
	v_mfma_f32_16x16x32_bf16 v[110:113], v[178:181], v[194:197], v[110:113]
	v_mfma_f32_16x16x32_bf16 v[106:109], v[186:189], v[194:197], v[106:109]
	v_mfma_f32_16x16x32_bf16 v[94:97], v[178:181], v[212:215], v[94:97]
	v_mfma_f32_16x16x32_bf16 v[90:93], v[186:189], v[212:215], v[90:93]
	v_mfma_f32_16x16x32_bf16 v[78:81], v[178:181], v[220:223], v[78:81]
	v_mfma_f32_16x16x32_bf16 v[74:77], v[186:189], v[220:223], v[74:77]
	v_mfma_f32_16x16x32_bf16 v[70:73], v[178:181], v[228:231], v[70:73]
	v_mfma_f32_16x16x32_bf16 v[66:69], v[186:189], v[228:231], v[66:69]
	v_mfma_f32_16x16x32_bf16 v[110:113], v[182:185], v[208:211], v[110:113]
	v_mfma_f32_16x16x32_bf16 v[106:109], v[190:193], v[208:211], v[106:109]
	v_mfma_f32_16x16x32_bf16 v[94:97], v[182:185], v[216:219], v[94:97]
	v_mfma_f32_16x16x32_bf16 v[90:93], v[190:193], v[216:219], v[90:93]
	v_mfma_f32_16x16x32_bf16 v[78:81], v[182:185], v[224:227], v[78:81]
	v_mfma_f32_16x16x32_bf16 v[74:77], v[190:193], v[224:227], v[74:77]
	v_mfma_f32_16x16x32_bf16 v[70:73], v[182:185], v[232:235], v[70:73]
	v_mfma_f32_16x16x32_bf16 v[66:69], v[190:193], v[232:235], v[66:69]
	s_setprio 0
	s_barrier
; #define PG8_STAGE(bufoff, gbase, voff) do { _Pragma("unroll") for (int _i = 0; _i < 2; ++_i) \
;         __builtin_amdgcn_global_load_lds((const unsigned*)((const char*)(gbase) + (voff)[_i]), (PG8_LAS unsigned*)(lds + (bufoff) + ldsw + _i * 8192), 16, 0, 0); } while (0)
; #define PG8_LDA(dst, b, h) do { _Pragma("unroll") for (int m = 0; m < 4; ++m) _Pragma("unroll") for (int k = 0; k < 2; ++k) dst[m][k] = *(const PG8_LAS bf16x8*)(lds + PG8_SA(b, h) + aoff + m * 2048 + k * 1024); } while (0)
; #define PG8_LDB(dst, b, h) do { _Pragma("unroll") for (int n = 0; n < 2; ++n) _Pragma("unroll") for (int k = 0; k < 2; ++k) dst[n][k] = *(const PG8_LAS bf16x8*)(lds + PG8_SB(b, h) + boff + n * 2048 + k * 1024); } while (0)
; #define PG8_MMA(ai, bj, At, Bt) do { __builtin_amdgcn_s_setprio(1); _Pragma("unroll") for (int m = 0; m < 4; ++m) _Pragma("unroll") for (int n = 0; n < 2; ++n) _Pragma("unroll") for (int k = 0; k < 2; ++k) \
;         acc[ai][bj][m][n] = __builtin_amdgcn_mfma_f32_16x16x32_bf16(Bt[n][k], At[m][k], acc[ai][bj][m][n], 0, 0, 0); __builtin_amdgcn_s_setprio(0); } while (0)
; #define PG8_WAIT_V(n) asm volatile("s_waitcnt vmcnt(" #n ")" ::: "memory")
; #define PG8_WAIT_L(n) asm volatile("s_waitcnt lgkmcnt(" #n ")" ::: "memory")
; #define PG8_BAR __builtin_amdgcn_s_barrier()
; #define PG8_SCHED __builtin_amdgcn_sched_barrier(0)
; template <class Epi, class Sched, bool ALIGN_EPI = false, bool SP2 = false>
; __device__ __forceinline__ void gemm_phase(PG8_LAS unsigned char* lds, const Gemm g, const Sched& S, const Epi& E, const int wave0) {
;     ...
;             PG8_WAIT_V(8); PG8_WAIT_L(0); PG8_BAR; PG8_MMA(0, 0, At, B0); PG8_MMA(0, 1, At, B1); PG8_BAR; PG8_SCHED;
;             PG8_LDA(At, 0, 1); PG8_STAGE(PG8_SB(0, 0), b2, voffB); PG8_STAGE(PG8_SB(0, 1), b2 + hstepB, voffB); PG8_STAGE(PG8_SA(0, 0), a2, voffA);
;             PG8_WAIT_V(8); PG8_WAIT_L(0); PG8_BAR; PG8_MMA(1, 0, At, B0); PG8_MMA(1, 1, At, B1); PG8_BAR; PG8_SCHED;
;             PG8_LDB(B0, 1, 0); PG8_LDB(B1, 1, 1); PG8_SCHED; PG8_LDA(At, 1, 0); PG8_STAGE(PG8_SA(0, 1), a2 + hstepA, voffA);
	s_add_i32 s40, s40, s22
	s_mov_b32 m0, s40
	ds_read_b128 v[194:197], v143 offset:16384
	ds_read_b128 v[208:211], v143 offset:17408
	ds_read_b128 v[212:215], v143 offset:18432
	ds_read_b128 v[216:219], v143 offset:19456
	ds_read_b128 v[220:223], v143 offset:20480
	ds_read_b128 v[224:227], v143 offset:21504
	ds_read_b128 v[228:231], v143 offset:22528
	ds_read_b128 v[232:235], v143 offset:23552
	global_load_lds_dwordx4 v64, s[16:17]
	s_add_i32 m0, s40, 0x2000
	s_add_u32 s40, s16, 0x80000
	s_addc_u32 s41, s17, 0
	s_add_i32 s42, s42, s22
	global_load_lds_dwordx4 v130, s[16:17]
	s_mov_b32 m0, s42
	s_mov_b64 s[100:101], s[18:19]
	global_load_lds_dwordx4 v64, s[40:41]
	s_add_i32 m0, s42, 0x2000
	s_nop 0
	global_load_lds_dwordx4 v130, s[40:41]
	s_mov_b32 m0, s23
	s_nop 0
	global_load_lds_dwordx4 v134, s[18:19]
	s_mov_b32 m0, s24
	s_nop 0
	global_load_lds_dwordx4 v132, s[18:19]
	s_waitcnt vmcnt(8)
	s_waitcnt lgkmcnt(0)
	s_barrier
	s_setprio 1
	s_waitcnt lgkmcnt(0)
	v_mfma_f32_16x16x32_bf16 v[60:63], v[144:147], v[194:197], v[60:63]
	v_mfma_f32_16x16x32_bf16 v[56:59], v[152:155], v[194:197], v[56:59]
	v_mfma_f32_16x16x32_bf16 v[52:55], v[144:147], v[212:215], v[52:55]
	v_mfma_f32_16x16x32_bf16 v[48:51], v[152:155], v[212:215], v[48:51]
	v_mfma_f32_16x16x32_bf16 v[36:39], v[144:147], v[220:223], v[36:39]
	v_mfma_f32_16x16x32_bf16 v[32:35], v[152:155], v[220:223], v[32:35]
	v_mfma_f32_16x16x32_bf16 v[20:23], v[144:147], v[228:231], v[20:23]
	v_mfma_f32_16x16x32_bf16 v[16:19], v[152:155], v[228:231], v[16:19]
	v_mfma_f32_16x16x32_bf16 v[60:63], v[148:151], v[208:211], v[60:63]
	v_mfma_f32_16x16x32_bf16 v[56:59], v[156:159], v[208:211], v[56:59]
	v_mfma_f32_16x16x32_bf16 v[52:55], v[148:151], v[216:219], v[52:55]
	v_mfma_f32_16x16x32_bf16 v[48:51], v[156:159], v[216:219], v[48:51]
	v_mfma_f32_16x16x32_bf16 v[36:39], v[148:151], v[224:227], v[36:39]
	v_mfma_f32_16x16x32_bf16 v[32:35], v[156:159], v[224:227], v[32:35]
	v_mfma_f32_16x16x32_bf16 v[20:23], v[148:151], v[232:235], v[20:23]
	v_mfma_f32_16x16x32_bf16 v[16:19], v[156:159], v[232:235], v[16:19]
	s_setprio 0
	s_setprio 1
	v_mfma_f32_16x16x32_bf16 v[44:47], v[178:181], v[194:197], v[44:47]
	v_mfma_f32_16x16x32_bf16 v[40:43], v[186:189], v[194:197], v[40:43]
	v_mfma_f32_16x16x32_bf16 v[28:31], v[178:181], v[212:215], v[28:31]
	v_mfma_f32_16x16x32_bf16 v[24:27], v[186:189], v[212:215], v[24:27]
	v_mfma_f32_16x16x32_bf16 v[12:15], v[178:181], v[220:223], v[12:15]
	v_mfma_f32_16x16x32_bf16 v[8:11], v[186:189], v[220:223], v[8:11]
	v_mfma_f32_16x16x32_bf16 v[4:7], v[178:181], v[228:231], v[4:7]
	v_mfma_f32_16x16x32_bf16 v[0:3], v[186:189], v[228:231], v[0:3]
	v_mfma_f32_16x16x32_bf16 v[44:47], v[182:185], v[208:211], v[44:47]
	v_mfma_f32_16x16x32_bf16 v[40:43], v[190:193], v[208:211], v[40:43]
	v_mfma_f32_16x16x32_bf16 v[28:31], v[182:185], v[216:219], v[28:31]
	v_mfma_f32_16x16x32_bf16 v[24:27], v[190:193], v[216:219], v[24:27]
	v_mfma_f32_16x16x32_bf16 v[12:15], v[182:185], v[224:227], v[12:15]
	v_mfma_f32_16x16x32_bf16 v[8:11], v[190:193], v[224:227], v[8:11]
	v_mfma_f32_16x16x32_bf16 v[4:7], v[182:185], v[232:235], v[4:7]
	v_mfma_f32_16x16x32_bf16 v[0:3], v[190:193], v[232:235], v[0:3]
	s_setprio 0
	s_barrier
	s_add_i32 s40, 0, 0x18000
	s_add_i32 s41, 0, 0x1c000
	ds_read_b128 v[144:147], v254
	ds_read_b128 v[148:151], v254 offset:1024
	ds_read_b128 v[152:155], v254 offset:2048
	ds_read_b128 v[156:159], v254 offset:3072
	ds_read_b128 v[178:181], v255
	ds_read_b128 v[182:185], v255 offset:1024
	ds_read_b128 v[186:189], v255 offset:2048
	ds_read_b128 v[190:193], v255 offset:3072
	s_add_u32 s18, s18, 0x80000
	s_addc_u32 s19, s19, 0
	s_mov_b32 m0, s25
	ds_read_b128 v[194:197], v143 offset:32768
	ds_read_b128 v[208:211], v143 offset:33792
	ds_read_b128 v[212:215], v143 offset:34816
	ds_read_b128 v[216:219], v143 offset:35840
	ds_read_b128 v[220:223], v143 offset:36864
	ds_read_b128 v[224:227], v143 offset:37888
	ds_read_b128 v[228:231], v143 offset:38912
	ds_read_b128 v[232:235], v143 offset:39936
	global_load_lds_dwordx4 v134, s[18:19]
	s_mov_b32 m0, s26
	s_nop 0
	global_load_lds_dwordx4 v132, s[18:19]
	s_waitcnt vmcnt(8)
	s_waitcnt lgkmcnt(0)
	s_barrier
; #define PG8_STAGE(bufoff, gbase, voff) do { _Pragma("unroll") for (int _i = 0; _i < 2; ++_i) \
;         __builtin_amdgcn_global_load_lds((const unsigned*)((const char*)(gbase) + (voff)[_i]), (PG8_LAS unsigned*)(lds + (bufoff) + ldsw + _i * 8192), 16, 0, 0); } while (0)
; #define PG8_LDA(dst, b, h) do { _Pragma("unroll") for (int m = 0; m < 4; ++m) _Pragma("unroll") for (int k = 0; k < 2; ++k) dst[m][k] = *(const PG8_LAS bf16x8*)(lds + PG8_SA(b, h) + aoff + m * 2048 + k * 1024); } while (0)
; #define PG8_MMA(ai, bj, At, Bt) do { __builtin_amdgcn_s_setprio(1); _Pragma("unroll") for (int m = 0; m < 4; ++m) _Pragma("unroll") for (int n = 0; n < 2; ++n) _Pragma("unroll") for (int k = 0; k < 2; ++k) \
;         acc[ai][bj][m][n] = __builtin_amdgcn_mfma_f32_16x16x32_bf16(Bt[n][k], At[m][k], acc[ai][bj][m][n], 0, 0, 0); __builtin_amdgcn_s_setprio(0); } while (0)
; #define PG8_WAIT_V(n) asm volatile("s_waitcnt vmcnt(" #n ")" ::: "memory")
; #define PG8_WAIT_L(n) asm volatile("s_waitcnt lgkmcnt(" #n ")" ::: "memory")
; #define PG8_BAR __builtin_amdgcn_s_barrier()
; #define PG8_SCHED __builtin_amdgcn_sched_barrier(0)
; template <class Epi, class Sched, bool ALIGN_EPI = false, bool SP2 = false>
; __device__ __forceinline__ void gemm_phase(PG8_LAS unsigned char* lds, const Gemm g, const Sched& S, const Epi& E, const int wave0) {
;     ...
;         for (int t = 0; t < nt; t += 2) {
;     ...
;             PG8_WAIT_V(8); PG8_WAIT_L(0); PG8_BAR; PG8_MMA(0, 0, At, B0); PG8_MMA(0, 1, At, B1); PG8_BAR; PG8_SCHED;
;             PG8_LDA(At, 1, 1); PG8_STAGE(PG8_SB(1, 0), b3, voffB); PG8_STAGE(PG8_SB(1, 1), b3 + hstepB, voffB); PG8_STAGE(PG8_SA(1, 0), a3, voffA);
;             PG8_WAIT_V(8); PG8_WAIT_L(0); PG8_BAR; PG8_MMA(1, 0, At, B0); PG8_MMA(1, 1, At, B1); PG8_BAR; PG8_SCHED;
	s_setprio 1
	s_waitcnt lgkmcnt(0)
	v_mfma_f32_16x16x32_bf16 v[126:129], v[144:147], v[194:197], v[126:129]
	v_mfma_f32_16x16x32_bf16 v[122:125], v[152:155], v[194:197], v[122:125]
	v_mfma_f32_16x16x32_bf16 v[118:121], v[144:147], v[212:215], v[118:121]
	v_mfma_f32_16x16x32_bf16 v[114:117], v[152:155], v[212:215], v[114:117]
	v_mfma_f32_16x16x32_bf16 v[102:105], v[144:147], v[220:223], v[102:105]
	v_mfma_f32_16x16x32_bf16 v[98:101], v[152:155], v[220:223], v[98:101]
	v_mfma_f32_16x16x32_bf16 v[86:89], v[144:147], v[228:231], v[86:89]
	v_mfma_f32_16x16x32_bf16 v[82:85], v[152:155], v[228:231], v[82:85]
	v_mfma_f32_16x16x32_bf16 v[126:129], v[148:151], v[208:211], v[126:129]
	v_mfma_f32_16x16x32_bf16 v[122:125], v[156:159], v[208:211], v[122:125]
	v_mfma_f32_16x16x32_bf16 v[118:121], v[148:151], v[216:219], v[118:121]
	v_mfma_f32_16x16x32_bf16 v[114:117], v[156:159], v[216:219], v[114:117]
	v_mfma_f32_16x16x32_bf16 v[102:105], v[148:151], v[224:227], v[102:105]
	v_mfma_f32_16x16x32_bf16 v[98:101], v[156:159], v[224:227], v[98:101]
	v_mfma_f32_16x16x32_bf16 v[86:89], v[148:151], v[232:235], v[86:89]
	v_mfma_f32_16x16x32_bf16 v[82:85], v[156:159], v[232:235], v[82:85]
	s_setprio 0
	s_setprio 1
	v_mfma_f32_16x16x32_bf16 v[110:113], v[178:181], v[194:197], v[110:113]
	v_mfma_f32_16x16x32_bf16 v[106:109], v[186:189], v[194:197], v[106:109]
	v_mfma_f32_16x16x32_bf16 v[94:97], v[178:181], v[212:215], v[94:97]
	v_mfma_f32_16x16x32_bf16 v[90:93], v[186:189], v[212:215], v[90:93]
	v_mfma_f32_16x16x32_bf16 v[78:81], v[178:181], v[220:223], v[78:81]
	v_mfma_f32_16x16x32_bf16 v[74:77], v[186:189], v[220:223], v[74:77]
	v_mfma_f32_16x16x32_bf16 v[70:73], v[178:181], v[228:231], v[70:73]
	v_mfma_f32_16x16x32_bf16 v[66:69], v[186:189], v[228:231], v[66:69]
	v_mfma_f32_16x16x32_bf16 v[110:113], v[182:185], v[208:211], v[110:113]
	v_mfma_f32_16x16x32_bf16 v[106:109], v[190:193], v[208:211], v[106:109]
	v_mfma_f32_16x16x32_bf16 v[94:97], v[182:185], v[216:219], v[94:97]
	v_mfma_f32_16x16x32_bf16 v[90:93], v[190:193], v[216:219], v[90:93]
	v_mfma_f32_16x16x32_bf16 v[78:81], v[182:185], v[224:227], v[78:81]
	v_mfma_f32_16x16x32_bf16 v[74:77], v[190:193], v[224:227], v[74:77]
	v_mfma_f32_16x16x32_bf16 v[70:73], v[182:185], v[232:235], v[70:73]
	v_mfma_f32_16x16x32_bf16 v[66:69], v[190:193], v[232:235], v[66:69]
	s_setprio 0
	s_barrier
	s_add_i32 s18, s40, s22
	s_add_u32 s44, s16, 0x80
	s_addc_u32 s45, s17, 0
	s_mov_b32 m0, s18
	ds_read_b128 v[194:197], v143 offset:49152
	ds_read_b128 v[208:211], v143 offset:50176
	ds_read_b128 v[212:215], v143 offset:51200
	ds_read_b128 v[216:219], v143 offset:52224
	ds_read_b128 v[220:223], v143 offset:53248
	ds_read_b128 v[224:227], v143 offset:54272
	ds_read_b128 v[228:231], v143 offset:55296
	ds_read_b128 v[232:235], v143 offset:56320
	global_load_lds_dwordx4 v64, s[44:45]
	s_add_i32 m0, s18, 0x2000
	s_add_u32 s16, s16, 0x80080
	s_addc_u32 s17, s17, 0
	s_add_i32 s18, s41, s22
	global_load_lds_dwordx4 v130, s[44:45]
	s_mov_b32 m0, s18
	s_nop 0
	global_load_lds_dwordx4 v64, s[16:17]
	s_add_i32 m0, s18, 0x2000
	s_nop 0
	global_load_lds_dwordx4 v130, s[16:17]
	s_add_u32 s100, s100, 0x80
	s_addc_u32 s101, s101, 0
	s_mov_b32 m0, s27
	s_nop 0
	global_load_lds_dwordx4 v134, s[100:101]
	s_mov_b32 m0, s28
	s_nop 0
	global_load_lds_dwordx4 v132, s[100:101]
	s_waitcnt vmcnt(8)
	s_waitcnt lgkmcnt(0)
	s_barrier
	s_setprio 1
	s_waitcnt lgkmcnt(0)
	v_mfma_f32_16x16x32_bf16 v[60:63], v[144:147], v[194:197], v[60:63]
	v_mfma_f32_16x16x32_bf16 v[56:59], v[152:155], v[194:197], v[56:59]
	v_mfma_f32_16x16x32_bf16 v[52:55], v[144:147], v[212:215], v[52:55]
	v_mfma_f32_16x16x32_bf16 v[48:51], v[152:155], v[212:215], v[48:51]
	v_mfma_f32_16x16x32_bf16 v[36:39], v[144:147], v[220:223], v[36:39]
	v_mfma_f32_16x16x32_bf16 v[32:35], v[152:155], v[220:223], v[32:35]
	v_mfma_f32_16x16x32_bf16 v[20:23], v[144:147], v[228:231], v[20:23]
	v_mfma_f32_16x16x32_bf16 v[16:19], v[152:155], v[228:231], v[16:19]
	v_mfma_f32_16x16x32_bf16 v[60:63], v[148:151], v[208:211], v[60:63]
	v_mfma_f32_16x16x32_bf16 v[56:59], v[156:159], v[208:211], v[56:59]
	v_mfma_f32_16x16x32_bf16 v[52:55], v[148:151], v[216:219], v[52:55]
	v_mfma_f32_16x16x32_bf16 v[48:51], v[156:159], v[216:219], v[48:51]
	v_mfma_f32_16x16x32_bf16 v[36:39], v[148:151], v[224:227], v[36:39]
	v_mfma_f32_16x16x32_bf16 v[32:35], v[156:159], v[224:227], v[32:35]
	v_mfma_f32_16x16x32_bf16 v[20:23], v[148:151], v[232:235], v[20:23]
	v_mfma_f32_16x16x32_bf16 v[16:19], v[156:159], v[232:235], v[16:19]
	s_setprio 0
	s_setprio 1
	v_mfma_f32_16x16x32_bf16 v[44:47], v[178:181], v[194:197], v[44:47]
	v_mfma_f32_16x16x32_bf16 v[40:43], v[186:189], v[194:197], v[40:43]
	v_mfma_f32_16x16x32_bf16 v[28:31], v[178:181], v[212:215], v[28:31]
	v_mfma_f32_16x16x32_bf16 v[24:27], v[186:189], v[212:215], v[24:27]
	v_mfma_f32_16x16x32_bf16 v[12:15], v[178:181], v[220:223], v[12:15]
	v_mfma_f32_16x16x32_bf16 v[8:11], v[186:189], v[220:223], v[8:11]
	v_mfma_f32_16x16x32_bf16 v[4:7], v[178:181], v[228:231], v[4:7]
	v_mfma_f32_16x16x32_bf16 v[0:3], v[186:189], v[228:231], v[0:3]
	v_mfma_f32_16x16x32_bf16 v[44:47], v[182:185], v[208:211], v[44:47]
	v_mfma_f32_16x16x32_bf16 v[40:43], v[190:193], v[208:211], v[40:43]
	v_mfma_f32_16x16x32_bf16 v[28:31], v[182:185], v[216:219], v[28:31]
	v_mfma_f32_16x16x32_bf16 v[24:27], v[190:193], v[216:219], v[24:27]
	v_mfma_f32_16x16x32_bf16 v[12:15], v[182:185], v[224:227], v[12:15]
	v_mfma_f32_16x16x32_bf16 v[8:11], v[190:193], v[224:227], v[8:11]
	v_mfma_f32_16x16x32_bf16 v[4:7], v[182:185], v[232:235], v[4:7]
	v_mfma_f32_16x16x32_bf16 v[0:3], v[190:193], v[232:235], v[0:3]
	s_setprio 0
	s_barrier
	s_add_i32 s37, s37, 2
	s_add_u32 s0, s0, 0x100
	s_addc_u32 s1, s1, 0
	s_add_u32 s35, s35, 0x100
	s_addc_u32 s36, s36, 0
	s_cmp_gt_u32 s37, 29
	s_cbranch_scc0 .LBB0_1341
	s_mov_b64 s[44:45], 0x80
	s_and_b64 vcc, exec, s[6:7]
	s_mov_b64 s[34:35], 0x45000
	s_cbranch_vccz .LBB0_1344
	s_barrier

; #define PG8_STAGE(bufoff, gbase, voff) do { _Pragma("unroll") for (int _i = 0; _i < 2; ++_i) \
;         __builtin_amdgcn_global_load_lds((const unsigned*)((const char*)(gbase) + (voff)[_i]), (PG8_LAS unsigned*)(lds + (bufoff) + ldsw + _i * 8192), 16, 0, 0); } while (0)
; #define PG8_LDA(dst, b, h) do { _Pragma("unroll") for (int m = 0; m < 4; ++m) _Pragma("unroll") for (int k = 0; k < 2; ++k) dst[m][k] = *(const PG8_LAS bf16x8*)(lds + PG8_SA(b, h) + aoff + m * 2048 + k * 1024); } while (0)
; #define PG8_LDB(dst, b, h) do { _Pragma("unroll") for (int n = 0; n < 2; ++n) _Pragma("unroll") for (int k = 0; k < 2; ++k) dst[n][k] = *(const PG8_LAS bf16x8*)(lds + PG8_SB(b, h) + boff + n * 2048 + k * 1024); } while (0)
; #define PG8_MMA(ai, bj, At, Bt) do { __builtin_amdgcn_s_setprio(1); _Pragma("unroll") for (int m = 0; m < 4; ++m) _Pragma("unroll") for (int n = 0; n < 2; ++n) _Pragma("unroll") for (int k = 0; k < 2; ++k) \
;         acc[ai][bj][m][n] = __builtin_amdgcn_mfma_f32_16x16x32_bf16(Bt[n][k], At[m][k], acc[ai][bj][m][n], 0, 0, 0); __builtin_amdgcn_s_setprio(0); } while (0)
; #define PG8_WAIT_V(n) asm volatile("s_waitcnt vmcnt(" #n ")" ::: "memory")
; #define PG8_WAIT_L(n) asm volatile("s_waitcnt lgkmcnt(" #n ")" ::: "memory")
; #define PG8_BAR __builtin_amdgcn_s_barrier()
; #define PG8_SCHED __builtin_amdgcn_sched_barrier(0)
; template <class Epi, class Sched, bool ALIGN_EPI = false, bool SP2 = false>
; __device__ __forceinline__ void gemm_phase(PG8_LAS unsigned char* lds, const Gemm g, const Sched& S, const Epi& E, const int wave0) {
;     ...
;             if constexpr (SP2) {
;             PG8_LDB(B0, 0, 0); PG8_LDB(B1, 0, 1); PG8_SCHED; PG8_LDA(At, 0, 0); PG8_STAGE(PG8_SA(1, 1), a1 + hstepA, voffA);
;             PG8_WAIT_V(8); PG8_WAIT_L(0); PG8_BAR; PG8_MMA(0, 0, At, B0); PG8_MMA(0, 1, At, B1); PG8_BAR; PG8_SCHED;
;     ...
;         for (int a = 0; a < 2; ++a)
; #pragma unroll
;             for (int b = 0; b < 2; ++b)
; #pragma unroll
;                 for (int m = 0; m < 4; ++m)
; #pragma unroll
;                     for (int n = 0; n < 2; ++n) acc[a][b][m][n] = (f32x4){0.f, 0.f, 0.f, 0.f};
.LBB0_1359:
	s_ashr_i32 s27, s26, 31
	s_lshl_b64 s[28:29], s[26:27], 20
	s_add_u32 s11, s20, s28
	s_addc_u32 s13, s21, s29
	s_add_u32 s28, s11, s18
	s_addc_u32 s29, s13, s19
	s_and_b64 s[18:19], s[2:3], exec
	s_cselect_b32 s11, s29, s17
	s_cselect_b32 s13, s28, s16
	s_add_u32 s0, s0, 0x80080
	s_addc_u32 s1, s1, 0
	s_add_u32 s15, s16, 0x100
	v_mov_b32_e32 v0, 0
	s_addc_u32 s27, s17, 0
	s_mov_b32 s41, -2
	v_mov_b32_e32 v1, v0
	v_mov_b64_e32 v[2:3], 0
	v_mov_b64_e32 v[4:5], 0
	v_mov_b64_e32 v[6:7], 0
	v_mov_b64_e32 v[8:9], 0
	v_mov_b64_e32 v[10:11], 0
	v_mov_b64_e32 v[12:13], 0
	v_mov_b64_e32 v[14:15], 0
	v_mov_b64_e32 v[24:25], 0
	v_mov_b64_e32 v[26:27], 0
	v_mov_b64_e32 v[28:29], 0
	v_mov_b64_e32 v[30:31], 0
	v_mov_b64_e32 v[40:41], 0
	v_mov_b64_e32 v[42:43], 0
	v_mov_b64_e32 v[44:45], 0
	v_mov_b64_e32 v[46:47], 0
	v_mov_b64_e32 v[16:17], 0
	v_mov_b64_e32 v[18:19], 0
	v_mov_b64_e32 v[20:21], 0
	v_mov_b64_e32 v[22:23], 0
	v_mov_b64_e32 v[32:33], 0
	v_mov_b64_e32 v[34:35], 0
	v_mov_b64_e32 v[36:37], 0
	v_mov_b64_e32 v[38:39], 0
	v_mov_b64_e32 v[48:49], 0
	v_mov_b64_e32 v[50:51], 0
	v_mov_b64_e32 v[52:53], 0
	v_mov_b64_e32 v[54:55], 0
	v_mov_b64_e32 v[56:57], 0
	v_mov_b64_e32 v[58:59], 0
	v_mov_b64_e32 v[60:61], 0
	v_mov_b64_e32 v[62:63], 0
	v_mov_b64_e32 v[66:67], 0
	v_mov_b64_e32 v[68:69], 0
	v_mov_b64_e32 v[70:71], 0
	v_mov_b64_e32 v[72:73], 0
	v_mov_b64_e32 v[74:75], 0
	v_mov_b64_e32 v[76:77], 0
	v_mov_b64_e32 v[78:79], 0
	v_mov_b64_e32 v[80:81], 0
	v_mov_b64_e32 v[90:91], 0
	v_mov_b64_e32 v[92:93], 0
	v_mov_b64_e32 v[94:95], 0
	v_mov_b64_e32 v[96:97], 0
	v_mov_b64_e32 v[106:107], 0
	v_mov_b64_e32 v[108:109], 0
	v_mov_b64_e32 v[110:111], 0
	v_mov_b64_e32 v[112:113], 0
	v_mov_b64_e32 v[82:83], 0
	v_mov_b64_e32 v[84:85], 0
	v_mov_b64_e32 v[86:87], 0
	v_mov_b64_e32 v[88:89], 0
	v_mov_b64_e32 v[98:99], 0
	v_mov_b64_e32 v[100:101], 0
	v_mov_b64_e32 v[102:103], 0
	v_mov_b64_e32 v[104:105], 0
	v_mov_b64_e32 v[114:115], 0
	v_mov_b64_e32 v[116:117], 0
	v_mov_b64_e32 v[118:119], 0
	v_mov_b64_e32 v[120:121], 0
	v_mov_b64_e32 v[122:123], 0
	v_mov_b64_e32 v[124:125], 0
	v_mov_b64_e32 v[126:127], 0
	v_mov_b64_e32 v[128:129], 0
	s_mov_b64 s[46:47], 0x80
	v_add_u32_e32 v252, 0x10000, v141
	v_add_u32_e32 v253, 0x14000, v141
	v_add_u32_e32 v254, 0x18000, v141
	v_add_u32_e32 v255, 0x1c000, v141
.LBB0_1360:
	s_add_u32 s16, s0, 0xfff80080
	s_addc_u32 s17, s1, -1
	s_add_i32 s42, 0, 0x10000
	s_cmp_eq_u32 s41, 12
	s_cselect_b32 s19, s5, s17
	s_cselect_b32 s18, s4, s16
	s_cselect_b32 s17, s11, s27
	s_cselect_b32 s16, s13, s15
	s_add_i32 s44, 0, 0x14000
	ds_read_b128 v[144:147], v252
	ds_read_b128 v[148:151], v252 offset:1024
	ds_read_b128 v[152:155], v252 offset:2048
	ds_read_b128 v[156:159], v252 offset:3072
	ds_read_b128 v[178:181], v253
	ds_read_b128 v[182:185], v253 offset:1024
	ds_read_b128 v[186:189], v253 offset:2048
	ds_read_b128 v[190:193], v253 offset:3072
	s_add_i32 m0, s23, 0xc000
	ds_read_b128 v[194:197], v143
	ds_read_b128 v[208:211], v143 offset:1024
	ds_read_b128 v[212:215], v143 offset:2048
	ds_read_b128 v[216:219], v143 offset:3072
	ds_read_b128 v[220:223], v143 offset:4096
	ds_read_b128 v[224:227], v143 offset:5120
	ds_read_b128 v[228:231], v143 offset:6144
	ds_read_b128 v[232:235], v143 offset:7168
	global_load_lds_dwordx4 v136, s[0:1]
	s_add_i32 m0, s23, 0xe000
	s_nop 0
	global_load_lds_dwordx4 v138, s[0:1]
	s_waitcnt vmcnt(8)
	s_waitcnt lgkmcnt(0)
	s_barrier
	s_setprio 1
	s_waitcnt lgkmcnt(0)
	v_mfma_f32_16x16x32_bf16 v[126:129], v[144:147], v[194:197], v[126:129]
	v_mfma_f32_16x16x32_bf16 v[122:125], v[152:155], v[194:197], v[122:125]
	v_mfma_f32_16x16x32_bf16 v[118:121], v[144:147], v[212:215], v[118:121]
	v_mfma_f32_16x16x32_bf16 v[114:117], v[152:155], v[212:215], v[114:117]
	v_mfma_f32_16x16x32_bf16 v[102:105], v[144:147], v[220:223], v[102:105]
	v_mfma_f32_16x16x32_bf16 v[98:101], v[152:155], v[220:223], v[98:101]
	v_mfma_f32_16x16x32_bf16 v[86:89], v[144:147], v[228:231], v[86:89]
	v_mfma_f32_16x16x32_bf16 v[82:85], v[152:155], v[228:231], v[82:85]
	v_mfma_f32_16x16x32_bf16 v[126:129], v[148:151], v[208:211], v[126:129]
	v_mfma_f32_16x16x32_bf16 v[122:125], v[156:159], v[208:211], v[122:125]
	v_mfma_f32_16x16x32_bf16 v[118:121], v[148:151], v[216:219], v[118:121]
	v_mfma_f32_16x16x32_bf16 v[114:117], v[156:159], v[216:219], v[114:117]
	v_mfma_f32_16x16x32_bf16 v[102:105], v[148:151], v[224:227], v[102:105]
	v_mfma_f32_16x16x32_bf16 v[98:101], v[156:159], v[224:227], v[98:101]
	v_mfma_f32_16x16x32_bf16 v[86:89], v[148:151], v[232:235], v[86:89]
	v_mfma_f32_16x16x32_bf16 v[82:85], v[156:159], v[232:235], v[82:85]
	s_setprio 0
	s_setprio 1
	v_mfma_f32_16x16x32_bf16 v[110:113], v[178:181], v[194:197], v[110:113]
	v_mfma_f32_16x16x32_bf16 v[106:109], v[186:189], v[194:197], v[106:109]
	v_mfma_f32_16x16x32_bf16 v[94:97], v[178:181], v[212:215], v[94:97]
	v_mfma_f32_16x16x32_bf16 v[90:93], v[186:189], v[212:215], v[90:93]
	v_mfma_f32_16x16x32_bf16 v[78:81], v[178:181], v[220:223], v[78:81]
	v_mfma_f32_16x16x32_bf16 v[74:77], v[186:189], v[220:223], v[74:77]
	v_mfma_f32_16x16x32_bf16 v[70:73], v[178:181], v[228:231], v[70:73]
	v_mfma_f32_16x16x32_bf16 v[66:69], v[186:189], v[228:231], v[66:69]
	v_mfma_f32_16x16x32_bf16 v[110:113], v[182:185], v[208:211], v[110:113]
	v_mfma_f32_16x16x32_bf16 v[106:109], v[190:193], v[208:211], v[106:109]
	v_mfma_f32_16x16x32_bf16 v[94:97], v[182:185], v[216:219], v[94:97]
	v_mfma_f32_16x16x32_bf16 v[90:93], v[190:193], v[216:219], v[90:93]
	v_mfma_f32_16x16x32_bf16 v[78:81], v[182:185], v[224:227], v[78:81]
	v_mfma_f32_16x16x32_bf16 v[74:77], v[190:193], v[224:227], v[74:77]
	v_mfma_f32_16x16x32_bf16 v[70:73], v[182:185], v[232:235], v[70:73]
	v_mfma_f32_16x16x32_bf16 v[66:69], v[190:193], v[232:235], v[66:69]
	s_setprio 0
	s_barrier
; #define PG8_STAGE(bufoff, gbase, voff) do { _Pragma("unroll") for (int _i = 0; _i < 2; ++_i) \
;         __builtin_amdgcn_global_load_lds((const unsigned*)((const char*)(gbase) + (voff)[_i]), (PG8_LAS unsigned*)(lds + (bufoff) + ldsw + _i * 8192), 16, 0, 0); } while (0)
; #define PG8_LDA(dst, b, h) do { _Pragma("unroll") for (int m = 0; m < 4; ++m) _Pragma("unroll") for (int k = 0; k < 2; ++k) dst[m][k] = *(const PG8_LAS bf16x8*)(lds + PG8_SA(b, h) + aoff + m * 2048 + k * 1024); } while (0)
; #define PG8_LDB(dst, b, h) do { _Pragma("unroll") for (int n = 0; n < 2; ++n) _Pragma("unroll") for (int k = 0; k < 2; ++k) dst[n][k] = *(const PG8_LAS bf16x8*)(lds + PG8_SB(b, h) + boff + n * 2048 + k * 1024); } while (0)
; #define PG8_MMA(ai, bj, At, Bt) do { __builtin_amdgcn_s_setprio(1); _Pragma("unroll") for (int m = 0; m < 4; ++m) _Pragma("unroll") for (int n = 0; n < 2; ++n) _Pragma("unroll") for (int k = 0; k < 2; ++k) \
;         acc[ai][bj][m][n] = __builtin_amdgcn_mfma_f32_16x16x32_bf16(Bt[n][k], At[m][k], acc[ai][bj][m][n], 0, 0, 0); __builtin_amdgcn_s_setprio(0); } while (0)
; #define PG8_WAIT_V(n) asm volatile("s_waitcnt vmcnt(" #n ")" ::: "memory")
; #define PG8_WAIT_L(n) asm volatile("s_waitcnt lgkmcnt(" #n ")" ::: "memory")
; #define PG8_BAR __builtin_amdgcn_s_barrier()
; #define PG8_SCHED __builtin_amdgcn_sched_barrier(0)
; template <class Epi, class Sched, bool ALIGN_EPI = false, bool SP2 = false>
; __device__ __forceinline__ void gemm_phase(PG8_LAS unsigned char* lds, const Gemm g, const Sched& S, const Epi& E, const int wave0) {
;     ...
;             PG8_WAIT_V(8); PG8_WAIT_L(0); PG8_BAR; PG8_MMA(0, 0, At, B0); PG8_MMA(0, 1, At, B1); PG8_BAR; PG8_SCHED;
;             PG8_LDA(At, 0, 1); PG8_STAGE(PG8_SB(0, 0), b2, voffB); PG8_STAGE(PG8_SB(0, 1), b2 + hstepB, voffB); PG8_STAGE(PG8_SA(0, 0), a2, voffA);
;             PG8_WAIT_V(8); PG8_WAIT_L(0); PG8_BAR; PG8_MMA(1, 0, At, B0); PG8_MMA(1, 1, At, B1); PG8_BAR; PG8_SCHED;
;             PG8_LDB(B0, 1, 0); PG8_LDB(B1, 1, 1); PG8_SCHED; PG8_LDA(At, 1, 0); PG8_STAGE(PG8_SA(0, 1), a2 + hstepA, voffA);
	s_add_i32 s42, s42, s22
	s_mov_b32 m0, s42
	ds_read_b128 v[194:197], v143 offset:16384
	ds_read_b128 v[208:211], v143 offset:17408
	ds_read_b128 v[212:215], v143 offset:18432
	ds_read_b128 v[216:219], v143 offset:19456
	ds_read_b128 v[220:223], v143 offset:20480
	ds_read_b128 v[224:227], v143 offset:21504
	ds_read_b128 v[228:231], v143 offset:22528
	ds_read_b128 v[232:235], v143 offset:23552
	global_load_lds_dwordx4 v64, s[16:17]
	s_add_i32 m0, s42, 0x2000
	s_add_u32 s42, s16, 0x80000
	s_addc_u32 s43, s17, 0
	s_add_i32 s44, s44, s22
	global_load_lds_dwordx4 v130, s[16:17]
	s_mov_b32 m0, s44
	s_mov_b64 s[100:101], s[18:19]
	global_load_lds_dwordx4 v64, s[42:43]
	s_add_i32 m0, s44, 0x2000
	s_nop 0
	global_load_lds_dwordx4 v130, s[42:43]
	s_mov_b32 m0, s23
	s_nop 0
	global_load_lds_dwordx4 v134, s[18:19]
	s_mov_b32 m0, s24
	s_nop 0
	global_load_lds_dwordx4 v132, s[18:19]
	s_waitcnt vmcnt(8)
	s_waitcnt lgkmcnt(0)
	s_barrier
	s_setprio 1
	s_waitcnt lgkmcnt(0)
	v_mfma_f32_16x16x32_bf16 v[60:63], v[144:147], v[194:197], v[60:63]
	v_mfma_f32_16x16x32_bf16 v[56:59], v[152:155], v[194:197], v[56:59]
	v_mfma_f32_16x16x32_bf16 v[52:55], v[144:147], v[212:215], v[52:55]
	v_mfma_f32_16x16x32_bf16 v[48:51], v[152:155], v[212:215], v[48:51]
	v_mfma_f32_16x16x32_bf16 v[36:39], v[144:147], v[220:223], v[36:39]
	v_mfma_f32_16x16x32_bf16 v[32:35], v[152:155], v[220:223], v[32:35]
	v_mfma_f32_16x16x32_bf16 v[20:23], v[144:147], v[228:231], v[20:23]
	v_mfma_f32_16x16x32_bf16 v[16:19], v[152:155], v[228:231], v[16:19]
	v_mfma_f32_16x16x32_bf16 v[60:63], v[148:151], v[208:211], v[60:63]
	v_mfma_f32_16x16x32_bf16 v[56:59], v[156:159], v[208:211], v[56:59]
	v_mfma_f32_16x16x32_bf16 v[52:55], v[148:151], v[216:219], v[52:55]
	v_mfma_f32_16x16x32_bf16 v[48:51], v[156:159], v[216:219], v[48:51]
	v_mfma_f32_16x16x32_bf16 v[36:39], v[148:151], v[224:227], v[36:39]
	v_mfma_f32_16x16x32_bf16 v[32:35], v[156:159], v[224:227], v[32:35]
	v_mfma_f32_16x16x32_bf16 v[20:23], v[148:151], v[232:235], v[20:23]
	v_mfma_f32_16x16x32_bf16 v[16:19], v[156:159], v[232:235], v[16:19]
	s_setprio 0
	s_setprio 1
	v_mfma_f32_16x16x32_bf16 v[44:47], v[178:181], v[194:197], v[44:47]
	v_mfma_f32_16x16x32_bf16 v[40:43], v[186:189], v[194:197], v[40:43]
	v_mfma_f32_16x16x32_bf16 v[28:31], v[178:181], v[212:215], v[28:31]
	v_mfma_f32_16x16x32_bf16 v[24:27], v[186:189], v[212:215], v[24:27]
	v_mfma_f32_16x16x32_bf16 v[12:15], v[178:181], v[220:223], v[12:15]
	v_mfma_f32_16x16x32_bf16 v[8:11], v[186:189], v[220:223], v[8:11]
	v_mfma_f32_16x16x32_bf16 v[4:7], v[178:181], v[228:231], v[4:7]
	v_mfma_f32_16x16x32_bf16 v[0:3], v[186:189], v[228:231], v[0:3]
	v_mfma_f32_16x16x32_bf16 v[44:47], v[182:185], v[208:211], v[44:47]
	v_mfma_f32_16x16x32_bf16 v[40:43], v[190:193], v[208:211], v[40:43]
	v_mfma_f32_16x16x32_bf16 v[28:31], v[182:185], v[216:219], v[28:31]
	v_mfma_f32_16x16x32_bf16 v[24:27], v[190:193], v[216:219], v[24:27]
	v_mfma_f32_16x16x32_bf16 v[12:15], v[182:185], v[224:227], v[12:15]
	v_mfma_f32_16x16x32_bf16 v[8:11], v[190:193], v[224:227], v[8:11]
	v_mfma_f32_16x16x32_bf16 v[4:7], v[182:185], v[232:235], v[4:7]
	v_mfma_f32_16x16x32_bf16 v[0:3], v[190:193], v[232:235], v[0:3]
	s_setprio 0
	s_barrier
	s_add_i32 s42, 0, 0x18000
	s_add_i32 s43, 0, 0x1c000
	ds_read_b128 v[144:147], v254
	ds_read_b128 v[148:151], v254 offset:1024
	ds_read_b128 v[152:155], v254 offset:2048
	ds_read_b128 v[156:159], v254 offset:3072
	ds_read_b128 v[178:181], v255
	ds_read_b128 v[182:185], v255 offset:1024
	ds_read_b128 v[186:189], v255 offset:2048
	ds_read_b128 v[190:193], v255 offset:3072
	s_add_u32 s18, s18, 0x80000
	s_addc_u32 s19, s19, 0
	s_mov_b32 m0, s25
	ds_read_b128 v[194:197], v143 offset:32768
	ds_read_b128 v[208:211], v143 offset:33792
	ds_read_b128 v[212:215], v143 offset:34816
	ds_read_b128 v[216:219], v143 offset:35840
	ds_read_b128 v[220:223], v143 offset:36864
	ds_read_b128 v[224:227], v143 offset:37888
	ds_read_b128 v[228:231], v143 offset:38912
	ds_read_b128 v[232:235], v143 offset:39936
	global_load_lds_dwordx4 v134, s[18:19]
	s_mov_b32 m0, s33
	s_nop 0
	global_load_lds_dwordx4 v132, s[18:19]
	s_waitcnt vmcnt(8)
	s_waitcnt lgkmcnt(0)
	s_barrier
; #define PG8_STAGE(bufoff, gbase, voff) do { _Pragma("unroll") for (int _i = 0; _i < 2; ++_i) \
;         __builtin_amdgcn_global_load_lds((const unsigned*)((const char*)(gbase) + (voff)[_i]), (PG8_LAS unsigned*)(lds + (bufoff) + ldsw + _i * 8192), 16, 0, 0); } while (0)
; #define PG8_LDA(dst, b, h) do { _Pragma("unroll") for (int m = 0; m < 4; ++m) _Pragma("unroll") for (int k = 0; k < 2; ++k) dst[m][k] = *(const PG8_LAS bf16x8*)(lds + PG8_SA(b, h) + aoff + m * 2048 + k * 1024); } while (0)
; #define PG8_MMA(ai, bj, At, Bt) do { __builtin_amdgcn_s_setprio(1); _Pragma("unroll") for (int m = 0; m < 4; ++m) _Pragma("unroll") for (int n = 0; n < 2; ++n) _Pragma("unroll") for (int k = 0; k < 2; ++k) \
;         acc[ai][bj][m][n] = __builtin_amdgcn_mfma_f32_16x16x32_bf16(Bt[n][k], At[m][k], acc[ai][bj][m][n], 0, 0, 0); __builtin_amdgcn_s_setprio(0); } while (0)
; #define PG8_WAIT_V(n) asm volatile("s_waitcnt vmcnt(" #n ")" ::: "memory")
; #define PG8_WAIT_L(n) asm volatile("s_waitcnt lgkmcnt(" #n ")" ::: "memory")
; #define PG8_BAR __builtin_amdgcn_s_barrier()
; #define PG8_SCHED __builtin_amdgcn_sched_barrier(0)
; template <class Epi, class Sched, bool ALIGN_EPI = false, bool SP2 = false>
; __device__ __forceinline__ void gemm_phase(PG8_LAS unsigned char* lds, const Gemm g, const Sched& S, const Epi& E, const int wave0) {
;     ...
;             PG8_WAIT_V(8); PG8_WAIT_L(0); PG8_BAR; PG8_MMA(0, 0, At, B0); PG8_MMA(0, 1, At, B1); PG8_BAR; PG8_SCHED;
;             PG8_LDA(At, 1, 1); PG8_STAGE(PG8_SB(1, 0), b3, voffB); PG8_STAGE(PG8_SB(1, 1), b3 + hstepB, voffB); PG8_STAGE(PG8_SA(1, 0), a3, voffA);
;             PG8_WAIT_V(8); PG8_WAIT_L(0); PG8_BAR; PG8_MMA(1, 0, At, B0); PG8_MMA(1, 1, At, B1); PG8_BAR; PG8_SCHED;
	s_setprio 1
	s_waitcnt lgkmcnt(0)
	v_mfma_f32_16x16x32_bf16 v[126:129], v[144:147], v[194:197], v[126:129]
	v_mfma_f32_16x16x32_bf16 v[122:125], v[152:155], v[194:197], v[122:125]
	v_mfma_f32_16x16x32_bf16 v[118:121], v[144:147], v[212:215], v[118:121]
	v_mfma_f32_16x16x32_bf16 v[114:117], v[152:155], v[212:215], v[114:117]
	v_mfma_f32_16x16x32_bf16 v[102:105], v[144:147], v[220:223], v[102:105]
	v_mfma_f32_16x16x32_bf16 v[98:101], v[152:155], v[220:223], v[98:101]
	v_mfma_f32_16x16x32_bf16 v[86:89], v[144:147], v[228:231], v[86:89]
	v_mfma_f32_16x16x32_bf16 v[82:85], v[152:155], v[228:231], v[82:85]
	v_mfma_f32_16x16x32_bf16 v[126:129], v[148:151], v[208:211], v[126:129]
	v_mfma_f32_16x16x32_bf16 v[122:125], v[156:159], v[208:211], v[122:125]
	v_mfma_f32_16x16x32_bf16 v[118:121], v[148:151], v[216:219], v[118:121]
	v_mfma_f32_16x16x32_bf16 v[114:117], v[156:159], v[216:219], v[114:117]
	v_mfma_f32_16x16x32_bf16 v[102:105], v[148:151], v[224:227], v[102:105]
	v_mfma_f32_16x16x32_bf16 v[98:101], v[156:159], v[224:227], v[98:101]
	v_mfma_f32_16x16x32_bf16 v[86:89], v[148:151], v[232:235], v[86:89]
	v_mfma_f32_16x16x32_bf16 v[82:85], v[156:159], v[232:235], v[82:85]
	s_setprio 0
	s_setprio 1
	v_mfma_f32_16x16x32_bf16 v[110:113], v[178:181], v[194:197], v[110:113]
	v_mfma_f32_16x16x32_bf16 v[106:109], v[186:189], v[194:197], v[106:109]
	v_mfma_f32_16x16x32_bf16 v[94:97], v[178:181], v[212:215], v[94:97]
	v_mfma_f32_16x16x32_bf16 v[90:93], v[186:189], v[212:215], v[90:93]
	v_mfma_f32_16x16x32_bf16 v[78:81], v[178:181], v[220:223], v[78:81]
	v_mfma_f32_16x16x32_bf16 v[74:77], v[186:189], v[220:223], v[74:77]
	v_mfma_f32_16x16x32_bf16 v[70:73], v[178:181], v[228:231], v[70:73]
	v_mfma_f32_16x16x32_bf16 v[66:69], v[186:189], v[228:231], v[66:69]
	v_mfma_f32_16x16x32_bf16 v[110:113], v[182:185], v[208:211], v[110:113]
	v_mfma_f32_16x16x32_bf16 v[106:109], v[190:193], v[208:211], v[106:109]
	v_mfma_f32_16x16x32_bf16 v[94:97], v[182:185], v[216:219], v[94:97]
	v_mfma_f32_16x16x32_bf16 v[90:93], v[190:193], v[216:219], v[90:93]
	v_mfma_f32_16x16x32_bf16 v[78:81], v[182:185], v[224:227], v[78:81]
	v_mfma_f32_16x16x32_bf16 v[74:77], v[190:193], v[224:227], v[74:77]
	v_mfma_f32_16x16x32_bf16 v[70:73], v[182:185], v[232:235], v[70:73]
	v_mfma_f32_16x16x32_bf16 v[66:69], v[190:193], v[232:235], v[66:69]
	s_setprio 0
	s_barrier
	s_add_i32 s18, s42, s22
	s_add_u32 s46, s16, 0x80
	s_addc_u32 s47, s17, 0
	s_mov_b32 m0, s18
	ds_read_b128 v[194:197], v143 offset:49152
	ds_read_b128 v[208:211], v143 offset:50176
	ds_read_b128 v[212:215], v143 offset:51200
	ds_read_b128 v[216:219], v143 offset:52224
	ds_read_b128 v[220:223], v143 offset:53248
	ds_read_b128 v[224:227], v143 offset:54272
	ds_read_b128 v[228:231], v143 offset:55296
	ds_read_b128 v[232:235], v143 offset:56320
	global_load_lds_dwordx4 v64, s[46:47]
	s_add_i32 m0, s18, 0x2000
	s_add_u32 s16, s16, 0x80080
	s_addc_u32 s17, s17, 0
	s_add_i32 s18, s43, s22
	global_load_lds_dwordx4 v130, s[46:47]
	s_mov_b32 m0, s18
	s_nop 0
	global_load_lds_dwordx4 v64, s[16:17]
	s_add_i32 m0, s18, 0x2000
	s_nop 0
	global_load_lds_dwordx4 v130, s[16:17]
	s_add_u32 s100, s100, 0x80
	s_addc_u32 s101, s101, 0
	s_mov_b32 m0, s34
	s_nop 0
	global_load_lds_dwordx4 v134, s[100:101]
	s_mov_b32 m0, s35
	s_nop 0
	global_load_lds_dwordx4 v132, s[100:101]
	s_waitcnt vmcnt(8)
	s_waitcnt lgkmcnt(0)
	s_barrier
	s_setprio 1
	s_waitcnt lgkmcnt(0)
	v_mfma_f32_16x16x32_bf16 v[60:63], v[144:147], v[194:197], v[60:63]
	v_mfma_f32_16x16x32_bf16 v[56:59], v[152:155], v[194:197], v[56:59]
	v_mfma_f32_16x16x32_bf16 v[52:55], v[144:147], v[212:215], v[52:55]
	v_mfma_f32_16x16x32_bf16 v[48:51], v[152:155], v[212:215], v[48:51]
	v_mfma_f32_16x16x32_bf16 v[36:39], v[144:147], v[220:223], v[36:39]
	v_mfma_f32_16x16x32_bf16 v[32:35], v[152:155], v[220:223], v[32:35]
	v_mfma_f32_16x16x32_bf16 v[20:23], v[144:147], v[228:231], v[20:23]
	v_mfma_f32_16x16x32_bf16 v[16:19], v[152:155], v[228:231], v[16:19]
	v_mfma_f32_16x16x32_bf16 v[60:63], v[148:151], v[208:211], v[60:63]
	v_mfma_f32_16x16x32_bf16 v[56:59], v[156:159], v[208:211], v[56:59]
	v_mfma_f32_16x16x32_bf16 v[52:55], v[148:151], v[216:219], v[52:55]
	v_mfma_f32_16x16x32_bf16 v[48:51], v[156:159], v[216:219], v[48:51]
	v_mfma_f32_16x16x32_bf16 v[36:39], v[148:151], v[224:227], v[36:39]
	v_mfma_f32_16x16x32_bf16 v[32:35], v[156:159], v[224:227], v[32:35]
	v_mfma_f32_16x16x32_bf16 v[20:23], v[148:151], v[232:235], v[20:23]
	v_mfma_f32_16x16x32_bf16 v[16:19], v[156:159], v[232:235], v[16:19]
	s_setprio 0
	s_setprio 1
	v_mfma_f32_16x16x32_bf16 v[44:47], v[178:181], v[194:197], v[44:47]
	v_mfma_f32_16x16x32_bf16 v[40:43], v[186:189], v[194:197], v[40:43]
	v_mfma_f32_16x16x32_bf16 v[28:31], v[178:181], v[212:215], v[28:31]
	v_mfma_f32_16x16x32_bf16 v[24:27], v[186:189], v[212:215], v[24:27]
	v_mfma_f32_16x16x32_bf16 v[12:15], v[178:181], v[220:223], v[12:15]
	v_mfma_f32_16x16x32_bf16 v[8:11], v[186:189], v[220:223], v[8:11]
	v_mfma_f32_16x16x32_bf16 v[4:7], v[178:181], v[228:231], v[4:7]
	v_mfma_f32_16x16x32_bf16 v[0:3], v[186:189], v[228:231], v[0:3]
	v_mfma_f32_16x16x32_bf16 v[44:47], v[182:185], v[208:211], v[44:47]
	v_mfma_f32_16x16x32_bf16 v[40:43], v[190:193], v[208:211], v[40:43]
	v_mfma_f32_16x16x32_bf16 v[28:31], v[182:185], v[216:219], v[28:31]
	v_mfma_f32_16x16x32_bf16 v[24:27], v[190:193], v[216:219], v[24:27]
	v_mfma_f32_16x16x32_bf16 v[12:15], v[182:185], v[224:227], v[12:15]
	v_mfma_f32_16x16x32_bf16 v[8:11], v[190:193], v[224:227], v[8:11]
	v_mfma_f32_16x16x32_bf16 v[4:7], v[182:185], v[232:235], v[4:7]
	v_mfma_f32_16x16x32_bf16 v[0:3], v[190:193], v[232:235], v[0:3]
	s_setprio 0
	s_barrier
	s_add_i32 s41, s41, 2
	s_add_u32 s0, s0, 0x100
	s_addc_u32 s1, s1, 0
	s_add_u32 s15, s15, 0x100
	s_addc_u32 s27, s27, 0
	s_cmp_gt_u32 s41, 13
	s_cbranch_scc0 .LBB0_1360
	s_mov_b64 s[46:47], 0x80
	s_and_b64 vcc, exec, s[8:9]
	s_cbranch_vccz .LBB0_1363
	s_barrier

;     __host__ __device__ bool next(int i, Unit& u) const { return tile((long)i * G + c, u); }
;     __host__ __device__ bool next(int i, Unit& u) const { if (!tile((long)(i / NZ) * G + c, u)) return false; u.z = i % NZ; return true; }
; #define PG8_STAGE(bufoff, gbase, voff) do { _Pragma("unroll") for (int _i = 0; _i < 2; ++_i) \
;         __builtin_amdgcn_global_load_lds((const unsigned*)((const char*)(gbase) + (voff)[_i]), (PG8_LAS unsigned*)(lds + (bufoff) + ldsw + _i * 8192), 16, 0, 0); } while (0)
; #define PG8_LDA(dst, b, h) do { _Pragma("unroll") for (int m = 0; m < 4; ++m) _Pragma("unroll") for (int k = 0; k < 2; ++k) dst[m][k] = *(const PG8_LAS bf16x8*)(lds + PG8_SA(b, h) + aoff + m * 2048 + k * 1024); } while (0)
; #define PG8_WAIT_V(n) asm volatile("s_waitcnt vmcnt(" #n ")" ::: "memory")
; #define PG8_WAIT_L(n) asm volatile("s_waitcnt lgkmcnt(" #n ")" ::: "memory")
; template <class Epi, class Sched, bool ALIGN_EPI = false, bool SP2 = false>
; __device__ __forceinline__ void gemm_phase(PG8_LAS unsigned char* lds, const Gemm g, const Sched& S, const Epi& E, const int wave0) {
;     ...
;         const bool has_next = S.next(ui + 1, nxt);
;         const char* nA = has_next ? (const char*)g.A + (size_t)nxt.z * g.zsA + (size_t)nxt.pm * tstepA + (size_t)nxt.k0 * 2 : cA; const char* nB = has_next ? (const char*)g.Bt + (size_t)nxt.z * g.zsB + (size_t)nxt.pn * tstepB + (size_t)nxt.k0 * 2 : cB;
;         for (int t = 0; t < nt; t += 2) {
;             const bool last = (t == nt - 2);
;             const char* a1 = cA + (size_t)(t + 1) * kstep;
;             const char* a2 = last ? nA : cA + (size_t)(t + 2) * kstep; const char* b2 = last ? nB : cB + (size_t)(t + 2) * kstep;
;             const char* a3 = a2 + kstep; const char* b3 = b2 + kstep;
;             if (last && has_next) S.a_ready(nxt);
;             if constexpr (SP2) {
;             PG8_LDB(B0, 0, 0); PG8_LDB(B1, 0, 1); PG8_SCHED; PG8_LDA(At, 0, 0); PG8_STAGE(PG8_SA(1, 1), a1 + hstepA, voffA);
;             PG8_WAIT_V(8); PG8_WAIT_L(0); PG8_BAR; PG8_MMA(0, 0, At, B0); PG8_MMA(0, 1, At, B1); PG8_BAR; PG8_SCHED;
;     ...
;         for (int a = 0; a < 2; ++a)
; #pragma unroll
;             for (int b = 0; b < 2; ++b)
; #pragma unroll
;                 for (int m = 0; m < 4; ++m)
; #pragma unroll
;                     for (int n = 0; n < 2; ++n) acc[a][b][m][n] = (f32x4){0.f, 0.f, 0.f, 0.f};
.LBB0_1570:
	s_ashr_i32 s9, s8, 31
	s_lshl_b64 s[10:11], s[8:9], 20
	v_readlane_b32 s12, v245, 1
	v_readlane_b32 s13, v245, 2
	s_add_u32 s10, s12, s10
	s_addc_u32 s11, s13, s11
	s_and_b64 s[12:13], s[42:43], exec
	s_cselect_b32 s9, s11, s1
	s_cselect_b32 s33, s10, s0
	s_ashr_i32 s7, s6, 31
	s_lshl_b64 s[12:13], s[6:7], 20
	s_add_u32 s12, s20, s12
	s_addc_u32 s13, s21, s13
	s_and_b64 s[18:19], s[42:43], exec
	s_cselect_b32 s7, s13, s17
	s_cselect_b32 s36, s12, s16
	s_add_u32 s0, s0, 0x80080
	s_addc_u32 s1, s1, 0
	s_add_u32 s37, s16, 0x100
	v_mov_b32_e32 v0, 0
	s_addc_u32 s44, s17, 0
	s_mov_b32 s45, -2
	v_mov_b32_e32 v1, v0
	v_mov_b64_e32 v[2:3], 0
	v_mov_b64_e32 v[4:5], 0
	v_mov_b64_e32 v[6:7], 0
	v_mov_b64_e32 v[16:17], 0
	v_mov_b64_e32 v[18:19], 0
	v_mov_b64_e32 v[20:21], 0
	v_mov_b64_e32 v[22:23], 0
	v_mov_b64_e32 v[32:33], 0
	v_mov_b64_e32 v[34:35], 0
	v_mov_b64_e32 v[36:37], 0
	v_mov_b64_e32 v[38:39], 0
	v_mov_b64_e32 v[48:49], 0
	v_mov_b64_e32 v[50:51], 0
	v_mov_b64_e32 v[52:53], 0
	v_mov_b64_e32 v[54:55], 0
	v_mov_b64_e32 v[8:9], 0
	v_mov_b64_e32 v[10:11], 0
	v_mov_b64_e32 v[12:13], 0
	v_mov_b64_e32 v[14:15], 0
	v_mov_b64_e32 v[24:25], 0
	v_mov_b64_e32 v[26:27], 0
	v_mov_b64_e32 v[28:29], 0
	v_mov_b64_e32 v[30:31], 0
	v_mov_b64_e32 v[40:41], 0
	v_mov_b64_e32 v[42:43], 0
	v_mov_b64_e32 v[44:45], 0
	v_mov_b64_e32 v[46:47], 0
	v_mov_b64_e32 v[56:57], 0
	v_mov_b64_e32 v[58:59], 0
	v_mov_b64_e32 v[60:61], 0
	v_mov_b64_e32 v[62:63], 0
	v_mov_b64_e32 v[66:67], 0
	v_mov_b64_e32 v[68:69], 0
	v_mov_b64_e32 v[70:71], 0
	v_mov_b64_e32 v[72:73], 0
	v_mov_b64_e32 v[82:83], 0
	v_mov_b64_e32 v[84:85], 0
	v_mov_b64_e32 v[86:87], 0
	v_mov_b64_e32 v[88:89], 0
	v_mov_b64_e32 v[98:99], 0
	v_mov_b64_e32 v[100:101], 0
	v_mov_b64_e32 v[102:103], 0
	v_mov_b64_e32 v[104:105], 0
	v_mov_b64_e32 v[114:115], 0
	v_mov_b64_e32 v[116:117], 0
	v_mov_b64_e32 v[118:119], 0
	v_mov_b64_e32 v[120:121], 0
	v_mov_b64_e32 v[74:75], 0
	v_mov_b64_e32 v[76:77], 0
	v_mov_b64_e32 v[78:79], 0
	v_mov_b64_e32 v[80:81], 0
	v_mov_b64_e32 v[90:91], 0
	v_mov_b64_e32 v[92:93], 0
	v_mov_b64_e32 v[94:95], 0
	v_mov_b64_e32 v[96:97], 0
	v_mov_b64_e32 v[106:107], 0
	v_mov_b64_e32 v[108:109], 0
	v_mov_b64_e32 v[110:111], 0
	v_mov_b64_e32 v[112:113], 0
	v_mov_b64_e32 v[122:123], 0
	v_mov_b64_e32 v[124:125], 0
	v_mov_b64_e32 v[126:127], 0
	v_mov_b64_e32 v[128:129], 0
	s_mov_b64 s[50:51], 0x80
	v_add_u32_e32 v252, 0x10000, v145
	v_add_u32_e32 v253, 0x14000, v145
	v_add_u32_e32 v254, 0x18000, v145
	v_add_u32_e32 v255, 0x1c000, v145
.LBB0_1571:
	s_add_u32 s16, s0, 0xfff80080
	s_addc_u32 s17, s1, -1
	s_add_i32 s46, 0, 0x10000
	s_cmp_eq_u32 s45, 28
	s_cselect_b32 s19, s9, s17
	s_cselect_b32 s18, s33, s16
	s_cselect_b32 s17, s7, s44
	s_cselect_b32 s16, s36, s37
	s_add_i32 s48, 0, 0x14000
	ds_read_b128 v[140:143], v252
	ds_read_b128 v[148:151], v252 offset:1024
	ds_read_b128 v[152:155], v252 offset:2048
	ds_read_b128 v[156:159], v252 offset:3072
	ds_read_b128 v[178:181], v253
	ds_read_b128 v[182:185], v253 offset:1024
	ds_read_b128 v[186:189], v253 offset:2048
	ds_read_b128 v[190:193], v253 offset:3072
	s_add_i32 m0, s15, 0xc000
	ds_read_b128 v[194:197], v147
	ds_read_b128 v[208:211], v147 offset:1024
	ds_read_b128 v[212:215], v147 offset:2048
	ds_read_b128 v[216:219], v147 offset:3072
	ds_read_b128 v[220:223], v147 offset:4096
	ds_read_b128 v[224:227], v147 offset:5120
	ds_read_b128 v[228:231], v147 offset:6144
	ds_read_b128 v[232:235], v147 offset:7168
	global_load_lds_dwordx4 v136, s[0:1]
	s_add_i32 m0, s15, 0xe000
	s_nop 0
	global_load_lds_dwordx4 v138, s[0:1]
	s_waitcnt vmcnt(8)
	s_waitcnt lgkmcnt(0)
	s_barrier
	s_setprio 1
	s_waitcnt lgkmcnt(0)
	v_mfma_f32_16x16x32_bf16 v[126:129], v[140:143], v[194:197], v[126:129]
	v_mfma_f32_16x16x32_bf16 v[122:125], v[152:155], v[194:197], v[122:125]
	v_mfma_f32_16x16x32_bf16 v[110:113], v[140:143], v[212:215], v[110:113]
	v_mfma_f32_16x16x32_bf16 v[106:109], v[152:155], v[212:215], v[106:109]
	v_mfma_f32_16x16x32_bf16 v[94:97], v[140:143], v[220:223], v[94:97]
	v_mfma_f32_16x16x32_bf16 v[90:93], v[152:155], v[220:223], v[90:93]
	v_mfma_f32_16x16x32_bf16 v[78:81], v[140:143], v[228:231], v[78:81]
	v_mfma_f32_16x16x32_bf16 v[74:77], v[152:155], v[228:231], v[74:77]
	v_mfma_f32_16x16x32_bf16 v[126:129], v[148:151], v[208:211], v[126:129]
	v_mfma_f32_16x16x32_bf16 v[122:125], v[156:159], v[208:211], v[122:125]
	v_mfma_f32_16x16x32_bf16 v[110:113], v[148:151], v[216:219], v[110:113]
	v_mfma_f32_16x16x32_bf16 v[106:109], v[156:159], v[216:219], v[106:109]
	v_mfma_f32_16x16x32_bf16 v[94:97], v[148:151], v[224:227], v[94:97]
	v_mfma_f32_16x16x32_bf16 v[90:93], v[156:159], v[224:227], v[90:93]
	v_mfma_f32_16x16x32_bf16 v[78:81], v[148:151], v[232:235], v[78:81]
	v_mfma_f32_16x16x32_bf16 v[74:77], v[156:159], v[232:235], v[74:77]
	s_setprio 0
	s_setprio 1
	v_mfma_f32_16x16x32_bf16 v[118:121], v[178:181], v[194:197], v[118:121]
	v_mfma_f32_16x16x32_bf16 v[114:117], v[186:189], v[194:197], v[114:117]
	v_mfma_f32_16x16x32_bf16 v[102:105], v[178:181], v[212:215], v[102:105]
	v_mfma_f32_16x16x32_bf16 v[98:101], v[186:189], v[212:215], v[98:101]
	v_mfma_f32_16x16x32_bf16 v[86:89], v[178:181], v[220:223], v[86:89]
	v_mfma_f32_16x16x32_bf16 v[82:85], v[186:189], v[220:223], v[82:85]
	v_mfma_f32_16x16x32_bf16 v[70:73], v[178:181], v[228:231], v[70:73]
	v_mfma_f32_16x16x32_bf16 v[66:69], v[186:189], v[228:231], v[66:69]
	v_mfma_f32_16x16x32_bf16 v[118:121], v[182:185], v[208:211], v[118:121]
	v_mfma_f32_16x16x32_bf16 v[114:117], v[190:193], v[208:211], v[114:117]
	v_mfma_f32_16x16x32_bf16 v[102:105], v[182:185], v[216:219], v[102:105]
	v_mfma_f32_16x16x32_bf16 v[98:101], v[190:193], v[216:219], v[98:101]
	v_mfma_f32_16x16x32_bf16 v[86:89], v[182:185], v[224:227], v[86:89]
	v_mfma_f32_16x16x32_bf16 v[82:85], v[190:193], v[224:227], v[82:85]
	v_mfma_f32_16x16x32_bf16 v[70:73], v[182:185], v[232:235], v[70:73]
	v_mfma_f32_16x16x32_bf16 v[66:69], v[190:193], v[232:235], v[66:69]
	s_setprio 0
	s_barrier
; #define PG8_STAGE(bufoff, gbase, voff) do { _Pragma("unroll") for (int _i = 0; _i < 2; ++_i) \
;         __builtin_amdgcn_global_load_lds((const unsigned*)((const char*)(gbase) + (voff)[_i]), (PG8_LAS unsigned*)(lds + (bufoff) + ldsw + _i * 8192), 16, 0, 0); } while (0)
; #define PG8_LDA(dst, b, h) do { _Pragma("unroll") for (int m = 0; m < 4; ++m) _Pragma("unroll") for (int k = 0; k < 2; ++k) dst[m][k] = *(const PG8_LAS bf16x8*)(lds + PG8_SA(b, h) + aoff + m * 2048 + k * 1024); } while (0)
; #define PG8_LDB(dst, b, h) do { _Pragma("unroll") for (int n = 0; n < 2; ++n) _Pragma("unroll") for (int k = 0; k < 2; ++k) dst[n][k] = *(const PG8_LAS bf16x8*)(lds + PG8_SB(b, h) + boff + n * 2048 + k * 1024); } while (0)
; #define PG8_MMA(ai, bj, At, Bt) do { __builtin_amdgcn_s_setprio(1); _Pragma("unroll") for (int m = 0; m < 4; ++m) _Pragma("unroll") for (int n = 0; n < 2; ++n) _Pragma("unroll") for (int k = 0; k < 2; ++k) \
;         acc[ai][bj][m][n] = __builtin_amdgcn_mfma_f32_16x16x32_bf16(Bt[n][k], At[m][k], acc[ai][bj][m][n], 0, 0, 0); __builtin_amdgcn_s_setprio(0); } while (0)
; #define PG8_WAIT_V(n) asm volatile("s_waitcnt vmcnt(" #n ")" ::: "memory")
; #define PG8_WAIT_L(n) asm volatile("s_waitcnt lgkmcnt(" #n ")" ::: "memory")
; #define PG8_BAR __builtin_amdgcn_s_barrier()
; #define PG8_SCHED __builtin_amdgcn_sched_barrier(0)
; template <class Epi, class Sched, bool ALIGN_EPI = false, bool SP2 = false>
; __device__ __forceinline__ void gemm_phase(PG8_LAS unsigned char* lds, const Gemm g, const Sched& S, const Epi& E, const int wave0) {
;     ...
;             PG8_LDA(At, 0, 1); PG8_STAGE(PG8_SB(0, 0), b2, voffB); PG8_STAGE(PG8_SB(0, 1), b2 + hstepB, voffB); PG8_STAGE(PG8_SA(0, 0), a2, voffA);
;             PG8_WAIT_V(8); PG8_WAIT_L(0); PG8_BAR; PG8_MMA(1, 0, At, B0); PG8_MMA(1, 1, At, B1); PG8_BAR; PG8_SCHED;
;             PG8_LDB(B0, 1, 0); PG8_LDB(B1, 1, 1); PG8_SCHED; PG8_LDA(At, 1, 0); PG8_STAGE(PG8_SA(0, 1), a2 + hstepA, voffA);
	s_add_i32 s46, s46, s28
	s_mov_b32 m0, s46
	ds_read_b128 v[194:197], v147 offset:16384
	ds_read_b128 v[208:211], v147 offset:17408
	ds_read_b128 v[212:215], v147 offset:18432
	ds_read_b128 v[216:219], v147 offset:19456
	ds_read_b128 v[220:223], v147 offset:20480
	ds_read_b128 v[224:227], v147 offset:21504
	ds_read_b128 v[228:231], v147 offset:22528
	ds_read_b128 v[232:235], v147 offset:23552
	global_load_lds_dwordx4 v64, s[16:17]
	s_add_i32 m0, s46, 0x2000
	s_add_u32 s46, s16, 0x80000
	s_addc_u32 s47, s17, 0
	s_add_i32 s48, s48, s28
	global_load_lds_dwordx4 v130, s[16:17]
	s_mov_b32 m0, s48
	s_mov_b64 s[100:101], s[18:19]
	global_load_lds_dwordx4 v64, s[46:47]
	s_add_i32 m0, s48, 0x2000
	s_nop 0
	global_load_lds_dwordx4 v130, s[46:47]
	s_mov_b32 m0, s15
	s_nop 0
	global_load_lds_dwordx4 v134, s[18:19]
	s_mov_b32 m0, s27
	s_nop 0
	global_load_lds_dwordx4 v132, s[18:19]
	s_waitcnt vmcnt(8)
	s_waitcnt lgkmcnt(0)
	s_barrier
	s_setprio 1
	s_waitcnt lgkmcnt(0)
	v_mfma_f32_16x16x32_bf16 v[60:63], v[140:143], v[194:197], v[60:63]
	v_mfma_f32_16x16x32_bf16 v[56:59], v[152:155], v[194:197], v[56:59]
	v_mfma_f32_16x16x32_bf16 v[44:47], v[140:143], v[212:215], v[44:47]
	v_mfma_f32_16x16x32_bf16 v[40:43], v[152:155], v[212:215], v[40:43]
	v_mfma_f32_16x16x32_bf16 v[28:31], v[140:143], v[220:223], v[28:31]
	v_mfma_f32_16x16x32_bf16 v[24:27], v[152:155], v[220:223], v[24:27]
	v_mfma_f32_16x16x32_bf16 v[12:15], v[140:143], v[228:231], v[12:15]
	v_mfma_f32_16x16x32_bf16 v[8:11], v[152:155], v[228:231], v[8:11]
	v_mfma_f32_16x16x32_bf16 v[60:63], v[148:151], v[208:211], v[60:63]
	v_mfma_f32_16x16x32_bf16 v[56:59], v[156:159], v[208:211], v[56:59]
	v_mfma_f32_16x16x32_bf16 v[44:47], v[148:151], v[216:219], v[44:47]
	v_mfma_f32_16x16x32_bf16 v[40:43], v[156:159], v[216:219], v[40:43]
	v_mfma_f32_16x16x32_bf16 v[28:31], v[148:151], v[224:227], v[28:31]
	v_mfma_f32_16x16x32_bf16 v[24:27], v[156:159], v[224:227], v[24:27]
	v_mfma_f32_16x16x32_bf16 v[12:15], v[148:151], v[232:235], v[12:15]
	v_mfma_f32_16x16x32_bf16 v[8:11], v[156:159], v[232:235], v[8:11]
	s_setprio 0
	s_setprio 1
	v_mfma_f32_16x16x32_bf16 v[52:55], v[178:181], v[194:197], v[52:55]
	v_mfma_f32_16x16x32_bf16 v[48:51], v[186:189], v[194:197], v[48:51]
	v_mfma_f32_16x16x32_bf16 v[36:39], v[178:181], v[212:215], v[36:39]
	v_mfma_f32_16x16x32_bf16 v[32:35], v[186:189], v[212:215], v[32:35]
	v_mfma_f32_16x16x32_bf16 v[20:23], v[178:181], v[220:223], v[20:23]
	v_mfma_f32_16x16x32_bf16 v[16:19], v[186:189], v[220:223], v[16:19]
	v_mfma_f32_16x16x32_bf16 v[4:7], v[178:181], v[228:231], v[4:7]
	v_mfma_f32_16x16x32_bf16 v[0:3], v[186:189], v[228:231], v[0:3]
	v_mfma_f32_16x16x32_bf16 v[52:55], v[182:185], v[208:211], v[52:55]
	v_mfma_f32_16x16x32_bf16 v[48:51], v[190:193], v[208:211], v[48:51]
	v_mfma_f32_16x16x32_bf16 v[36:39], v[182:185], v[216:219], v[36:39]
	v_mfma_f32_16x16x32_bf16 v[32:35], v[190:193], v[216:219], v[32:35]
	v_mfma_f32_16x16x32_bf16 v[20:23], v[182:185], v[224:227], v[20:23]
	v_mfma_f32_16x16x32_bf16 v[16:19], v[190:193], v[224:227], v[16:19]
	v_mfma_f32_16x16x32_bf16 v[4:7], v[182:185], v[232:235], v[4:7]
	v_mfma_f32_16x16x32_bf16 v[0:3], v[190:193], v[232:235], v[0:3]
	s_setprio 0
	s_barrier
	s_add_i32 s46, 0, 0x18000
	s_add_i32 s47, 0, 0x1c000
	ds_read_b128 v[140:143], v254
	ds_read_b128 v[148:151], v254 offset:1024
	ds_read_b128 v[152:155], v254 offset:2048
	ds_read_b128 v[156:159], v254 offset:3072
	ds_read_b128 v[178:181], v255
	ds_read_b128 v[182:185], v255 offset:1024
	ds_read_b128 v[186:189], v255 offset:2048
	ds_read_b128 v[190:193], v255 offset:3072
	s_add_u32 s18, s18, 0x80000
	s_addc_u32 s19, s19, 0
	s_mov_b32 m0, s29
	ds_read_b128 v[194:197], v147 offset:32768
	ds_read_b128 v[208:211], v147 offset:33792
	ds_read_b128 v[212:215], v147 offset:34816
	ds_read_b128 v[216:219], v147 offset:35840
	ds_read_b128 v[220:223], v147 offset:36864
	ds_read_b128 v[224:227], v147 offset:37888
	ds_read_b128 v[228:231], v147 offset:38912
	ds_read_b128 v[232:235], v147 offset:39936
	global_load_lds_dwordx4 v134, s[18:19]
	s_mov_b32 m0, s30
	s_nop 0
	global_load_lds_dwordx4 v132, s[18:19]
	s_waitcnt vmcnt(8)
	s_waitcnt lgkmcnt(0)
	s_barrier
; #define PG8_STAGE(bufoff, gbase, voff) do { _Pragma("unroll") for (int _i = 0; _i < 2; ++_i) \
;         __builtin_amdgcn_global_load_lds((const unsigned*)((const char*)(gbase) + (voff)[_i]), (PG8_LAS unsigned*)(lds + (bufoff) + ldsw + _i * 8192), 16, 0, 0); } while (0)
; #define PG8_LDA(dst, b, h) do { _Pragma("unroll") for (int m = 0; m < 4; ++m) _Pragma("unroll") for (int k = 0; k < 2; ++k) dst[m][k] = *(const PG8_LAS bf16x8*)(lds + PG8_SA(b, h) + aoff + m * 2048 + k * 1024); } while (0)
; #define PG8_MMA(ai, bj, At, Bt) do { __builtin_amdgcn_s_setprio(1); _Pragma("unroll") for (int m = 0; m < 4; ++m) _Pragma("unroll") for (int n = 0; n < 2; ++n) _Pragma("unroll") for (int k = 0; k < 2; ++k) \
;         acc[ai][bj][m][n] = __builtin_amdgcn_mfma_f32_16x16x32_bf16(Bt[n][k], At[m][k], acc[ai][bj][m][n], 0, 0, 0); __builtin_amdgcn_s_setprio(0); } while (0)
; #define PG8_WAIT_V(n) asm volatile("s_waitcnt vmcnt(" #n ")" ::: "memory")
; #define PG8_WAIT_L(n) asm volatile("s_waitcnt lgkmcnt(" #n ")" ::: "memory")
; #define PG8_BAR __builtin_amdgcn_s_barrier()
; #define PG8_SCHED __builtin_amdgcn_sched_barrier(0)
; template <class Epi, class Sched, bool ALIGN_EPI = false, bool SP2 = false>
; __device__ __forceinline__ void gemm_phase(PG8_LAS unsigned char* lds, const Gemm g, const Sched& S, const Epi& E, const int wave0) {
;     ...
;             PG8_WAIT_V(8); PG8_WAIT_L(0); PG8_BAR; PG8_MMA(0, 0, At, B0); PG8_MMA(0, 1, At, B1); PG8_BAR; PG8_SCHED;
;             PG8_LDA(At, 1, 1); PG8_STAGE(PG8_SB(1, 0), b3, voffB); PG8_STAGE(PG8_SB(1, 1), b3 + hstepB, voffB); PG8_STAGE(PG8_SA(1, 0), a3, voffA);
;             PG8_WAIT_V(8); PG8_WAIT_L(0); PG8_BAR; PG8_MMA(1, 0, At, B0); PG8_MMA(1, 1, At, B1); PG8_BAR; PG8_SCHED;
	s_setprio 1
	s_waitcnt lgkmcnt(0)
	v_mfma_f32_16x16x32_bf16 v[126:129], v[140:143], v[194:197], v[126:129]
	v_mfma_f32_16x16x32_bf16 v[122:125], v[152:155], v[194:197], v[122:125]
	v_mfma_f32_16x16x32_bf16 v[110:113], v[140:143], v[212:215], v[110:113]
	v_mfma_f32_16x16x32_bf16 v[106:109], v[152:155], v[212:215], v[106:109]
	v_mfma_f32_16x16x32_bf16 v[94:97], v[140:143], v[220:223], v[94:97]
	v_mfma_f32_16x16x32_bf16 v[90:93], v[152:155], v[220:223], v[90:93]
	v_mfma_f32_16x16x32_bf16 v[78:81], v[140:143], v[228:231], v[78:81]
	v_mfma_f32_16x16x32_bf16 v[74:77], v[152:155], v[228:231], v[74:77]
	v_mfma_f32_16x16x32_bf16 v[126:129], v[148:151], v[208:211], v[126:129]
	v_mfma_f32_16x16x32_bf16 v[122:125], v[156:159], v[208:211], v[122:125]
	v_mfma_f32_16x16x32_bf16 v[110:113], v[148:151], v[216:219], v[110:113]
	v_mfma_f32_16x16x32_bf16 v[106:109], v[156:159], v[216:219], v[106:109]
	v_mfma_f32_16x16x32_bf16 v[94:97], v[148:151], v[224:227], v[94:97]
	v_mfma_f32_16x16x32_bf16 v[90:93], v[156:159], v[224:227], v[90:93]
	v_mfma_f32_16x16x32_bf16 v[78:81], v[148:151], v[232:235], v[78:81]
	v_mfma_f32_16x16x32_bf16 v[74:77], v[156:159], v[232:235], v[74:77]
	s_setprio 0
	s_setprio 1
	v_mfma_f32_16x16x32_bf16 v[118:121], v[178:181], v[194:197], v[118:121]
	v_mfma_f32_16x16x32_bf16 v[114:117], v[186:189], v[194:197], v[114:117]
	v_mfma_f32_16x16x32_bf16 v[102:105], v[178:181], v[212:215], v[102:105]
	v_mfma_f32_16x16x32_bf16 v[98:101], v[186:189], v[212:215], v[98:101]
	v_mfma_f32_16x16x32_bf16 v[86:89], v[178:181], v[220:223], v[86:89]
	v_mfma_f32_16x16x32_bf16 v[82:85], v[186:189], v[220:223], v[82:85]
	v_mfma_f32_16x16x32_bf16 v[70:73], v[178:181], v[228:231], v[70:73]
	v_mfma_f32_16x16x32_bf16 v[66:69], v[186:189], v[228:231], v[66:69]
	v_mfma_f32_16x16x32_bf16 v[118:121], v[182:185], v[208:211], v[118:121]
	v_mfma_f32_16x16x32_bf16 v[114:117], v[190:193], v[208:211], v[114:117]
	v_mfma_f32_16x16x32_bf16 v[102:105], v[182:185], v[216:219], v[102:105]
	v_mfma_f32_16x16x32_bf16 v[98:101], v[190:193], v[216:219], v[98:101]
	v_mfma_f32_16x16x32_bf16 v[86:89], v[182:185], v[224:227], v[86:89]
	v_mfma_f32_16x16x32_bf16 v[82:85], v[190:193], v[224:227], v[82:85]
	v_mfma_f32_16x16x32_bf16 v[70:73], v[182:185], v[232:235], v[70:73]
	v_mfma_f32_16x16x32_bf16 v[66:69], v[190:193], v[232:235], v[66:69]
	s_setprio 0
	s_barrier
	s_add_i32 s18, s46, s28
	s_add_u32 s50, s16, 0x80
	s_addc_u32 s51, s17, 0
	s_mov_b32 m0, s18
	ds_read_b128 v[194:197], v147 offset:49152
	ds_read_b128 v[208:211], v147 offset:50176
	ds_read_b128 v[212:215], v147 offset:51200
	ds_read_b128 v[216:219], v147 offset:52224
	ds_read_b128 v[220:223], v147 offset:53248
	ds_read_b128 v[224:227], v147 offset:54272
	ds_read_b128 v[228:231], v147 offset:55296
	ds_read_b128 v[232:235], v147 offset:56320
	global_load_lds_dwordx4 v64, s[50:51]
	s_add_i32 m0, s18, 0x2000
	s_add_u32 s16, s16, 0x80080
	s_addc_u32 s17, s17, 0
	s_add_i32 s18, s47, s28
	global_load_lds_dwordx4 v130, s[50:51]
	s_mov_b32 m0, s18
	s_nop 0
	global_load_lds_dwordx4 v64, s[16:17]
	s_add_i32 m0, s18, 0x2000
	s_nop 0
	global_load_lds_dwordx4 v130, s[16:17]
	s_add_u32 s100, s100, 0x80
	s_addc_u32 s101, s101, 0
	s_mov_b32 m0, s31
	s_nop 0
	global_load_lds_dwordx4 v134, s[100:101]
	s_mov_b32 m0, s34
	s_nop 0
	global_load_lds_dwordx4 v132, s[100:101]
	s_waitcnt vmcnt(8)
	s_waitcnt lgkmcnt(0)
	s_barrier
	s_setprio 1
	s_waitcnt lgkmcnt(0)
	v_mfma_f32_16x16x32_bf16 v[60:63], v[140:143], v[194:197], v[60:63]
	v_mfma_f32_16x16x32_bf16 v[56:59], v[152:155], v[194:197], v[56:59]
	v_mfma_f32_16x16x32_bf16 v[44:47], v[140:143], v[212:215], v[44:47]
	v_mfma_f32_16x16x32_bf16 v[40:43], v[152:155], v[212:215], v[40:43]
	v_mfma_f32_16x16x32_bf16 v[28:31], v[140:143], v[220:223], v[28:31]
	v_mfma_f32_16x16x32_bf16 v[24:27], v[152:155], v[220:223], v[24:27]
	v_mfma_f32_16x16x32_bf16 v[12:15], v[140:143], v[228:231], v[12:15]
	v_mfma_f32_16x16x32_bf16 v[8:11], v[152:155], v[228:231], v[8:11]
	v_mfma_f32_16x16x32_bf16 v[60:63], v[148:151], v[208:211], v[60:63]
	v_mfma_f32_16x16x32_bf16 v[56:59], v[156:159], v[208:211], v[56:59]
	v_mfma_f32_16x16x32_bf16 v[44:47], v[148:151], v[216:219], v[44:47]
	v_mfma_f32_16x16x32_bf16 v[40:43], v[156:159], v[216:219], v[40:43]
	v_mfma_f32_16x16x32_bf16 v[28:31], v[148:151], v[224:227], v[28:31]
	v_mfma_f32_16x16x32_bf16 v[24:27], v[156:159], v[224:227], v[24:27]
	v_mfma_f32_16x16x32_bf16 v[12:15], v[148:151], v[232:235], v[12:15]
	v_mfma_f32_16x16x32_bf16 v[8:11], v[156:159], v[232:235], v[8:11]
	s_setprio 0
	s_setprio 1
	v_mfma_f32_16x16x32_bf16 v[52:55], v[178:181], v[194:197], v[52:55]
	v_mfma_f32_16x16x32_bf16 v[48:51], v[186:189], v[194:197], v[48:51]
	v_mfma_f32_16x16x32_bf16 v[36:39], v[178:181], v[212:215], v[36:39]
	v_mfma_f32_16x16x32_bf16 v[32:35], v[186:189], v[212:215], v[32:35]
	v_mfma_f32_16x16x32_bf16 v[20:23], v[178:181], v[220:223], v[20:23]
	v_mfma_f32_16x16x32_bf16 v[16:19], v[186:189], v[220:223], v[16:19]
	v_mfma_f32_16x16x32_bf16 v[4:7], v[178:181], v[228:231], v[4:7]
	v_mfma_f32_16x16x32_bf16 v[0:3], v[186:189], v[228:231], v[0:3]
	v_mfma_f32_16x16x32_bf16 v[52:55], v[182:185], v[208:211], v[52:55]
	v_mfma_f32_16x16x32_bf16 v[48:51], v[190:193], v[208:211], v[48:51]
	v_mfma_f32_16x16x32_bf16 v[36:39], v[182:185], v[216:219], v[36:39]
	v_mfma_f32_16x16x32_bf16 v[32:35], v[190:193], v[216:219], v[32:35]
	v_mfma_f32_16x16x32_bf16 v[20:23], v[182:185], v[224:227], v[20:23]
	v_mfma_f32_16x16x32_bf16 v[16:19], v[190:193], v[224:227], v[16:19]
	v_mfma_f32_16x16x32_bf16 v[4:7], v[182:185], v[232:235], v[4:7]
	v_mfma_f32_16x16x32_bf16 v[0:3], v[190:193], v[232:235], v[0:3]
	s_setprio 0
	s_barrier
	s_add_i32 s45, s45, 2
	s_add_u32 s0, s0, 0x100
	s_addc_u32 s1, s1, 0
	s_add_u32 s37, s37, 0x100
	s_addc_u32 s44, s44, 0
	s_cmp_gt_u32 s45, 29
	s_cbranch_scc0 .LBB0_1571
	s_mov_b64 s[50:51], 0x80
	s_and_b64 vcc, exec, s[4:5]
	s_cbranch_vccz .LBB0_1574
	s_barrier

;     __host__ __device__ bool next(int i, Unit& u) const { return tile((long)i * G + c, u); }
;     __host__ __device__ bool next(int i, Unit& u) const { if (!tile((long)(i / NZ) * G + c, u)) return false; u.z = i % NZ; return true; }
; #define PG8_STAGE(bufoff, gbase, voff) do { _Pragma("unroll") for (int _i = 0; _i < 2; ++_i) \
;         __builtin_amdgcn_global_load_lds((const unsigned*)((const char*)(gbase) + (voff)[_i]), (PG8_LAS unsigned*)(lds + (bufoff) + ldsw + _i * 8192), 16, 0, 0); } while (0)
; #define PG8_LDA(dst, b, h) do { _Pragma("unroll") for (int m = 0; m < 4; ++m) _Pragma("unroll") for (int k = 0; k < 2; ++k) dst[m][k] = *(const PG8_LAS bf16x8*)(lds + PG8_SA(b, h) + aoff + m * 2048 + k * 1024); } while (0)
; #define PG8_WAIT_V(n) asm volatile("s_waitcnt vmcnt(" #n ")" ::: "memory")
; #define PG8_WAIT_L(n) asm volatile("s_waitcnt lgkmcnt(" #n ")" ::: "memory")
; template <class Epi, class Sched, bool ALIGN_EPI = false, bool SP2 = false>
; __device__ __forceinline__ void gemm_phase(PG8_LAS unsigned char* lds, const Gemm g, const Sched& S, const Epi& E, const int wave0) {
;     ...
;         const bool has_next = S.next(ui + 1, nxt);
;         const char* nA = has_next ? (const char*)g.A + (size_t)nxt.z * g.zsA + (size_t)nxt.pm * tstepA + (size_t)nxt.k0 * 2 : cA; const char* nB = has_next ? (const char*)g.Bt + (size_t)nxt.z * g.zsB + (size_t)nxt.pn * tstepB + (size_t)nxt.k0 * 2 : cB;
;         for (int t = 0; t < nt; t += 2) {
;             const bool last = (t == nt - 2);
;             const char* a1 = cA + (size_t)(t + 1) * kstep;
;             const char* a2 = last ? nA : cA + (size_t)(t + 2) * kstep; const char* b2 = last ? nB : cB + (size_t)(t + 2) * kstep;
;             const char* a3 = a2 + kstep; const char* b3 = b2 + kstep;
;             if (last && has_next) S.a_ready(nxt);
;             if constexpr (SP2) {
;             PG8_LDB(B0, 0, 0); PG8_LDB(B1, 0, 1); PG8_SCHED; PG8_LDA(At, 0, 0); PG8_STAGE(PG8_SA(1, 1), a1 + hstepA, voffA);
;             PG8_WAIT_V(8); PG8_WAIT_L(0); PG8_BAR; PG8_MMA(0, 0, At, B0); PG8_MMA(0, 1, At, B1); PG8_BAR; PG8_SCHED;
;     ...
;         for (int a = 0; a < 2; ++a)
; #pragma unroll
;             for (int b = 0; b < 2; ++b)
; #pragma unroll
;                 for (int m = 0; m < 4; ++m)
; #pragma unroll
;                     for (int n = 0; n < 2; ++n) acc[a][b][m][n] = (f32x4){0.f, 0.f, 0.f, 0.f};
.LBB0_1684:
	s_ashr_i32 s11, s10, 31
	s_lshl_b64 s[12:13], s[10:11], 22
	v_readlane_b32 s14, v246, 44
	v_readlane_b32 s15, v246, 45
	s_add_u32 s12, s14, s12
	s_addc_u32 s13, s15, s13
	s_and_b64 s[14:15], s[2:3], exec
	s_cselect_b32 s11, s13, s1
	s_cselect_b32 s34, s12, s0
	s_ashr_i32 s9, s8, 31
	s_lshl_b64 s[14:15], s[8:9], 22
	s_add_u32 s14, s23, s14
	s_addc_u32 s15, s24, s15
	s_and_b64 s[18:19], s[2:3], exec
	s_cselect_b32 s9, s15, s17
	s_cselect_b32 s35, s14, s16
	s_add_u32 s0, s0, 0x200080
	s_addc_u32 s1, s1, 0
	s_add_u32 s36, s16, 0x100
	v_mov_b32_e32 v0, 0
	s_addc_u32 s37, s17, 0
	s_mov_b32 s42, -2
	v_mov_b32_e32 v1, v0
	v_mov_b64_e32 v[2:3], 0
	v_mov_b64_e32 v[4:5], 0
	v_mov_b64_e32 v[6:7], 0
	v_mov_b64_e32 v[8:9], 0
	v_mov_b64_e32 v[10:11], 0
	v_mov_b64_e32 v[12:13], 0
	v_mov_b64_e32 v[14:15], 0
	v_mov_b64_e32 v[24:25], 0
	v_mov_b64_e32 v[26:27], 0
	v_mov_b64_e32 v[28:29], 0
	v_mov_b64_e32 v[30:31], 0
	v_mov_b64_e32 v[40:41], 0
	v_mov_b64_e32 v[42:43], 0
	v_mov_b64_e32 v[44:45], 0
	v_mov_b64_e32 v[46:47], 0
	v_mov_b64_e32 v[16:17], 0
	v_mov_b64_e32 v[18:19], 0
	v_mov_b64_e32 v[20:21], 0
	v_mov_b64_e32 v[22:23], 0
	v_mov_b64_e32 v[32:33], 0
	v_mov_b64_e32 v[34:35], 0
	v_mov_b64_e32 v[36:37], 0
	v_mov_b64_e32 v[38:39], 0
	v_mov_b64_e32 v[48:49], 0
	v_mov_b64_e32 v[50:51], 0
	v_mov_b64_e32 v[52:53], 0
	v_mov_b64_e32 v[54:55], 0
	v_mov_b64_e32 v[56:57], 0
	v_mov_b64_e32 v[58:59], 0
	v_mov_b64_e32 v[60:61], 0
	v_mov_b64_e32 v[62:63], 0
	v_mov_b64_e32 v[66:67], 0
	v_mov_b64_e32 v[68:69], 0
	v_mov_b64_e32 v[70:71], 0
	v_mov_b64_e32 v[72:73], 0
	v_mov_b64_e32 v[74:75], 0
	v_mov_b64_e32 v[76:77], 0
	v_mov_b64_e32 v[78:79], 0
	v_mov_b64_e32 v[80:81], 0
	v_mov_b64_e32 v[90:91], 0
	v_mov_b64_e32 v[92:93], 0
	v_mov_b64_e32 v[94:95], 0
	v_mov_b64_e32 v[96:97], 0
	v_mov_b64_e32 v[106:107], 0
	v_mov_b64_e32 v[108:109], 0
	v_mov_b64_e32 v[110:111], 0
	v_mov_b64_e32 v[112:113], 0
	v_mov_b64_e32 v[82:83], 0
	v_mov_b64_e32 v[84:85], 0
	v_mov_b64_e32 v[86:87], 0
	v_mov_b64_e32 v[88:89], 0
	v_mov_b64_e32 v[98:99], 0
	v_mov_b64_e32 v[100:101], 0
	v_mov_b64_e32 v[102:103], 0
	v_mov_b64_e32 v[104:105], 0
	v_mov_b64_e32 v[114:115], 0
	v_mov_b64_e32 v[116:117], 0
	v_mov_b64_e32 v[118:119], 0
	v_mov_b64_e32 v[120:121], 0
	v_mov_b64_e32 v[122:123], 0
	v_mov_b64_e32 v[124:125], 0
	v_mov_b64_e32 v[126:127], 0
	v_mov_b64_e32 v[128:129], 0
	s_mov_b64 s[48:49], 0x80
	v_add_u32_e32 v252, 0x10000, v141
	v_add_u32_e32 v253, 0x14000, v141
	v_add_u32_e32 v254, 0x18000, v141
	v_add_u32_e32 v255, 0x1c000, v141
.LBB0_1685:
	s_add_u32 s16, s0, 0xffe00080
	s_addc_u32 s17, s1, -1
	s_add_i32 s43, 0, 0x10000
	s_cmpk_eq_i32 s42, 0x7c
	s_cselect_b32 s19, s11, s17
	s_cselect_b32 s18, s34, s16
	s_cselect_b32 s17, s9, s37
	s_cselect_b32 s16, s35, s36
	s_add_i32 s46, 0, 0x14000
	ds_read_b128 v[144:147], v252
	ds_read_b128 v[148:151], v252 offset:1024
	ds_read_b128 v[152:155], v252 offset:2048
	ds_read_b128 v[156:159], v252 offset:3072
	ds_read_b128 v[178:181], v253
	ds_read_b128 v[182:185], v253 offset:1024
	ds_read_b128 v[186:189], v253 offset:2048
	ds_read_b128 v[190:193], v253 offset:3072
	s_add_i32 m0, s21, 0xc000
	ds_read_b128 v[194:197], v143
	ds_read_b128 v[208:211], v143 offset:1024
	ds_read_b128 v[212:215], v143 offset:2048
	ds_read_b128 v[216:219], v143 offset:3072
	ds_read_b128 v[220:223], v143 offset:4096
	ds_read_b128 v[224:227], v143 offset:5120
	ds_read_b128 v[228:231], v143 offset:6144
	ds_read_b128 v[232:235], v143 offset:7168
	global_load_lds_dwordx4 v136, s[0:1]
	s_add_i32 m0, s21, 0xe000
	s_nop 0
	global_load_lds_dwordx4 v138, s[0:1]
	s_waitcnt vmcnt(8)
	s_waitcnt lgkmcnt(0)
	s_barrier
	s_setprio 1
	s_waitcnt lgkmcnt(0)
	v_mfma_f32_16x16x32_bf16 v[126:129], v[144:147], v[194:197], v[126:129]
	v_mfma_f32_16x16x32_bf16 v[122:125], v[152:155], v[194:197], v[122:125]
	v_mfma_f32_16x16x32_bf16 v[118:121], v[144:147], v[212:215], v[118:121]
	v_mfma_f32_16x16x32_bf16 v[114:117], v[152:155], v[212:215], v[114:117]
	v_mfma_f32_16x16x32_bf16 v[102:105], v[144:147], v[220:223], v[102:105]
	v_mfma_f32_16x16x32_bf16 v[98:101], v[152:155], v[220:223], v[98:101]
	v_mfma_f32_16x16x32_bf16 v[86:89], v[144:147], v[228:231], v[86:89]
	v_mfma_f32_16x16x32_bf16 v[82:85], v[152:155], v[228:231], v[82:85]
	v_mfma_f32_16x16x32_bf16 v[126:129], v[148:151], v[208:211], v[126:129]
	v_mfma_f32_16x16x32_bf16 v[122:125], v[156:159], v[208:211], v[122:125]
	v_mfma_f32_16x16x32_bf16 v[118:121], v[148:151], v[216:219], v[118:121]
	v_mfma_f32_16x16x32_bf16 v[114:117], v[156:159], v[216:219], v[114:117]
	v_mfma_f32_16x16x32_bf16 v[102:105], v[148:151], v[224:227], v[102:105]
	v_mfma_f32_16x16x32_bf16 v[98:101], v[156:159], v[224:227], v[98:101]
	v_mfma_f32_16x16x32_bf16 v[86:89], v[148:151], v[232:235], v[86:89]
	v_mfma_f32_16x16x32_bf16 v[82:85], v[156:159], v[232:235], v[82:85]
	s_setprio 0
	s_setprio 1
	v_mfma_f32_16x16x32_bf16 v[110:113], v[178:181], v[194:197], v[110:113]
	v_mfma_f32_16x16x32_bf16 v[106:109], v[186:189], v[194:197], v[106:109]
	v_mfma_f32_16x16x32_bf16 v[94:97], v[178:181], v[212:215], v[94:97]
	v_mfma_f32_16x16x32_bf16 v[90:93], v[186:189], v[212:215], v[90:93]
	v_mfma_f32_16x16x32_bf16 v[78:81], v[178:181], v[220:223], v[78:81]
	v_mfma_f32_16x16x32_bf16 v[74:77], v[186:189], v[220:223], v[74:77]
	v_mfma_f32_16x16x32_bf16 v[70:73], v[178:181], v[228:231], v[70:73]
	v_mfma_f32_16x16x32_bf16 v[66:69], v[186:189], v[228:231], v[66:69]
	v_mfma_f32_16x16x32_bf16 v[110:113], v[182:185], v[208:211], v[110:113]
	v_mfma_f32_16x16x32_bf16 v[106:109], v[190:193], v[208:211], v[106:109]
	v_mfma_f32_16x16x32_bf16 v[94:97], v[182:185], v[216:219], v[94:97]
	v_mfma_f32_16x16x32_bf16 v[90:93], v[190:193], v[216:219], v[90:93]
	v_mfma_f32_16x16x32_bf16 v[78:81], v[182:185], v[224:227], v[78:81]
	v_mfma_f32_16x16x32_bf16 v[74:77], v[190:193], v[224:227], v[74:77]
	v_mfma_f32_16x16x32_bf16 v[70:73], v[182:185], v[232:235], v[70:73]
	v_mfma_f32_16x16x32_bf16 v[66:69], v[190:193], v[232:235], v[66:69]
	s_setprio 0
	s_barrier
; #define PG8_STAGE(bufoff, gbase, voff) do { _Pragma("unroll") for (int _i = 0; _i < 2; ++_i) \
;         __builtin_amdgcn_global_load_lds((const unsigned*)((const char*)(gbase) + (voff)[_i]), (PG8_LAS unsigned*)(lds + (bufoff) + ldsw + _i * 8192), 16, 0, 0); } while (0)
; #define PG8_LDA(dst, b, h) do { _Pragma("unroll") for (int m = 0; m < 4; ++m) _Pragma("unroll") for (int k = 0; k < 2; ++k) dst[m][k] = *(const PG8_LAS bf16x8*)(lds + PG8_SA(b, h) + aoff + m * 2048 + k * 1024); } while (0)
; #define PG8_LDB(dst, b, h) do { _Pragma("unroll") for (int n = 0; n < 2; ++n) _Pragma("unroll") for (int k = 0; k < 2; ++k) dst[n][k] = *(const PG8_LAS bf16x8*)(lds + PG8_SB(b, h) + boff + n * 2048 + k * 1024); } while (0)
; #define PG8_MMA(ai, bj, At, Bt) do { __builtin_amdgcn_s_setprio(1); _Pragma("unroll") for (int m = 0; m < 4; ++m) _Pragma("unroll") for (int n = 0; n < 2; ++n) _Pragma("unroll") for (int k = 0; k < 2; ++k) \
;         acc[ai][bj][m][n] = __builtin_amdgcn_mfma_f32_16x16x32_bf16(Bt[n][k], At[m][k], acc[ai][bj][m][n], 0, 0, 0); __builtin_amdgcn_s_setprio(0); } while (0)
; #define PG8_WAIT_V(n) asm volatile("s_waitcnt vmcnt(" #n ")" ::: "memory")
; #define PG8_WAIT_L(n) asm volatile("s_waitcnt lgkmcnt(" #n ")" ::: "memory")
; #define PG8_BAR __builtin_amdgcn_s_barrier()
; #define PG8_SCHED __builtin_amdgcn_sched_barrier(0)
; template <class Epi, class Sched, bool ALIGN_EPI = false, bool SP2 = false>
; __device__ __forceinline__ void gemm_phase(PG8_LAS unsigned char* lds, const Gemm g, const Sched& S, const Epi& E, const int wave0) {
;     ...
;             PG8_LDA(At, 0, 1); PG8_STAGE(PG8_SB(0, 0), b2, voffB); PG8_STAGE(PG8_SB(0, 1), b2 + hstepB, voffB); PG8_STAGE(PG8_SA(0, 0), a2, voffA);
;             PG8_WAIT_V(8); PG8_WAIT_L(0); PG8_BAR; PG8_MMA(1, 0, At, B0); PG8_MMA(1, 1, At, B1); PG8_BAR; PG8_SCHED;
;             PG8_LDB(B0, 1, 0); PG8_LDB(B1, 1, 1); PG8_SCHED; PG8_LDA(At, 1, 0); PG8_STAGE(PG8_SA(0, 1), a2 + hstepA, voffA);
	s_add_i32 s43, s43, s20
	s_mov_b32 m0, s43
	ds_read_b128 v[194:197], v143 offset:16384
	ds_read_b128 v[208:211], v143 offset:17408
	ds_read_b128 v[212:215], v143 offset:18432
	ds_read_b128 v[216:219], v143 offset:19456
	ds_read_b128 v[220:223], v143 offset:20480
	ds_read_b128 v[224:227], v143 offset:21504
	ds_read_b128 v[228:231], v143 offset:22528
	ds_read_b128 v[232:235], v143 offset:23552
	global_load_lds_dwordx4 v64, s[16:17]
	s_add_i32 m0, s43, 0x2000
	s_add_u32 s44, s16, 0x200000
	s_addc_u32 s45, s17, 0
	s_add_i32 s43, s46, s20
	global_load_lds_dwordx4 v130, s[16:17]
	s_mov_b32 m0, s43
	s_mov_b64 s[100:101], s[18:19]
	global_load_lds_dwordx4 v64, s[44:45]
	s_add_i32 m0, s43, 0x2000
	s_nop 0
	global_load_lds_dwordx4 v130, s[44:45]
	s_mov_b32 m0, s21
	s_nop 0
	global_load_lds_dwordx4 v134, s[18:19]
	s_mov_b32 m0, s25
	s_nop 0
	global_load_lds_dwordx4 v132, s[18:19]
	s_waitcnt vmcnt(8)
	s_waitcnt lgkmcnt(0)
	s_barrier
	s_setprio 1
	s_waitcnt lgkmcnt(0)
	v_mfma_f32_16x16x32_bf16 v[60:63], v[144:147], v[194:197], v[60:63]
	v_mfma_f32_16x16x32_bf16 v[56:59], v[152:155], v[194:197], v[56:59]
	v_mfma_f32_16x16x32_bf16 v[52:55], v[144:147], v[212:215], v[52:55]
	v_mfma_f32_16x16x32_bf16 v[48:51], v[152:155], v[212:215], v[48:51]
	v_mfma_f32_16x16x32_bf16 v[36:39], v[144:147], v[220:223], v[36:39]
	v_mfma_f32_16x16x32_bf16 v[32:35], v[152:155], v[220:223], v[32:35]
	v_mfma_f32_16x16x32_bf16 v[20:23], v[144:147], v[228:231], v[20:23]
	v_mfma_f32_16x16x32_bf16 v[16:19], v[152:155], v[228:231], v[16:19]
	v_mfma_f32_16x16x32_bf16 v[60:63], v[148:151], v[208:211], v[60:63]
	v_mfma_f32_16x16x32_bf16 v[56:59], v[156:159], v[208:211], v[56:59]
	v_mfma_f32_16x16x32_bf16 v[52:55], v[148:151], v[216:219], v[52:55]
	v_mfma_f32_16x16x32_bf16 v[48:51], v[156:159], v[216:219], v[48:51]
	v_mfma_f32_16x16x32_bf16 v[36:39], v[148:151], v[224:227], v[36:39]
	v_mfma_f32_16x16x32_bf16 v[32:35], v[156:159], v[224:227], v[32:35]
	v_mfma_f32_16x16x32_bf16 v[20:23], v[148:151], v[232:235], v[20:23]
	v_mfma_f32_16x16x32_bf16 v[16:19], v[156:159], v[232:235], v[16:19]
	s_setprio 0
	s_setprio 1
	v_mfma_f32_16x16x32_bf16 v[44:47], v[178:181], v[194:197], v[44:47]
	v_mfma_f32_16x16x32_bf16 v[40:43], v[186:189], v[194:197], v[40:43]
	v_mfma_f32_16x16x32_bf16 v[28:31], v[178:181], v[212:215], v[28:31]
	v_mfma_f32_16x16x32_bf16 v[24:27], v[186:189], v[212:215], v[24:27]
	v_mfma_f32_16x16x32_bf16 v[12:15], v[178:181], v[220:223], v[12:15]
	v_mfma_f32_16x16x32_bf16 v[8:11], v[186:189], v[220:223], v[8:11]
	v_mfma_f32_16x16x32_bf16 v[4:7], v[178:181], v[228:231], v[4:7]
	v_mfma_f32_16x16x32_bf16 v[0:3], v[186:189], v[228:231], v[0:3]
	v_mfma_f32_16x16x32_bf16 v[44:47], v[182:185], v[208:211], v[44:47]
	v_mfma_f32_16x16x32_bf16 v[40:43], v[190:193], v[208:211], v[40:43]
	v_mfma_f32_16x16x32_bf16 v[28:31], v[182:185], v[216:219], v[28:31]
	v_mfma_f32_16x16x32_bf16 v[24:27], v[190:193], v[216:219], v[24:27]
	v_mfma_f32_16x16x32_bf16 v[12:15], v[182:185], v[224:227], v[12:15]
	v_mfma_f32_16x16x32_bf16 v[8:11], v[190:193], v[224:227], v[8:11]
	v_mfma_f32_16x16x32_bf16 v[4:7], v[182:185], v[232:235], v[4:7]
	v_mfma_f32_16x16x32_bf16 v[0:3], v[190:193], v[232:235], v[0:3]
	s_setprio 0
	s_barrier
	s_add_i32 s43, 0, 0x18000
	s_add_i32 s44, 0, 0x1c000
	ds_read_b128 v[144:147], v254
	ds_read_b128 v[148:151], v254 offset:1024
	ds_read_b128 v[152:155], v254 offset:2048
	ds_read_b128 v[156:159], v254 offset:3072
	ds_read_b128 v[178:181], v255
	ds_read_b128 v[182:185], v255 offset:1024
	ds_read_b128 v[186:189], v255 offset:2048
	ds_read_b128 v[190:193], v255 offset:3072
	s_add_u32 s18, s18, 0x200000
	s_addc_u32 s19, s19, 0
	s_mov_b32 m0, s26
	ds_read_b128 v[194:197], v143 offset:32768
	ds_read_b128 v[208:211], v143 offset:33792
	ds_read_b128 v[212:215], v143 offset:34816
	ds_read_b128 v[216:219], v143 offset:35840
	ds_read_b128 v[220:223], v143 offset:36864
	ds_read_b128 v[224:227], v143 offset:37888
	ds_read_b128 v[228:231], v143 offset:38912
	ds_read_b128 v[232:235], v143 offset:39936
	global_load_lds_dwordx4 v134, s[18:19]
	s_mov_b32 m0, s27
	s_nop 0
	global_load_lds_dwordx4 v132, s[18:19]
	s_waitcnt vmcnt(8)
	s_waitcnt lgkmcnt(0)
	s_barrier
; #define PG8_STAGE(bufoff, gbase, voff) do { _Pragma("unroll") for (int _i = 0; _i < 2; ++_i) \
;         __builtin_amdgcn_global_load_lds((const unsigned*)((const char*)(gbase) + (voff)[_i]), (PG8_LAS unsigned*)(lds + (bufoff) + ldsw + _i * 8192), 16, 0, 0); } while (0)
; #define PG8_LDA(dst, b, h) do { _Pragma("unroll") for (int m = 0; m < 4; ++m) _Pragma("unroll") for (int k = 0; k < 2; ++k) dst[m][k] = *(const PG8_LAS bf16x8*)(lds + PG8_SA(b, h) + aoff + m * 2048 + k * 1024); } while (0)
; #define PG8_MMA(ai, bj, At, Bt) do { __builtin_amdgcn_s_setprio(1); _Pragma("unroll") for (int m = 0; m < 4; ++m) _Pragma("unroll") for (int n = 0; n < 2; ++n) _Pragma("unroll") for (int k = 0; k < 2; ++k) \
;         acc[ai][bj][m][n] = __builtin_amdgcn_mfma_f32_16x16x32_bf16(Bt[n][k], At[m][k], acc[ai][bj][m][n], 0, 0, 0); __builtin_amdgcn_s_setprio(0); } while (0)
; #define PG8_WAIT_V(n) asm volatile("s_waitcnt vmcnt(" #n ")" ::: "memory")
; #define PG8_WAIT_L(n) asm volatile("s_waitcnt lgkmcnt(" #n ")" ::: "memory")
; #define PG8_BAR __builtin_amdgcn_s_barrier()
; #define PG8_SCHED __builtin_amdgcn_sched_barrier(0)
; template <class Epi, class Sched, bool ALIGN_EPI = false, bool SP2 = false>
; __device__ __forceinline__ void gemm_phase(PG8_LAS unsigned char* lds, const Gemm g, const Sched& S, const Epi& E, const int wave0) {
;     ...
;             PG8_WAIT_V(8); PG8_WAIT_L(0); PG8_BAR; PG8_MMA(0, 0, At, B0); PG8_MMA(0, 1, At, B1); PG8_BAR; PG8_SCHED;
;             PG8_LDA(At, 1, 1); PG8_STAGE(PG8_SB(1, 0), b3, voffB); PG8_STAGE(PG8_SB(1, 1), b3 + hstepB, voffB); PG8_STAGE(PG8_SA(1, 0), a3, voffA);
;             PG8_WAIT_V(8); PG8_WAIT_L(0); PG8_BAR; PG8_MMA(1, 0, At, B0); PG8_MMA(1, 1, At, B1); PG8_BAR; PG8_SCHED;
	s_setprio 1
	s_waitcnt lgkmcnt(0)
	v_mfma_f32_16x16x32_bf16 v[126:129], v[144:147], v[194:197], v[126:129]
	v_mfma_f32_16x16x32_bf16 v[122:125], v[152:155], v[194:197], v[122:125]
	v_mfma_f32_16x16x32_bf16 v[118:121], v[144:147], v[212:215], v[118:121]
	v_mfma_f32_16x16x32_bf16 v[114:117], v[152:155], v[212:215], v[114:117]
	v_mfma_f32_16x16x32_bf16 v[102:105], v[144:147], v[220:223], v[102:105]
	v_mfma_f32_16x16x32_bf16 v[98:101], v[152:155], v[220:223], v[98:101]
	v_mfma_f32_16x16x32_bf16 v[86:89], v[144:147], v[228:231], v[86:89]
	v_mfma_f32_16x16x32_bf16 v[82:85], v[152:155], v[228:231], v[82:85]
	v_mfma_f32_16x16x32_bf16 v[126:129], v[148:151], v[208:211], v[126:129]
	v_mfma_f32_16x16x32_bf16 v[122:125], v[156:159], v[208:211], v[122:125]
	v_mfma_f32_16x16x32_bf16 v[118:121], v[148:151], v[216:219], v[118:121]
	v_mfma_f32_16x16x32_bf16 v[114:117], v[156:159], v[216:219], v[114:117]
	v_mfma_f32_16x16x32_bf16 v[102:105], v[148:151], v[224:227], v[102:105]
	v_mfma_f32_16x16x32_bf16 v[98:101], v[156:159], v[224:227], v[98:101]
	v_mfma_f32_16x16x32_bf16 v[86:89], v[148:151], v[232:235], v[86:89]
	v_mfma_f32_16x16x32_bf16 v[82:85], v[156:159], v[232:235], v[82:85]
	s_setprio 0
	s_setprio 1
	v_mfma_f32_16x16x32_bf16 v[110:113], v[178:181], v[194:197], v[110:113]
	v_mfma_f32_16x16x32_bf16 v[106:109], v[186:189], v[194:197], v[106:109]
	v_mfma_f32_16x16x32_bf16 v[94:97], v[178:181], v[212:215], v[94:97]
	v_mfma_f32_16x16x32_bf16 v[90:93], v[186:189], v[212:215], v[90:93]
	v_mfma_f32_16x16x32_bf16 v[78:81], v[178:181], v[220:223], v[78:81]
	v_mfma_f32_16x16x32_bf16 v[74:77], v[186:189], v[220:223], v[74:77]
	v_mfma_f32_16x16x32_bf16 v[70:73], v[178:181], v[228:231], v[70:73]
	v_mfma_f32_16x16x32_bf16 v[66:69], v[186:189], v[228:231], v[66:69]
	v_mfma_f32_16x16x32_bf16 v[110:113], v[182:185], v[208:211], v[110:113]
	v_mfma_f32_16x16x32_bf16 v[106:109], v[190:193], v[208:211], v[106:109]
	v_mfma_f32_16x16x32_bf16 v[94:97], v[182:185], v[216:219], v[94:97]
	v_mfma_f32_16x16x32_bf16 v[90:93], v[190:193], v[216:219], v[90:93]
	v_mfma_f32_16x16x32_bf16 v[78:81], v[182:185], v[224:227], v[78:81]
	v_mfma_f32_16x16x32_bf16 v[74:77], v[190:193], v[224:227], v[74:77]
	v_mfma_f32_16x16x32_bf16 v[70:73], v[182:185], v[232:235], v[70:73]
	v_mfma_f32_16x16x32_bf16 v[66:69], v[190:193], v[232:235], v[66:69]
	s_setprio 0
	s_barrier
	s_add_i32 s18, s43, s20
	s_add_u32 s48, s16, 0x80
	s_addc_u32 s49, s17, 0
	s_mov_b32 m0, s18
	ds_read_b128 v[194:197], v143 offset:49152
	ds_read_b128 v[208:211], v143 offset:50176
	ds_read_b128 v[212:215], v143 offset:51200
	ds_read_b128 v[216:219], v143 offset:52224
	ds_read_b128 v[220:223], v143 offset:53248
	ds_read_b128 v[224:227], v143 offset:54272
	ds_read_b128 v[228:231], v143 offset:55296
	ds_read_b128 v[232:235], v143 offset:56320
	global_load_lds_dwordx4 v64, s[48:49]
	s_add_i32 m0, s18, 0x2000
	s_add_u32 s16, s16, 0x200080
	s_addc_u32 s17, s17, 0
	s_add_i32 s18, s44, s20
	global_load_lds_dwordx4 v130, s[48:49]
	s_mov_b32 m0, s18
	s_nop 0
	global_load_lds_dwordx4 v64, s[16:17]
	s_add_i32 m0, s18, 0x2000
	s_nop 0
	global_load_lds_dwordx4 v130, s[16:17]
	s_add_u32 s100, s100, 0x80
	s_addc_u32 s101, s101, 0
	s_mov_b32 m0, s28
	s_nop 0
	global_load_lds_dwordx4 v134, s[100:101]
	s_mov_b32 m0, s29
	s_nop 0
	global_load_lds_dwordx4 v132, s[100:101]
	s_waitcnt vmcnt(8)
	s_waitcnt lgkmcnt(0)
	s_barrier
	s_setprio 1
	s_waitcnt lgkmcnt(0)
	v_mfma_f32_16x16x32_bf16 v[60:63], v[144:147], v[194:197], v[60:63]
	v_mfma_f32_16x16x32_bf16 v[56:59], v[152:155], v[194:197], v[56:59]
	v_mfma_f32_16x16x32_bf16 v[52:55], v[144:147], v[212:215], v[52:55]
	v_mfma_f32_16x16x32_bf16 v[48:51], v[152:155], v[212:215], v[48:51]
	v_mfma_f32_16x16x32_bf16 v[36:39], v[144:147], v[220:223], v[36:39]
	v_mfma_f32_16x16x32_bf16 v[32:35], v[152:155], v[220:223], v[32:35]
	v_mfma_f32_16x16x32_bf16 v[20:23], v[144:147], v[228:231], v[20:23]
	v_mfma_f32_16x16x32_bf16 v[16:19], v[152:155], v[228:231], v[16:19]
	v_mfma_f32_16x16x32_bf16 v[60:63], v[148:151], v[208:211], v[60:63]
	v_mfma_f32_16x16x32_bf16 v[56:59], v[156:159], v[208:211], v[56:59]
	v_mfma_f32_16x16x32_bf16 v[52:55], v[148:151], v[216:219], v[52:55]
	v_mfma_f32_16x16x32_bf16 v[48:51], v[156:159], v[216:219], v[48:51]
	v_mfma_f32_16x16x32_bf16 v[36:39], v[148:151], v[224:227], v[36:39]
	v_mfma_f32_16x16x32_bf16 v[32:35], v[156:159], v[224:227], v[32:35]
	v_mfma_f32_16x16x32_bf16 v[20:23], v[148:151], v[232:235], v[20:23]
	v_mfma_f32_16x16x32_bf16 v[16:19], v[156:159], v[232:235], v[16:19]
	s_setprio 0
	s_setprio 1
	v_mfma_f32_16x16x32_bf16 v[44:47], v[178:181], v[194:197], v[44:47]
	v_mfma_f32_16x16x32_bf16 v[40:43], v[186:189], v[194:197], v[40:43]
	v_mfma_f32_16x16x32_bf16 v[28:31], v[178:181], v[212:215], v[28:31]
	v_mfma_f32_16x16x32_bf16 v[24:27], v[186:189], v[212:215], v[24:27]
	v_mfma_f32_16x16x32_bf16 v[12:15], v[178:181], v[220:223], v[12:15]
	v_mfma_f32_16x16x32_bf16 v[8:11], v[186:189], v[220:223], v[8:11]
	v_mfma_f32_16x16x32_bf16 v[4:7], v[178:181], v[228:231], v[4:7]
	v_mfma_f32_16x16x32_bf16 v[0:3], v[186:189], v[228:231], v[0:3]
	v_mfma_f32_16x16x32_bf16 v[44:47], v[182:185], v[208:211], v[44:47]
	v_mfma_f32_16x16x32_bf16 v[40:43], v[190:193], v[208:211], v[40:43]
	v_mfma_f32_16x16x32_bf16 v[28:31], v[182:185], v[216:219], v[28:31]
	v_mfma_f32_16x16x32_bf16 v[24:27], v[190:193], v[216:219], v[24:27]
	v_mfma_f32_16x16x32_bf16 v[12:15], v[182:185], v[224:227], v[12:15]
	v_mfma_f32_16x16x32_bf16 v[8:11], v[190:193], v[224:227], v[8:11]
	v_mfma_f32_16x16x32_bf16 v[4:7], v[182:185], v[232:235], v[4:7]
	v_mfma_f32_16x16x32_bf16 v[0:3], v[190:193], v[232:235], v[0:3]
	s_setprio 0
	s_barrier
	s_add_i32 s42, s42, 2
	s_add_u32 s0, s0, 0x100
	s_addc_u32 s1, s1, 0
	s_add_u32 s36, s36, 0x100
	s_addc_u32 s37, s37, 0
	s_cmpk_gt_u32 s42, 0x7d
	s_cbranch_scc0 .LBB0_1685
	s_mov_b64 s[48:49], 0x80
	s_and_b64 vcc, exec, s[6:7]
	s_mov_b64 s[34:35], 0x45000
	s_cbranch_vccz .LBB0_1688
	s_barrier

;     __host__ __device__ bool next(int i, Unit& u) const { return tile((long)i * G + c, u); }
;     __host__ __device__ bool next(int i, Unit& u) const { if (!tile((long)(i / NZ) * G + c, u)) return false; u.z = i % NZ; return true; }
; #define PG8_STAGE(bufoff, gbase, voff) do { _Pragma("unroll") for (int _i = 0; _i < 2; ++_i) \
;         __builtin_amdgcn_global_load_lds((const unsigned*)((const char*)(gbase) + (voff)[_i]), (PG8_LAS unsigned*)(lds + (bufoff) + ldsw + _i * 8192), 16, 0, 0); } while (0)
; #define PG8_LDA(dst, b, h) do { _Pragma("unroll") for (int m = 0; m < 4; ++m) _Pragma("unroll") for (int k = 0; k < 2; ++k) dst[m][k] = *(const PG8_LAS bf16x8*)(lds + PG8_SA(b, h) + aoff + m * 2048 + k * 1024); } while (0)
; #define PG8_WAIT_V(n) asm volatile("s_waitcnt vmcnt(" #n ")" ::: "memory")
; #define PG8_WAIT_L(n) asm volatile("s_waitcnt lgkmcnt(" #n ")" ::: "memory")
; template <class Epi, class Sched, bool ALIGN_EPI = false, bool SP2 = false>
; __device__ __forceinline__ void gemm_phase(PG8_LAS unsigned char* lds, const Gemm g, const Sched& S, const Epi& E, const int wave0) {
;     ...
;         const bool has_next = S.next(ui + 1, nxt);
;         const char* nA = has_next ? (const char*)g.A + (size_t)nxt.z * g.zsA + (size_t)nxt.pm * tstepA + (size_t)nxt.k0 * 2 : cA; const char* nB = has_next ? (const char*)g.Bt + (size_t)nxt.z * g.zsB + (size_t)nxt.pn * tstepB + (size_t)nxt.k0 * 2 : cB;
;         for (int t = 0; t < nt; t += 2) {
;             const bool last = (t == nt - 2);
;             const char* a1 = cA + (size_t)(t + 1) * kstep;
;             const char* a2 = last ? nA : cA + (size_t)(t + 2) * kstep; const char* b2 = last ? nB : cB + (size_t)(t + 2) * kstep;
;             const char* a3 = a2 + kstep; const char* b3 = b2 + kstep;
;             if (last && has_next) S.a_ready(nxt);
;             if constexpr (SP2) {
;             PG8_LDB(B0, 0, 0); PG8_LDB(B1, 0, 1); PG8_SCHED; PG8_LDA(At, 0, 0); PG8_STAGE(PG8_SA(1, 1), a1 + hstepA, voffA);
;             PG8_WAIT_V(8); PG8_WAIT_L(0); PG8_BAR; PG8_MMA(0, 0, At, B0); PG8_MMA(0, 1, At, B1); PG8_BAR; PG8_SCHED;
;     ...
;         for (int a = 0; a < 2; ++a)
; #pragma unroll
;             for (int b = 0; b < 2; ++b)
; #pragma unroll
;                 for (int m = 0; m < 4; ++m)
; #pragma unroll
;                     for (int n = 0; n < 2; ++n) acc[a][b][m][n] = (f32x4){0.f, 0.f, 0.f, 0.f};
.LBB0_1701:
	s_ashr_i32 s9, s8, 31
	s_lshl_b64 s[14:15], s[8:9], 22
	v_readlane_b32 s20, v246, 44
	v_readlane_b32 s21, v246, 45
	s_add_u32 s9, s20, s14
	s_addc_u32 s13, s21, s15
	s_ashr_i32 s11, s10, 31
	s_lshl_b64 s[20:21], s[10:11], 1
	s_add_u32 s14, s9, s20
	s_addc_u32 s15, s13, s21
	s_and_b64 s[26:27], s[2:3], exec
	s_cselect_b32 s9, s15, s17
	s_cselect_b32 s11, s14, s16
	s_ashr_i32 s13, s12, 31
	s_lshl_b64 s[26:27], s[12:13], 22
	s_add_u32 s13, s23, s26
	s_addc_u32 s27, s24, s27
	s_add_u32 s26, s13, s20
	s_addc_u32 s27, s27, s21
	s_and_b64 s[20:21], s[2:3], exec
	s_cselect_b32 s13, s27, s19
	s_cselect_b32 s38, s26, s18
	s_add_u32 s16, s16, 0x200080
	s_addc_u32 s17, s17, 0
	s_add_u32 s39, s18, 0x100
	v_mov_b32_e32 v0, 0
	s_addc_u32 s42, s19, 0
	s_mov_b32 s43, -2
	v_mov_b32_e32 v1, v0
	v_mov_b64_e32 v[2:3], 0
	v_mov_b64_e32 v[4:5], 0
	v_mov_b64_e32 v[6:7], 0
	v_mov_b64_e32 v[8:9], 0
	v_mov_b64_e32 v[10:11], 0
	v_mov_b64_e32 v[12:13], 0
	v_mov_b64_e32 v[14:15], 0
	v_mov_b64_e32 v[24:25], 0
	v_mov_b64_e32 v[26:27], 0
	v_mov_b64_e32 v[28:29], 0
	v_mov_b64_e32 v[30:31], 0
	v_mov_b64_e32 v[40:41], 0
	v_mov_b64_e32 v[42:43], 0
	v_mov_b64_e32 v[44:45], 0
	v_mov_b64_e32 v[46:47], 0
	v_mov_b64_e32 v[16:17], 0
	v_mov_b64_e32 v[18:19], 0
	v_mov_b64_e32 v[20:21], 0
	v_mov_b64_e32 v[22:23], 0
	v_mov_b64_e32 v[32:33], 0
	v_mov_b64_e32 v[34:35], 0
	v_mov_b64_e32 v[36:37], 0
	v_mov_b64_e32 v[38:39], 0
	v_mov_b64_e32 v[48:49], 0
	v_mov_b64_e32 v[50:51], 0
	v_mov_b64_e32 v[52:53], 0
	v_mov_b64_e32 v[54:55], 0
	v_mov_b64_e32 v[56:57], 0
	v_mov_b64_e32 v[58:59], 0
	v_mov_b64_e32 v[60:61], 0
	v_mov_b64_e32 v[62:63], 0
	v_mov_b64_e32 v[66:67], 0
	v_mov_b64_e32 v[68:69], 0
	v_mov_b64_e32 v[70:71], 0
	v_mov_b64_e32 v[72:73], 0
	v_mov_b64_e32 v[74:75], 0
	v_mov_b64_e32 v[76:77], 0
	v_mov_b64_e32 v[78:79], 0
	v_mov_b64_e32 v[80:81], 0
	v_mov_b64_e32 v[90:91], 0
	v_mov_b64_e32 v[92:93], 0
	v_mov_b64_e32 v[94:95], 0
	v_mov_b64_e32 v[96:97], 0
	v_mov_b64_e32 v[106:107], 0
	v_mov_b64_e32 v[108:109], 0
	v_mov_b64_e32 v[110:111], 0
	v_mov_b64_e32 v[112:113], 0
	v_mov_b64_e32 v[82:83], 0
	v_mov_b64_e32 v[84:85], 0
	v_mov_b64_e32 v[86:87], 0
	v_mov_b64_e32 v[88:89], 0
	v_mov_b64_e32 v[98:99], 0
	v_mov_b64_e32 v[100:101], 0
	v_mov_b64_e32 v[102:103], 0
	v_mov_b64_e32 v[104:105], 0
	v_mov_b64_e32 v[114:115], 0
	v_mov_b64_e32 v[116:117], 0
	v_mov_b64_e32 v[118:119], 0
	v_mov_b64_e32 v[120:121], 0
	v_mov_b64_e32 v[122:123], 0
	v_mov_b64_e32 v[124:125], 0
	v_mov_b64_e32 v[126:127], 0
	v_mov_b64_e32 v[128:129], 0
	s_mov_b64 s[48:49], 0x80
	v_add_u32_e32 v252, 0x10000, v141
	v_add_u32_e32 v253, 0x14000, v141
	v_add_u32_e32 v254, 0x18000, v141
	v_add_u32_e32 v255, 0x1c000, v141
.LBB0_1702:
	s_add_u32 s18, s16, 0xffe00080
	s_addc_u32 s19, s17, -1
	s_add_i32 s44, 0, 0x10000
	s_cmp_eq_u32 s43, 12
	s_cselect_b32 s21, s9, s19
	s_cselect_b32 s20, s11, s18
	s_cselect_b32 s19, s13, s42
	s_cselect_b32 s18, s38, s39
	s_add_i32 s46, 0, 0x14000
	ds_read_b128 v[144:147], v252
	ds_read_b128 v[148:151], v252 offset:1024
	ds_read_b128 v[152:155], v252 offset:2048
	ds_read_b128 v[156:159], v252 offset:3072
	ds_read_b128 v[178:181], v253
	ds_read_b128 v[182:185], v253 offset:1024
	ds_read_b128 v[186:189], v253 offset:2048
	ds_read_b128 v[190:193], v253 offset:3072
	s_add_i32 m0, s28, 0xc000
	ds_read_b128 v[194:197], v143
	ds_read_b128 v[208:211], v143 offset:1024
	ds_read_b128 v[212:215], v143 offset:2048
	ds_read_b128 v[216:219], v143 offset:3072
	ds_read_b128 v[220:223], v143 offset:4096
	ds_read_b128 v[224:227], v143 offset:5120
	ds_read_b128 v[228:231], v143 offset:6144
	ds_read_b128 v[232:235], v143 offset:7168
	global_load_lds_dwordx4 v136, s[16:17]
	s_add_i32 m0, s28, 0xe000
	s_nop 0
	global_load_lds_dwordx4 v138, s[16:17]
	s_waitcnt vmcnt(8)
	s_waitcnt lgkmcnt(0)
	s_barrier
	s_setprio 1
	s_waitcnt lgkmcnt(0)
	v_mfma_f32_16x16x32_bf16 v[126:129], v[144:147], v[194:197], v[126:129]
	v_mfma_f32_16x16x32_bf16 v[122:125], v[152:155], v[194:197], v[122:125]
	v_mfma_f32_16x16x32_bf16 v[118:121], v[144:147], v[212:215], v[118:121]
	v_mfma_f32_16x16x32_bf16 v[114:117], v[152:155], v[212:215], v[114:117]
	v_mfma_f32_16x16x32_bf16 v[102:105], v[144:147], v[220:223], v[102:105]
	v_mfma_f32_16x16x32_bf16 v[98:101], v[152:155], v[220:223], v[98:101]
	v_mfma_f32_16x16x32_bf16 v[86:89], v[144:147], v[228:231], v[86:89]
	v_mfma_f32_16x16x32_bf16 v[82:85], v[152:155], v[228:231], v[82:85]
	v_mfma_f32_16x16x32_bf16 v[126:129], v[148:151], v[208:211], v[126:129]
	v_mfma_f32_16x16x32_bf16 v[122:125], v[156:159], v[208:211], v[122:125]
	v_mfma_f32_16x16x32_bf16 v[118:121], v[148:151], v[216:219], v[118:121]
	v_mfma_f32_16x16x32_bf16 v[114:117], v[156:159], v[216:219], v[114:117]
	v_mfma_f32_16x16x32_bf16 v[102:105], v[148:151], v[224:227], v[102:105]
	v_mfma_f32_16x16x32_bf16 v[98:101], v[156:159], v[224:227], v[98:101]
	v_mfma_f32_16x16x32_bf16 v[86:89], v[148:151], v[232:235], v[86:89]
	v_mfma_f32_16x16x32_bf16 v[82:85], v[156:159], v[232:235], v[82:85]
	s_setprio 0
	s_setprio 1
	v_mfma_f32_16x16x32_bf16 v[110:113], v[178:181], v[194:197], v[110:113]
	v_mfma_f32_16x16x32_bf16 v[106:109], v[186:189], v[194:197], v[106:109]
	v_mfma_f32_16x16x32_bf16 v[94:97], v[178:181], v[212:215], v[94:97]
	v_mfma_f32_16x16x32_bf16 v[90:93], v[186:189], v[212:215], v[90:93]
	v_mfma_f32_16x16x32_bf16 v[78:81], v[178:181], v[220:223], v[78:81]
	v_mfma_f32_16x16x32_bf16 v[74:77], v[186:189], v[220:223], v[74:77]
	v_mfma_f32_16x16x32_bf16 v[70:73], v[178:181], v[228:231], v[70:73]
	v_mfma_f32_16x16x32_bf16 v[66:69], v[186:189], v[228:231], v[66:69]
	v_mfma_f32_16x16x32_bf16 v[110:113], v[182:185], v[208:211], v[110:113]
	v_mfma_f32_16x16x32_bf16 v[106:109], v[190:193], v[208:211], v[106:109]
	v_mfma_f32_16x16x32_bf16 v[94:97], v[182:185], v[216:219], v[94:97]
	v_mfma_f32_16x16x32_bf16 v[90:93], v[190:193], v[216:219], v[90:93]
	v_mfma_f32_16x16x32_bf16 v[78:81], v[182:185], v[224:227], v[78:81]
	v_mfma_f32_16x16x32_bf16 v[74:77], v[190:193], v[224:227], v[74:77]
	v_mfma_f32_16x16x32_bf16 v[70:73], v[182:185], v[232:235], v[70:73]
	v_mfma_f32_16x16x32_bf16 v[66:69], v[190:193], v[232:235], v[66:69]
	s_setprio 0
	s_barrier
; #define PG8_STAGE(bufoff, gbase, voff) do { _Pragma("unroll") for (int _i = 0; _i < 2; ++_i) \
;         __builtin_amdgcn_global_load_lds((const unsigned*)((const char*)(gbase) + (voff)[_i]), (PG8_LAS unsigned*)(lds + (bufoff) + ldsw + _i * 8192), 16, 0, 0); } while (0)
; #define PG8_LDA(dst, b, h) do { _Pragma("unroll") for (int m = 0; m < 4; ++m) _Pragma("unroll") for (int k = 0; k < 2; ++k) dst[m][k] = *(const PG8_LAS bf16x8*)(lds + PG8_SA(b, h) + aoff + m * 2048 + k * 1024); } while (0)
; #define PG8_LDB(dst, b, h) do { _Pragma("unroll") for (int n = 0; n < 2; ++n) _Pragma("unroll") for (int k = 0; k < 2; ++k) dst[n][k] = *(const PG8_LAS bf16x8*)(lds + PG8_SB(b, h) + boff + n * 2048 + k * 1024); } while (0)
; #define PG8_MMA(ai, bj, At, Bt) do { __builtin_amdgcn_s_setprio(1); _Pragma("unroll") for (int m = 0; m < 4; ++m) _Pragma("unroll") for (int n = 0; n < 2; ++n) _Pragma("unroll") for (int k = 0; k < 2; ++k) \
;         acc[ai][bj][m][n] = __builtin_amdgcn_mfma_f32_16x16x32_bf16(Bt[n][k], At[m][k], acc[ai][bj][m][n], 0, 0, 0); __builtin_amdgcn_s_setprio(0); } while (0)
; #define PG8_WAIT_V(n) asm volatile("s_waitcnt vmcnt(" #n ")" ::: "memory")
; #define PG8_WAIT_L(n) asm volatile("s_waitcnt lgkmcnt(" #n ")" ::: "memory")
; #define PG8_BAR __builtin_amdgcn_s_barrier()
; #define PG8_SCHED __builtin_amdgcn_sched_barrier(0)
; template <class Epi, class Sched, bool ALIGN_EPI = false, bool SP2 = false>
; __device__ __forceinline__ void gemm_phase(PG8_LAS unsigned char* lds, const Gemm g, const Sched& S, const Epi& E, const int wave0) {
;     ...
;             PG8_LDA(At, 0, 1); PG8_STAGE(PG8_SB(0, 0), b2, voffB); PG8_STAGE(PG8_SB(0, 1), b2 + hstepB, voffB); PG8_STAGE(PG8_SA(0, 0), a2, voffA);
;             PG8_WAIT_V(8); PG8_WAIT_L(0); PG8_BAR; PG8_MMA(1, 0, At, B0); PG8_MMA(1, 1, At, B1); PG8_BAR; PG8_SCHED;
;             PG8_LDB(B0, 1, 0); PG8_LDB(B1, 1, 1); PG8_SCHED; PG8_LDA(At, 1, 0); PG8_STAGE(PG8_SA(0, 1), a2 + hstepA, voffA);
	s_add_i32 s44, s44, s25
	s_mov_b32 m0, s44
	ds_read_b128 v[194:197], v143 offset:16384
	ds_read_b128 v[208:211], v143 offset:17408
	ds_read_b128 v[212:215], v143 offset:18432
	ds_read_b128 v[216:219], v143 offset:19456
	ds_read_b128 v[220:223], v143 offset:20480
	ds_read_b128 v[224:227], v143 offset:21504
	ds_read_b128 v[228:231], v143 offset:22528
	ds_read_b128 v[232:235], v143 offset:23552
	global_load_lds_dwordx4 v64, s[18:19]
	s_add_i32 m0, s44, 0x2000
	s_add_u32 s44, s18, 0x200000
	s_addc_u32 s45, s19, 0
	s_add_i32 s46, s46, s25
	global_load_lds_dwordx4 v130, s[18:19]
	s_mov_b32 m0, s46
	s_mov_b64 s[100:101], s[20:21]
	global_load_lds_dwordx4 v64, s[44:45]
	s_add_i32 m0, s46, 0x2000
	s_nop 0
	global_load_lds_dwordx4 v130, s[44:45]
	s_mov_b32 m0, s28
	s_nop 0
	global_load_lds_dwordx4 v134, s[20:21]
	s_mov_b32 m0, s29
	s_nop 0
	global_load_lds_dwordx4 v132, s[20:21]
	s_waitcnt vmcnt(8)
	s_waitcnt lgkmcnt(0)
	s_barrier
	s_setprio 1
	s_waitcnt lgkmcnt(0)
	v_mfma_f32_16x16x32_bf16 v[60:63], v[144:147], v[194:197], v[60:63]
	v_mfma_f32_16x16x32_bf16 v[56:59], v[152:155], v[194:197], v[56:59]
	v_mfma_f32_16x16x32_bf16 v[52:55], v[144:147], v[212:215], v[52:55]
	v_mfma_f32_16x16x32_bf16 v[48:51], v[152:155], v[212:215], v[48:51]
	v_mfma_f32_16x16x32_bf16 v[36:39], v[144:147], v[220:223], v[36:39]
	v_mfma_f32_16x16x32_bf16 v[32:35], v[152:155], v[220:223], v[32:35]
	v_mfma_f32_16x16x32_bf16 v[20:23], v[144:147], v[228:231], v[20:23]
	v_mfma_f32_16x16x32_bf16 v[16:19], v[152:155], v[228:231], v[16:19]
	v_mfma_f32_16x16x32_bf16 v[60:63], v[148:151], v[208:211], v[60:63]
	v_mfma_f32_16x16x32_bf16 v[56:59], v[156:159], v[208:211], v[56:59]
	v_mfma_f32_16x16x32_bf16 v[52:55], v[148:151], v[216:219], v[52:55]
	v_mfma_f32_16x16x32_bf16 v[48:51], v[156:159], v[216:219], v[48:51]
	v_mfma_f32_16x16x32_bf16 v[36:39], v[148:151], v[224:227], v[36:39]
	v_mfma_f32_16x16x32_bf16 v[32:35], v[156:159], v[224:227], v[32:35]
	v_mfma_f32_16x16x32_bf16 v[20:23], v[148:151], v[232:235], v[20:23]
	v_mfma_f32_16x16x32_bf16 v[16:19], v[156:159], v[232:235], v[16:19]
	s_setprio 0
	s_setprio 1
	v_mfma_f32_16x16x32_bf16 v[44:47], v[178:181], v[194:197], v[44:47]
	v_mfma_f32_16x16x32_bf16 v[40:43], v[186:189], v[194:197], v[40:43]
	v_mfma_f32_16x16x32_bf16 v[28:31], v[178:181], v[212:215], v[28:31]
	v_mfma_f32_16x16x32_bf16 v[24:27], v[186:189], v[212:215], v[24:27]
	v_mfma_f32_16x16x32_bf16 v[12:15], v[178:181], v[220:223], v[12:15]
	v_mfma_f32_16x16x32_bf16 v[8:11], v[186:189], v[220:223], v[8:11]
	v_mfma_f32_16x16x32_bf16 v[4:7], v[178:181], v[228:231], v[4:7]
	v_mfma_f32_16x16x32_bf16 v[0:3], v[186:189], v[228:231], v[0:3]
	v_mfma_f32_16x16x32_bf16 v[44:47], v[182:185], v[208:211], v[44:47]
	v_mfma_f32_16x16x32_bf16 v[40:43], v[190:193], v[208:211], v[40:43]
	v_mfma_f32_16x16x32_bf16 v[28:31], v[182:185], v[216:219], v[28:31]
	v_mfma_f32_16x16x32_bf16 v[24:27], v[190:193], v[216:219], v[24:27]
	v_mfma_f32_16x16x32_bf16 v[12:15], v[182:185], v[224:227], v[12:15]
	v_mfma_f32_16x16x32_bf16 v[8:11], v[190:193], v[224:227], v[8:11]
	v_mfma_f32_16x16x32_bf16 v[4:7], v[182:185], v[232:235], v[4:7]
	v_mfma_f32_16x16x32_bf16 v[0:3], v[190:193], v[232:235], v[0:3]
	s_setprio 0
	s_barrier
	s_add_i32 s44, 0, 0x18000
	s_add_i32 s45, 0, 0x1c000
	ds_read_b128 v[144:147], v254
	ds_read_b128 v[148:151], v254 offset:1024
	ds_read_b128 v[152:155], v254 offset:2048
	ds_read_b128 v[156:159], v254 offset:3072
	ds_read_b128 v[178:181], v255
	ds_read_b128 v[182:185], v255 offset:1024
	ds_read_b128 v[186:189], v255 offset:2048
	ds_read_b128 v[190:193], v255 offset:3072
	s_add_u32 s20, s20, 0x200000
	s_addc_u32 s21, s21, 0
	s_mov_b32 m0, s30
	ds_read_b128 v[194:197], v143 offset:32768
	ds_read_b128 v[208:211], v143 offset:33792
	ds_read_b128 v[212:215], v143 offset:34816
	ds_read_b128 v[216:219], v143 offset:35840
	ds_read_b128 v[220:223], v143 offset:36864
	ds_read_b128 v[224:227], v143 offset:37888
	ds_read_b128 v[228:231], v143 offset:38912
	ds_read_b128 v[232:235], v143 offset:39936
	global_load_lds_dwordx4 v134, s[20:21]
	s_mov_b32 m0, s31
	s_nop 0
	global_load_lds_dwordx4 v132, s[20:21]
	s_waitcnt vmcnt(8)
	s_waitcnt lgkmcnt(0)
	s_barrier
; #define PG8_STAGE(bufoff, gbase, voff) do { _Pragma("unroll") for (int _i = 0; _i < 2; ++_i) \
;         __builtin_amdgcn_global_load_lds((const unsigned*)((const char*)(gbase) + (voff)[_i]), (PG8_LAS unsigned*)(lds + (bufoff) + ldsw + _i * 8192), 16, 0, 0); } while (0)
; #define PG8_LDA(dst, b, h) do { _Pragma("unroll") for (int m = 0; m < 4; ++m) _Pragma("unroll") for (int k = 0; k < 2; ++k) dst[m][k] = *(const PG8_LAS bf16x8*)(lds + PG8_SA(b, h) + aoff + m * 2048 + k * 1024); } while (0)
; #define PG8_MMA(ai, bj, At, Bt) do { __builtin_amdgcn_s_setprio(1); _Pragma("unroll") for (int m = 0; m < 4; ++m) _Pragma("unroll") for (int n = 0; n < 2; ++n) _Pragma("unroll") for (int k = 0; k < 2; ++k) \
;         acc[ai][bj][m][n] = __builtin_amdgcn_mfma_f32_16x16x32_bf16(Bt[n][k], At[m][k], acc[ai][bj][m][n], 0, 0, 0); __builtin_amdgcn_s_setprio(0); } while (0)
; #define PG8_WAIT_V(n) asm volatile("s_waitcnt vmcnt(" #n ")" ::: "memory")
; #define PG8_WAIT_L(n) asm volatile("s_waitcnt lgkmcnt(" #n ")" ::: "memory")
; #define PG8_BAR __builtin_amdgcn_s_barrier()
; #define PG8_SCHED __builtin_amdgcn_sched_barrier(0)
; template <class Epi, class Sched, bool ALIGN_EPI = false, bool SP2 = false>
; __device__ __forceinline__ void gemm_phase(PG8_LAS unsigned char* lds, const Gemm g, const Sched& S, const Epi& E, const int wave0) {
;     ...
;             PG8_WAIT_V(8); PG8_WAIT_L(0); PG8_BAR; PG8_MMA(0, 0, At, B0); PG8_MMA(0, 1, At, B1); PG8_BAR; PG8_SCHED;
;             PG8_LDA(At, 1, 1); PG8_STAGE(PG8_SB(1, 0), b3, voffB); PG8_STAGE(PG8_SB(1, 1), b3 + hstepB, voffB); PG8_STAGE(PG8_SA(1, 0), a3, voffA);
;             PG8_WAIT_V(8); PG8_WAIT_L(0); PG8_BAR; PG8_MMA(1, 0, At, B0); PG8_MMA(1, 1, At, B1); PG8_BAR; PG8_SCHED;
	s_setprio 1
	s_waitcnt lgkmcnt(0)
	v_mfma_f32_16x16x32_bf16 v[126:129], v[144:147], v[194:197], v[126:129]
	v_mfma_f32_16x16x32_bf16 v[122:125], v[152:155], v[194:197], v[122:125]
	v_mfma_f32_16x16x32_bf16 v[118:121], v[144:147], v[212:215], v[118:121]
	v_mfma_f32_16x16x32_bf16 v[114:117], v[152:155], v[212:215], v[114:117]
	v_mfma_f32_16x16x32_bf16 v[102:105], v[144:147], v[220:223], v[102:105]
	v_mfma_f32_16x16x32_bf16 v[98:101], v[152:155], v[220:223], v[98:101]
	v_mfma_f32_16x16x32_bf16 v[86:89], v[144:147], v[228:231], v[86:89]
	v_mfma_f32_16x16x32_bf16 v[82:85], v[152:155], v[228:231], v[82:85]
	v_mfma_f32_16x16x32_bf16 v[126:129], v[148:151], v[208:211], v[126:129]
	v_mfma_f32_16x16x32_bf16 v[122:125], v[156:159], v[208:211], v[122:125]
	v_mfma_f32_16x16x32_bf16 v[118:121], v[148:151], v[216:219], v[118:121]
	v_mfma_f32_16x16x32_bf16 v[114:117], v[156:159], v[216:219], v[114:117]
	v_mfma_f32_16x16x32_bf16 v[102:105], v[148:151], v[224:227], v[102:105]
	v_mfma_f32_16x16x32_bf16 v[98:101], v[156:159], v[224:227], v[98:101]
	v_mfma_f32_16x16x32_bf16 v[86:89], v[148:151], v[232:235], v[86:89]
	v_mfma_f32_16x16x32_bf16 v[82:85], v[156:159], v[232:235], v[82:85]
	s_setprio 0
	s_setprio 1
	v_mfma_f32_16x16x32_bf16 v[110:113], v[178:181], v[194:197], v[110:113]
	v_mfma_f32_16x16x32_bf16 v[106:109], v[186:189], v[194:197], v[106:109]
	v_mfma_f32_16x16x32_bf16 v[94:97], v[178:181], v[212:215], v[94:97]
	v_mfma_f32_16x16x32_bf16 v[90:93], v[186:189], v[212:215], v[90:93]
	v_mfma_f32_16x16x32_bf16 v[78:81], v[178:181], v[220:223], v[78:81]
	v_mfma_f32_16x16x32_bf16 v[74:77], v[186:189], v[220:223], v[74:77]
	v_mfma_f32_16x16x32_bf16 v[70:73], v[178:181], v[228:231], v[70:73]
	v_mfma_f32_16x16x32_bf16 v[66:69], v[186:189], v[228:231], v[66:69]
	v_mfma_f32_16x16x32_bf16 v[110:113], v[182:185], v[208:211], v[110:113]
	v_mfma_f32_16x16x32_bf16 v[106:109], v[190:193], v[208:211], v[106:109]
	v_mfma_f32_16x16x32_bf16 v[94:97], v[182:185], v[216:219], v[94:97]
	v_mfma_f32_16x16x32_bf16 v[90:93], v[190:193], v[216:219], v[90:93]
	v_mfma_f32_16x16x32_bf16 v[78:81], v[182:185], v[224:227], v[78:81]
	v_mfma_f32_16x16x32_bf16 v[74:77], v[190:193], v[224:227], v[74:77]
	v_mfma_f32_16x16x32_bf16 v[70:73], v[182:185], v[232:235], v[70:73]
	v_mfma_f32_16x16x32_bf16 v[66:69], v[190:193], v[232:235], v[66:69]
	s_setprio 0
	s_barrier
	s_add_i32 s20, s44, s25
	s_add_u32 s48, s18, 0x80
	s_addc_u32 s49, s19, 0
	s_mov_b32 m0, s20
	ds_read_b128 v[194:197], v143 offset:49152
	ds_read_b128 v[208:211], v143 offset:50176
	ds_read_b128 v[212:215], v143 offset:51200
	ds_read_b128 v[216:219], v143 offset:52224
	ds_read_b128 v[220:223], v143 offset:53248
	ds_read_b128 v[224:227], v143 offset:54272
	ds_read_b128 v[228:231], v143 offset:55296
	ds_read_b128 v[232:235], v143 offset:56320
	global_load_lds_dwordx4 v64, s[48:49]
	s_add_i32 m0, s20, 0x2000
	s_add_u32 s18, s18, 0x200080
	s_addc_u32 s19, s19, 0
	s_add_i32 s20, s45, s25
	global_load_lds_dwordx4 v130, s[48:49]
	s_mov_b32 m0, s20
	s_nop 0
	global_load_lds_dwordx4 v64, s[18:19]
	s_add_i32 m0, s20, 0x2000
	s_nop 0
	global_load_lds_dwordx4 v130, s[18:19]
	s_add_u32 s100, s100, 0x80
	s_addc_u32 s101, s101, 0
	s_mov_b32 m0, s33
	s_nop 0
	global_load_lds_dwordx4 v134, s[100:101]
	s_mov_b32 m0, s34
	s_nop 0
	global_load_lds_dwordx4 v132, s[100:101]
	s_waitcnt vmcnt(8)
	s_waitcnt lgkmcnt(0)
	s_barrier
	s_setprio 1
	s_waitcnt lgkmcnt(0)
	v_mfma_f32_16x16x32_bf16 v[60:63], v[144:147], v[194:197], v[60:63]
	v_mfma_f32_16x16x32_bf16 v[56:59], v[152:155], v[194:197], v[56:59]
	v_mfma_f32_16x16x32_bf16 v[52:55], v[144:147], v[212:215], v[52:55]
	v_mfma_f32_16x16x32_bf16 v[48:51], v[152:155], v[212:215], v[48:51]
	v_mfma_f32_16x16x32_bf16 v[36:39], v[144:147], v[220:223], v[36:39]
	v_mfma_f32_16x16x32_bf16 v[32:35], v[152:155], v[220:223], v[32:35]
	v_mfma_f32_16x16x32_bf16 v[20:23], v[144:147], v[228:231], v[20:23]
	v_mfma_f32_16x16x32_bf16 v[16:19], v[152:155], v[228:231], v[16:19]
	v_mfma_f32_16x16x32_bf16 v[60:63], v[148:151], v[208:211], v[60:63]
	v_mfma_f32_16x16x32_bf16 v[56:59], v[156:159], v[208:211], v[56:59]
	v_mfma_f32_16x16x32_bf16 v[52:55], v[148:151], v[216:219], v[52:55]
	v_mfma_f32_16x16x32_bf16 v[48:51], v[156:159], v[216:219], v[48:51]
	v_mfma_f32_16x16x32_bf16 v[36:39], v[148:151], v[224:227], v[36:39]
	v_mfma_f32_16x16x32_bf16 v[32:35], v[156:159], v[224:227], v[32:35]
	v_mfma_f32_16x16x32_bf16 v[20:23], v[148:151], v[232:235], v[20:23]
	v_mfma_f32_16x16x32_bf16 v[16:19], v[156:159], v[232:235], v[16:19]
	s_setprio 0
	s_setprio 1
	v_mfma_f32_16x16x32_bf16 v[44:47], v[178:181], v[194:197], v[44:47]
	v_mfma_f32_16x16x32_bf16 v[40:43], v[186:189], v[194:197], v[40:43]
	v_mfma_f32_16x16x32_bf16 v[28:31], v[178:181], v[212:215], v[28:31]
	v_mfma_f32_16x16x32_bf16 v[24:27], v[186:189], v[212:215], v[24:27]
	v_mfma_f32_16x16x32_bf16 v[12:15], v[178:181], v[220:223], v[12:15]
	v_mfma_f32_16x16x32_bf16 v[8:11], v[186:189], v[220:223], v[8:11]
	v_mfma_f32_16x16x32_bf16 v[4:7], v[178:181], v[228:231], v[4:7]
	v_mfma_f32_16x16x32_bf16 v[0:3], v[186:189], v[228:231], v[0:3]
	v_mfma_f32_16x16x32_bf16 v[44:47], v[182:185], v[208:211], v[44:47]
	v_mfma_f32_16x16x32_bf16 v[40:43], v[190:193], v[208:211], v[40:43]
	v_mfma_f32_16x16x32_bf16 v[28:31], v[182:185], v[216:219], v[28:31]
	v_mfma_f32_16x16x32_bf16 v[24:27], v[190:193], v[216:219], v[24:27]
	v_mfma_f32_16x16x32_bf16 v[12:15], v[182:185], v[224:227], v[12:15]
	v_mfma_f32_16x16x32_bf16 v[8:11], v[190:193], v[224:227], v[8:11]
	v_mfma_f32_16x16x32_bf16 v[4:7], v[182:185], v[232:235], v[4:7]
	v_mfma_f32_16x16x32_bf16 v[0:3], v[190:193], v[232:235], v[0:3]
	s_setprio 0
	s_barrier
	s_add_i32 s43, s43, 2
	s_add_u32 s16, s16, 0x100
	s_addc_u32 s17, s17, 0
	s_add_u32 s39, s39, 0x100
	s_addc_u32 s42, s42, 0
	s_cmp_gt_u32 s43, 13
	s_cbranch_scc0 .LBB0_1702
	s_mov_b64 s[48:49], 0x80
	s_and_b64 vcc, exec, s[6:7]
	s_cbranch_vccz .LBB0_1705
	s_barrier
